# GEMM K-loops: s_setprio immediates inverted so the load segment (ds_read + LDS-DMA issue) runs at raised priority and the MFMA block at base priority
# baseline (speedup 1.0000x reference)
.LBB0_344:
	s_add_i32 s30, s8, 2
	s_add_u32 s9, s12, 0xfff80080
	s_addc_u32 s16, s13, -1
	s_add_i32 s31, 0, 0x10000
	s_cmp_eq_u32 s60, s8
	s_cselect_b32 s17, s53, s16
	s_cselect_b32 s16, s52, s9
	s_cselect_b32 s9, s2, s10
	s_cselect_b32 s8, s3, s7
	s_add_i32 s33, 0, 0x14000
	v_add_u32_e32 v140, s31, v162
	v_add_u32_e32 v168, s33, v162
	ds_read_b128 v[128:131], v140
	ds_read_b128 v[132:135], v140 offset:1024
	ds_read_b128 v[136:139], v140 offset:2048
	ds_read_b128 v[140:143], v140 offset:3072
	ds_read_b128 v[154:157], v168
	ds_read_b128 v[158:161], v168 offset:1024
	ds_read_b128 v[164:167], v168 offset:2048
	ds_read_b128 v[168:171], v168 offset:3072
	v_lshl_add_u64 v[204:205], s[12:13], 0, v[150:151]
	s_add_i32 m0, s28, 0xc000
	ds_read_b128 v[172:175], v163
	ds_read_b128 v[176:179], v163 offset:1024
	ds_read_b128 v[180:183], v163 offset:2048
	ds_read_b128 v[184:187], v163 offset:3072
	ds_read_b128 v[188:191], v163 offset:4096
	ds_read_b128 v[192:195], v163 offset:5120
	ds_read_b128 v[196:199], v163 offset:6144
	ds_read_b128 v[200:203], v163 offset:7168
	global_load_lds_dwordx4 v[204:205], off
	v_lshl_add_u64 v[204:205], s[12:13], 0, v[152:153]
	s_add_i32 m0, s28, 0xe000
	s_nop 0
	global_load_lds_dwordx4 v[204:205], off
	s_waitcnt vmcnt(8)
	s_waitcnt lgkmcnt(0)
	s_barrier
	s_setprio 0
	s_waitcnt lgkmcnt(0)
	v_mfma_f32_16x16x32_bf16 v[112:115], v[128:131], v[172:175], v[112:115]
	v_mfma_f32_16x16x32_bf16 v[116:119], v[136:139], v[172:175], v[116:119]
	v_mfma_f32_16x16x32_bf16 v[96:99], v[128:131], v[180:183], v[96:99]
	v_mfma_f32_16x16x32_bf16 v[100:103], v[136:139], v[180:183], v[100:103]
	v_mfma_f32_16x16x32_bf16 v[80:83], v[128:131], v[188:191], v[80:83]
	v_mfma_f32_16x16x32_bf16 v[84:87], v[136:139], v[188:191], v[84:87]
	v_mfma_f32_16x16x32_bf16 v[48:51], v[128:131], v[196:199], v[48:51]
	v_mfma_f32_16x16x32_bf16 v[52:55], v[136:139], v[196:199], v[52:55]
	v_mfma_f32_16x16x32_bf16 v[112:115], v[132:135], v[176:179], v[112:115]
	v_mfma_f32_16x16x32_bf16 v[116:119], v[140:143], v[176:179], v[116:119]
	v_mfma_f32_16x16x32_bf16 v[96:99], v[132:135], v[184:187], v[96:99]
	v_mfma_f32_16x16x32_bf16 v[100:103], v[140:143], v[184:187], v[100:103]
	v_mfma_f32_16x16x32_bf16 v[80:83], v[132:135], v[192:195], v[80:83]
	v_mfma_f32_16x16x32_bf16 v[84:87], v[140:143], v[192:195], v[84:87]
	v_mfma_f32_16x16x32_bf16 v[48:51], v[132:135], v[200:203], v[48:51]
	v_mfma_f32_16x16x32_bf16 v[52:55], v[140:143], v[200:203], v[52:55]
	s_setprio 1
	s_setprio 0
	v_mfma_f32_16x16x32_bf16 v[120:123], v[154:157], v[172:175], v[120:123]
	v_mfma_f32_16x16x32_bf16 v[124:127], v[164:167], v[172:175], v[124:127]
	v_mfma_f32_16x16x32_bf16 v[104:107], v[154:157], v[180:183], v[104:107]
	v_mfma_f32_16x16x32_bf16 v[108:111], v[164:167], v[180:183], v[108:111]
	v_mfma_f32_16x16x32_bf16 v[88:91], v[154:157], v[188:191], v[88:91]
	v_mfma_f32_16x16x32_bf16 v[92:95], v[164:167], v[188:191], v[92:95]
	v_mfma_f32_16x16x32_bf16 v[64:67], v[154:157], v[196:199], v[64:67]
	v_mfma_f32_16x16x32_bf16 v[68:71], v[164:167], v[196:199], v[68:71]
	v_mfma_f32_16x16x32_bf16 v[120:123], v[158:161], v[176:179], v[120:123]
	v_mfma_f32_16x16x32_bf16 v[124:127], v[168:171], v[176:179], v[124:127]
	v_mfma_f32_16x16x32_bf16 v[104:107], v[158:161], v[184:187], v[104:107]
	v_mfma_f32_16x16x32_bf16 v[108:111], v[168:171], v[184:187], v[108:111]
	v_mfma_f32_16x16x32_bf16 v[88:91], v[158:161], v[192:195], v[88:91]
	v_mfma_f32_16x16x32_bf16 v[92:95], v[168:171], v[192:195], v[92:95]
	v_mfma_f32_16x16x32_bf16 v[64:67], v[158:161], v[200:203], v[64:67]
	v_mfma_f32_16x16x32_bf16 v[68:71], v[168:171], v[200:203], v[68:71]
	s_setprio 1
	s_barrier
	s_add_i32 s31, s31, s26
	v_lshl_add_u64 v[204:205], s[8:9], 0, v[224:225]
	s_mov_b32 m0, s31
	ds_read_b128 v[172:175], v163 offset:16384
	ds_read_b128 v[176:179], v163 offset:17408
	ds_read_b128 v[180:183], v163 offset:18432
	ds_read_b128 v[184:187], v163 offset:19456
	ds_read_b128 v[188:191], v163 offset:20480
	ds_read_b128 v[192:195], v163 offset:21504
	ds_read_b128 v[196:199], v163 offset:22528
	ds_read_b128 v[200:203], v163 offset:23552
	global_load_lds_dwordx4 v[204:205], off
	s_add_i32 m0, s31, 0x2000
	s_add_u32 s40, s8, 0x80000
	v_lshl_add_u64 v[206:207], s[8:9], 0, v[144:145]
	s_addc_u32 s41, s9, 0
	s_add_i32 s31, s33, s26
	global_load_lds_dwordx4 v[206:207], off
	v_lshl_add_u64 v[208:209], s[40:41], 0, v[224:225]
	s_mov_b32 m0, s31
	v_lshl_add_u64 v[210:211], s[16:17], 0, v[146:147]
	global_load_lds_dwordx4 v[208:209], off
	v_lshl_add_u64 v[208:209], s[40:41], 0, v[144:145]
	s_add_i32 m0, s31, 0x2000
	s_nop 0
	global_load_lds_dwordx4 v[208:209], off
	v_lshl_add_u64 v[208:209], s[16:17], 0, v[148:149]
	s_mov_b32 m0, s28
	s_nop 0
	global_load_lds_dwordx4 v[208:209], off
	s_mov_b32 m0, s29
	s_nop 0
	global_load_lds_dwordx4 v[210:211], off
	s_waitcnt vmcnt(8)
	s_waitcnt lgkmcnt(0)
	s_barrier
	s_setprio 0
	s_waitcnt lgkmcnt(0)
	v_mfma_f32_16x16x32_bf16 v[56:59], v[128:131], v[172:175], v[56:59]
	v_mfma_f32_16x16x32_bf16 v[60:63], v[136:139], v[172:175], v[60:63]
	v_mfma_f32_16x16x32_bf16 v[32:35], v[128:131], v[180:183], v[32:35]
	v_mfma_f32_16x16x32_bf16 v[36:39], v[136:139], v[180:183], v[36:39]
	v_mfma_f32_16x16x32_bf16 v[16:19], v[128:131], v[188:191], v[16:19]
	v_mfma_f32_16x16x32_bf16 v[20:23], v[136:139], v[188:191], v[20:23]
	v_mfma_f32_16x16x32_bf16 v[0:3], v[128:131], v[196:199], v[0:3]
	v_mfma_f32_16x16x32_bf16 v[4:7], v[136:139], v[196:199], v[4:7]
	v_mfma_f32_16x16x32_bf16 v[56:59], v[132:135], v[176:179], v[56:59]
	v_mfma_f32_16x16x32_bf16 v[60:63], v[140:143], v[176:179], v[60:63]
	v_mfma_f32_16x16x32_bf16 v[32:35], v[132:135], v[184:187], v[32:35]
	v_mfma_f32_16x16x32_bf16 v[36:39], v[140:143], v[184:187], v[36:39]
	v_mfma_f32_16x16x32_bf16 v[16:19], v[132:135], v[192:195], v[16:19]
	v_mfma_f32_16x16x32_bf16 v[20:23], v[140:143], v[192:195], v[20:23]
	v_mfma_f32_16x16x32_bf16 v[0:3], v[132:135], v[200:203], v[0:3]
	v_mfma_f32_16x16x32_bf16 v[4:7], v[140:143], v[200:203], v[4:7]
	s_setprio 1
	s_setprio 0
	v_mfma_f32_16x16x32_bf16 v[72:75], v[154:157], v[172:175], v[72:75]
	v_mfma_f32_16x16x32_bf16 v[76:79], v[164:167], v[172:175], v[76:79]
	v_mfma_f32_16x16x32_bf16 v[40:43], v[154:157], v[180:183], v[40:43]
	v_mfma_f32_16x16x32_bf16 v[44:47], v[164:167], v[180:183], v[44:47]
	v_mfma_f32_16x16x32_bf16 v[24:27], v[154:157], v[188:191], v[24:27]
	v_mfma_f32_16x16x32_bf16 v[28:31], v[164:167], v[188:191], v[28:31]
	v_mfma_f32_16x16x32_bf16 v[8:11], v[154:157], v[196:199], v[8:11]
	v_mfma_f32_16x16x32_bf16 v[12:15], v[164:167], v[196:199], v[12:15]
	v_mfma_f32_16x16x32_bf16 v[72:75], v[158:161], v[176:179], v[72:75]
	v_mfma_f32_16x16x32_bf16 v[76:79], v[168:171], v[176:179], v[76:79]
	v_mfma_f32_16x16x32_bf16 v[40:43], v[158:161], v[184:187], v[40:43]
	v_mfma_f32_16x16x32_bf16 v[44:47], v[168:171], v[184:187], v[44:47]
	v_mfma_f32_16x16x32_bf16 v[24:27], v[158:161], v[192:195], v[24:27]
	v_mfma_f32_16x16x32_bf16 v[28:31], v[168:171], v[192:195], v[28:31]
	v_mfma_f32_16x16x32_bf16 v[8:11], v[158:161], v[200:203], v[8:11]
	v_mfma_f32_16x16x32_bf16 v[12:15], v[168:171], v[200:203], v[12:15]
	s_setprio 1
	s_barrier
	s_add_i32 s31, 0, 0x18000
	s_add_i32 s33, 0, 0x1c000
	v_add_u32_e32 v140, s31, v162
	v_add_u32_e32 v168, s33, v162
	ds_read_b128 v[128:131], v140
	ds_read_b128 v[132:135], v140 offset:1024
	ds_read_b128 v[136:139], v140 offset:2048
	ds_read_b128 v[140:143], v140 offset:3072
	ds_read_b128 v[154:157], v168
	ds_read_b128 v[158:161], v168 offset:1024
	ds_read_b128 v[164:167], v168 offset:2048
	ds_read_b128 v[168:171], v168 offset:3072
	s_add_u32 s16, s16, 0x80000
	s_addc_u32 s17, s17, 0
	s_mov_b32 m0, s34
	v_lshl_add_u64 v[212:213], s[16:17], 0, v[148:149]
	ds_read_b128 v[172:175], v163 offset:32768
	ds_read_b128 v[176:179], v163 offset:33792
	ds_read_b128 v[180:183], v163 offset:34816
	ds_read_b128 v[184:187], v163 offset:35840
	ds_read_b128 v[188:191], v163 offset:36864
	ds_read_b128 v[192:195], v163 offset:37888
	ds_read_b128 v[196:199], v163 offset:38912
	ds_read_b128 v[200:203], v163 offset:39936
	global_load_lds_dwordx4 v[212:213], off
	v_lshl_add_u64 v[212:213], s[16:17], 0, v[146:147]
	s_mov_b32 m0, s35
	s_nop 0
	global_load_lds_dwordx4 v[212:213], off
	s_waitcnt vmcnt(8)
	s_waitcnt lgkmcnt(0)
	s_barrier
	s_setprio 0
	s_waitcnt lgkmcnt(0)
	v_mfma_f32_16x16x32_bf16 v[112:115], v[128:131], v[172:175], v[112:115]
	v_mfma_f32_16x16x32_bf16 v[116:119], v[136:139], v[172:175], v[116:119]
	v_mfma_f32_16x16x32_bf16 v[96:99], v[128:131], v[180:183], v[96:99]
	v_mfma_f32_16x16x32_bf16 v[100:103], v[136:139], v[180:183], v[100:103]
	v_mfma_f32_16x16x32_bf16 v[80:83], v[128:131], v[188:191], v[80:83]
	v_mfma_f32_16x16x32_bf16 v[84:87], v[136:139], v[188:191], v[84:87]
	v_mfma_f32_16x16x32_bf16 v[48:51], v[128:131], v[196:199], v[48:51]
	v_mfma_f32_16x16x32_bf16 v[52:55], v[136:139], v[196:199], v[52:55]
	v_mfma_f32_16x16x32_bf16 v[112:115], v[132:135], v[176:179], v[112:115]
	v_mfma_f32_16x16x32_bf16 v[116:119], v[140:143], v[176:179], v[116:119]
	v_mfma_f32_16x16x32_bf16 v[96:99], v[132:135], v[184:187], v[96:99]
	v_mfma_f32_16x16x32_bf16 v[100:103], v[140:143], v[184:187], v[100:103]
	v_mfma_f32_16x16x32_bf16 v[80:83], v[132:135], v[192:195], v[80:83]
	v_mfma_f32_16x16x32_bf16 v[84:87], v[140:143], v[192:195], v[84:87]
	v_mfma_f32_16x16x32_bf16 v[48:51], v[132:135], v[200:203], v[48:51]
	v_mfma_f32_16x16x32_bf16 v[52:55], v[140:143], v[200:203], v[52:55]
	s_setprio 1
	s_setprio 0
	v_mfma_f32_16x16x32_bf16 v[120:123], v[154:157], v[172:175], v[120:123]
	v_mfma_f32_16x16x32_bf16 v[124:127], v[164:167], v[172:175], v[124:127]
	v_mfma_f32_16x16x32_bf16 v[104:107], v[154:157], v[180:183], v[104:107]
	v_mfma_f32_16x16x32_bf16 v[108:111], v[164:167], v[180:183], v[108:111]
	v_mfma_f32_16x16x32_bf16 v[88:91], v[154:157], v[188:191], v[88:91]
	v_mfma_f32_16x16x32_bf16 v[92:95], v[164:167], v[188:191], v[92:95]
	v_mfma_f32_16x16x32_bf16 v[64:67], v[154:157], v[196:199], v[64:67]
	v_mfma_f32_16x16x32_bf16 v[68:71], v[164:167], v[196:199], v[68:71]
	v_mfma_f32_16x16x32_bf16 v[120:123], v[158:161], v[176:179], v[120:123]
	v_mfma_f32_16x16x32_bf16 v[124:127], v[168:171], v[176:179], v[124:127]
	v_mfma_f32_16x16x32_bf16 v[104:107], v[158:161], v[184:187], v[104:107]
	v_mfma_f32_16x16x32_bf16 v[108:111], v[168:171], v[184:187], v[108:111]
	v_mfma_f32_16x16x32_bf16 v[88:91], v[158:161], v[192:195], v[88:91]
	v_mfma_f32_16x16x32_bf16 v[92:95], v[168:171], v[192:195], v[92:95]
	v_mfma_f32_16x16x32_bf16 v[64:67], v[158:161], v[200:203], v[64:67]
	v_mfma_f32_16x16x32_bf16 v[68:71], v[168:171], v[200:203], v[68:71]
	s_setprio 1
	s_barrier
	s_add_i32 s16, s31, s26
	v_lshl_add_u64 v[204:205], v[204:205], 0, s[24:25]
	s_mov_b32 m0, s16
	ds_read_b128 v[172:175], v163 offset:49152
	ds_read_b128 v[176:179], v163 offset:50176
	ds_read_b128 v[180:183], v163 offset:51200
	ds_read_b128 v[184:187], v163 offset:52224
	ds_read_b128 v[188:191], v163 offset:53248
	ds_read_b128 v[192:195], v163 offset:54272
	ds_read_b128 v[196:199], v163 offset:55296
	ds_read_b128 v[200:203], v163 offset:56320
	global_load_lds_dwordx4 v[204:205], off
	s_add_i32 m0, s16, 0x2000
	s_add_u32 s8, s8, 0x80080
	v_lshl_add_u64 v[204:205], v[206:207], 0, s[24:25]
	s_addc_u32 s9, s9, 0
	s_add_i32 s16, s33, s26
	global_load_lds_dwordx4 v[204:205], off
	v_lshl_add_u64 v[204:205], s[8:9], 0, v[224:225]
	s_mov_b32 m0, s16
	s_nop 0
	global_load_lds_dwordx4 v[204:205], off
	v_lshl_add_u64 v[204:205], s[8:9], 0, v[144:145]
	s_add_i32 m0, s16, 0x2000
	s_nop 0
	global_load_lds_dwordx4 v[204:205], off
	v_lshl_add_u64 v[204:205], v[208:209], 0, s[24:25]
	s_mov_b32 m0, s58
	s_nop 0
	global_load_lds_dwordx4 v[204:205], off
	v_lshl_add_u64 v[204:205], v[210:211], 0, s[24:25]
	s_mov_b32 m0, s59
	s_nop 0
	global_load_lds_dwordx4 v[204:205], off
	s_waitcnt vmcnt(8)
	s_waitcnt lgkmcnt(0)
	s_barrier
	s_setprio 0
	s_waitcnt lgkmcnt(0)
	v_mfma_f32_16x16x32_bf16 v[56:59], v[128:131], v[172:175], v[56:59]
	v_mfma_f32_16x16x32_bf16 v[60:63], v[136:139], v[172:175], v[60:63]
	v_mfma_f32_16x16x32_bf16 v[32:35], v[128:131], v[180:183], v[32:35]
	v_mfma_f32_16x16x32_bf16 v[36:39], v[136:139], v[180:183], v[36:39]
	v_mfma_f32_16x16x32_bf16 v[16:19], v[128:131], v[188:191], v[16:19]
	v_mfma_f32_16x16x32_bf16 v[20:23], v[136:139], v[188:191], v[20:23]
	v_mfma_f32_16x16x32_bf16 v[0:3], v[128:131], v[196:199], v[0:3]
	v_mfma_f32_16x16x32_bf16 v[4:7], v[136:139], v[196:199], v[4:7]
	v_mfma_f32_16x16x32_bf16 v[56:59], v[132:135], v[176:179], v[56:59]
	v_mfma_f32_16x16x32_bf16 v[60:63], v[140:143], v[176:179], v[60:63]
	v_mfma_f32_16x16x32_bf16 v[32:35], v[132:135], v[184:187], v[32:35]
	v_mfma_f32_16x16x32_bf16 v[36:39], v[140:143], v[184:187], v[36:39]
	v_mfma_f32_16x16x32_bf16 v[16:19], v[132:135], v[192:195], v[16:19]
	v_mfma_f32_16x16x32_bf16 v[20:23], v[140:143], v[192:195], v[20:23]
	v_mfma_f32_16x16x32_bf16 v[0:3], v[132:135], v[200:203], v[0:3]
	v_mfma_f32_16x16x32_bf16 v[4:7], v[140:143], v[200:203], v[4:7]
	s_setprio 1
	s_setprio 0
	v_mfma_f32_16x16x32_bf16 v[72:75], v[154:157], v[172:175], v[72:75]
	v_mfma_f32_16x16x32_bf16 v[76:79], v[164:167], v[172:175], v[76:79]
	v_mfma_f32_16x16x32_bf16 v[40:43], v[154:157], v[180:183], v[40:43]
	v_mfma_f32_16x16x32_bf16 v[44:47], v[164:167], v[180:183], v[44:47]
	v_mfma_f32_16x16x32_bf16 v[24:27], v[154:157], v[188:191], v[24:27]
	v_mfma_f32_16x16x32_bf16 v[28:31], v[164:167], v[188:191], v[28:31]
	v_mfma_f32_16x16x32_bf16 v[8:11], v[154:157], v[196:199], v[8:11]
	v_mfma_f32_16x16x32_bf16 v[12:15], v[164:167], v[196:199], v[12:15]
	v_mfma_f32_16x16x32_bf16 v[72:75], v[158:161], v[176:179], v[72:75]
	v_mfma_f32_16x16x32_bf16 v[76:79], v[168:171], v[176:179], v[76:79]
	v_mfma_f32_16x16x32_bf16 v[40:43], v[158:161], v[184:187], v[40:43]
	v_mfma_f32_16x16x32_bf16 v[44:47], v[168:171], v[184:187], v[44:47]
	v_mfma_f32_16x16x32_bf16 v[24:27], v[158:161], v[192:195], v[24:27]
	v_mfma_f32_16x16x32_bf16 v[28:31], v[168:171], v[192:195], v[28:31]
	v_mfma_f32_16x16x32_bf16 v[8:11], v[158:161], v[200:203], v[8:11]
	v_mfma_f32_16x16x32_bf16 v[12:15], v[168:171], v[200:203], v[12:15]
	s_setprio 1
	s_barrier
	s_add_u32 s12, s12, 0x100
	s_addc_u32 s13, s13, 0
	s_add_u32 s7, s7, 0x100
	s_addc_u32 s10, s10, 0
	s_cmp_ge_i32 s30, s57
	s_mov_b32 s8, s30
	s_cbranch_scc0 .LBB0_344

.LBB0_920:
	s_add_i32 s33, s8, 2
	s_add_u32 s9, s12, 0xffff0080
	s_addc_u32 s20, s13, -1
	s_add_i32 s61, 0, 0x10000
	s_cmp_eq_u32 s59, s8
	s_cselect_b32 s21, s3, s20
	s_cselect_b32 s20, s7, s9
	s_cselect_b32 s9, s23, s31
	s_cselect_b32 s8, s27, s30
	s_add_i32 s64, 0, 0x14000
	v_add_u32_e32 v150, s61, v170
	v_add_u32_e32 v166, s64, v170
	ds_read_b128 v[128:131], v150
	ds_read_b128 v[132:135], v150 offset:1024
	ds_read_b128 v[146:149], v150 offset:2048
	ds_read_b128 v[150:153], v150 offset:3072
	ds_read_b128 v[154:157], v166
	ds_read_b128 v[158:161], v166 offset:1024
	ds_read_b128 v[162:165], v166 offset:2048
	ds_read_b128 v[166:169], v166 offset:3072
	v_lshl_add_u64 v[204:205], s[12:13], 0, v[142:143]
	s_add_i32 m0, s49, 0xc000
	ds_read_b128 v[172:175], v171
	ds_read_b128 v[176:179], v171 offset:1024
	ds_read_b128 v[180:183], v171 offset:2048
	ds_read_b128 v[184:187], v171 offset:3072
	ds_read_b128 v[188:191], v171 offset:4096
	ds_read_b128 v[192:195], v171 offset:5120
	ds_read_b128 v[196:199], v171 offset:6144
	ds_read_b128 v[200:203], v171 offset:7168
	global_load_lds_dwordx4 v[204:205], off
	v_lshl_add_u64 v[204:205], s[12:13], 0, v[144:145]
	s_add_i32 m0, s49, 0xe000
	s_nop 0
	global_load_lds_dwordx4 v[204:205], off
	s_waitcnt vmcnt(8)
	s_waitcnt lgkmcnt(0)
	s_barrier
	s_setprio 0
	s_waitcnt lgkmcnt(0)
	v_mfma_f32_16x16x32_bf16 v[120:123], v[128:131], v[172:175], v[120:123]
	v_mfma_f32_16x16x32_bf16 v[124:127], v[146:149], v[172:175], v[124:127]
	v_mfma_f32_16x16x32_bf16 v[116:119], v[128:131], v[180:183], v[116:119]
	v_mfma_f32_16x16x32_bf16 v[112:115], v[146:149], v[180:183], v[112:115]
	v_mfma_f32_16x16x32_bf16 v[108:111], v[128:131], v[188:191], v[108:111]
	v_mfma_f32_16x16x32_bf16 v[104:107], v[146:149], v[188:191], v[104:107]
	v_mfma_f32_16x16x32_bf16 v[100:103], v[128:131], v[196:199], v[100:103]
	v_mfma_f32_16x16x32_bf16 v[96:99], v[146:149], v[196:199], v[96:99]
	v_mfma_f32_16x16x32_bf16 v[120:123], v[132:135], v[176:179], v[120:123]
	v_mfma_f32_16x16x32_bf16 v[124:127], v[150:153], v[176:179], v[124:127]
	v_mfma_f32_16x16x32_bf16 v[116:119], v[132:135], v[184:187], v[116:119]
	v_mfma_f32_16x16x32_bf16 v[112:115], v[150:153], v[184:187], v[112:115]
	v_mfma_f32_16x16x32_bf16 v[108:111], v[132:135], v[192:195], v[108:111]
	v_mfma_f32_16x16x32_bf16 v[104:107], v[150:153], v[192:195], v[104:107]
	v_mfma_f32_16x16x32_bf16 v[100:103], v[132:135], v[200:203], v[100:103]
	v_mfma_f32_16x16x32_bf16 v[96:99], v[150:153], v[200:203], v[96:99]
	s_setprio 1
	s_setprio 0
	v_mfma_f32_16x16x32_bf16 v[60:63], v[154:157], v[172:175], v[60:63]
	v_mfma_f32_16x16x32_bf16 v[56:59], v[162:165], v[172:175], v[56:59]
	v_mfma_f32_16x16x32_bf16 v[52:55], v[154:157], v[180:183], v[52:55]
	v_mfma_f32_16x16x32_bf16 v[48:51], v[162:165], v[180:183], v[48:51]
	v_mfma_f32_16x16x32_bf16 v[44:47], v[154:157], v[188:191], v[44:47]
	v_mfma_f32_16x16x32_bf16 v[40:43], v[162:165], v[188:191], v[40:43]
	v_mfma_f32_16x16x32_bf16 v[36:39], v[154:157], v[196:199], v[36:39]
	v_mfma_f32_16x16x32_bf16 v[32:35], v[162:165], v[196:199], v[32:35]
	v_mfma_f32_16x16x32_bf16 v[60:63], v[158:161], v[176:179], v[60:63]
	v_mfma_f32_16x16x32_bf16 v[56:59], v[166:169], v[176:179], v[56:59]
	v_mfma_f32_16x16x32_bf16 v[52:55], v[158:161], v[184:187], v[52:55]
	v_mfma_f32_16x16x32_bf16 v[48:51], v[166:169], v[184:187], v[48:51]
	v_mfma_f32_16x16x32_bf16 v[44:47], v[158:161], v[192:195], v[44:47]
	v_mfma_f32_16x16x32_bf16 v[40:43], v[166:169], v[192:195], v[40:43]
	v_mfma_f32_16x16x32_bf16 v[36:39], v[158:161], v[200:203], v[36:39]
	v_mfma_f32_16x16x32_bf16 v[32:35], v[166:169], v[200:203], v[32:35]
	s_setprio 1
	s_barrier
	s_add_i32 s61, s61, s35
	v_lshl_add_u64 v[204:205], s[8:9], 0, v[224:225]
	s_mov_b32 m0, s61
	ds_read_b128 v[172:175], v171 offset:16384
	ds_read_b128 v[176:179], v171 offset:17408
	ds_read_b128 v[180:183], v171 offset:18432
	ds_read_b128 v[184:187], v171 offset:19456
	ds_read_b128 v[188:191], v171 offset:20480
	ds_read_b128 v[192:195], v171 offset:21504
	ds_read_b128 v[196:199], v171 offset:22528
	ds_read_b128 v[200:203], v171 offset:23552
	global_load_lds_dwordx4 v[204:205], off
	s_add_i32 m0, s61, 0x2000
	s_add_u32 s62, s8, 0x10000
	v_lshl_add_u64 v[206:207], s[8:9], 0, v[136:137]
	s_addc_u32 s63, s9, 0
	s_add_i32 s61, s64, s35
	global_load_lds_dwordx4 v[206:207], off
	v_lshl_add_u64 v[208:209], s[62:63], 0, v[224:225]
	s_mov_b32 m0, s61
	v_lshl_add_u64 v[210:211], s[20:21], 0, v[138:139]
	global_load_lds_dwordx4 v[208:209], off
	v_lshl_add_u64 v[208:209], s[62:63], 0, v[136:137]
	s_add_i32 m0, s61, 0x2000
	s_nop 0
	global_load_lds_dwordx4 v[208:209], off
	v_lshl_add_u64 v[208:209], s[20:21], 0, v[140:141]
	s_mov_b32 m0, s49
	s_nop 0
	global_load_lds_dwordx4 v[208:209], off
	s_mov_b32 m0, s50
	s_nop 0
	global_load_lds_dwordx4 v[210:211], off
	s_waitcnt vmcnt(8)
	s_waitcnt lgkmcnt(0)
	s_barrier
	s_setprio 0
	s_waitcnt lgkmcnt(0)
	v_mfma_f32_16x16x32_bf16 v[92:95], v[128:131], v[172:175], v[92:95]
	v_mfma_f32_16x16x32_bf16 v[88:91], v[146:149], v[172:175], v[88:91]
	v_mfma_f32_16x16x32_bf16 v[84:87], v[128:131], v[180:183], v[84:87]
	v_mfma_f32_16x16x32_bf16 v[80:83], v[146:149], v[180:183], v[80:83]
	v_mfma_f32_16x16x32_bf16 v[76:79], v[128:131], v[188:191], v[76:79]
	v_mfma_f32_16x16x32_bf16 v[72:75], v[146:149], v[188:191], v[72:75]
	v_mfma_f32_16x16x32_bf16 v[68:71], v[128:131], v[196:199], v[68:71]
	v_mfma_f32_16x16x32_bf16 v[64:67], v[146:149], v[196:199], v[64:67]
	v_mfma_f32_16x16x32_bf16 v[92:95], v[132:135], v[176:179], v[92:95]
	v_mfma_f32_16x16x32_bf16 v[88:91], v[150:153], v[176:179], v[88:91]
	v_mfma_f32_16x16x32_bf16 v[84:87], v[132:135], v[184:187], v[84:87]
	v_mfma_f32_16x16x32_bf16 v[80:83], v[150:153], v[184:187], v[80:83]
	v_mfma_f32_16x16x32_bf16 v[76:79], v[132:135], v[192:195], v[76:79]
	v_mfma_f32_16x16x32_bf16 v[72:75], v[150:153], v[192:195], v[72:75]
	v_mfma_f32_16x16x32_bf16 v[68:71], v[132:135], v[200:203], v[68:71]
	v_mfma_f32_16x16x32_bf16 v[64:67], v[150:153], v[200:203], v[64:67]
	s_setprio 1
	s_setprio 0
	v_mfma_f32_16x16x32_bf16 v[28:31], v[154:157], v[172:175], v[28:31]
	v_mfma_f32_16x16x32_bf16 v[24:27], v[162:165], v[172:175], v[24:27]
	v_mfma_f32_16x16x32_bf16 v[20:23], v[154:157], v[180:183], v[20:23]
	v_mfma_f32_16x16x32_bf16 v[16:19], v[162:165], v[180:183], v[16:19]
	v_mfma_f32_16x16x32_bf16 v[12:15], v[154:157], v[188:191], v[12:15]
	v_mfma_f32_16x16x32_bf16 v[8:11], v[162:165], v[188:191], v[8:11]
	v_mfma_f32_16x16x32_bf16 v[4:7], v[154:157], v[196:199], v[4:7]
	v_mfma_f32_16x16x32_bf16 v[0:3], v[162:165], v[196:199], v[0:3]
	v_mfma_f32_16x16x32_bf16 v[28:31], v[158:161], v[176:179], v[28:31]
	v_mfma_f32_16x16x32_bf16 v[24:27], v[166:169], v[176:179], v[24:27]
	v_mfma_f32_16x16x32_bf16 v[20:23], v[158:161], v[184:187], v[20:23]
	v_mfma_f32_16x16x32_bf16 v[16:19], v[166:169], v[184:187], v[16:19]
	v_mfma_f32_16x16x32_bf16 v[12:15], v[158:161], v[192:195], v[12:15]
	v_mfma_f32_16x16x32_bf16 v[8:11], v[166:169], v[192:195], v[8:11]
	v_mfma_f32_16x16x32_bf16 v[4:7], v[158:161], v[200:203], v[4:7]
	v_mfma_f32_16x16x32_bf16 v[0:3], v[166:169], v[200:203], v[0:3]
	s_setprio 1
	s_barrier
	s_add_i32 s61, 0, 0x18000
	s_add_i32 s62, 0, 0x1c000
	v_add_u32_e32 v150, s61, v170
	v_add_u32_e32 v166, s62, v170
	ds_read_b128 v[128:131], v150
	ds_read_b128 v[132:135], v150 offset:1024
	ds_read_b128 v[146:149], v150 offset:2048
	ds_read_b128 v[150:153], v150 offset:3072
	ds_read_b128 v[154:157], v166
	ds_read_b128 v[158:161], v166 offset:1024
	ds_read_b128 v[162:165], v166 offset:2048
	ds_read_b128 v[166:169], v166 offset:3072
	s_add_u32 s20, s20, 0x10000
	s_addc_u32 s21, s21, 0
	s_mov_b32 m0, s51
	v_lshl_add_u64 v[212:213], s[20:21], 0, v[140:141]
	ds_read_b128 v[172:175], v171 offset:32768
	ds_read_b128 v[176:179], v171 offset:33792
	ds_read_b128 v[180:183], v171 offset:34816
	ds_read_b128 v[184:187], v171 offset:35840
	ds_read_b128 v[188:191], v171 offset:36864
	ds_read_b128 v[192:195], v171 offset:37888
	ds_read_b128 v[196:199], v171 offset:38912
	ds_read_b128 v[200:203], v171 offset:39936
	global_load_lds_dwordx4 v[212:213], off
	v_lshl_add_u64 v[212:213], s[20:21], 0, v[138:139]
	s_mov_b32 m0, s52
	s_nop 0
	global_load_lds_dwordx4 v[212:213], off
	s_waitcnt vmcnt(8)
	s_waitcnt lgkmcnt(0)
	s_barrier
	s_setprio 0
	s_waitcnt lgkmcnt(0)
	v_mfma_f32_16x16x32_bf16 v[120:123], v[128:131], v[172:175], v[120:123]
	v_mfma_f32_16x16x32_bf16 v[124:127], v[146:149], v[172:175], v[124:127]
	v_mfma_f32_16x16x32_bf16 v[116:119], v[128:131], v[180:183], v[116:119]
	v_mfma_f32_16x16x32_bf16 v[112:115], v[146:149], v[180:183], v[112:115]
	v_mfma_f32_16x16x32_bf16 v[108:111], v[128:131], v[188:191], v[108:111]
	v_mfma_f32_16x16x32_bf16 v[104:107], v[146:149], v[188:191], v[104:107]
	v_mfma_f32_16x16x32_bf16 v[100:103], v[128:131], v[196:199], v[100:103]
	v_mfma_f32_16x16x32_bf16 v[96:99], v[146:149], v[196:199], v[96:99]
	v_mfma_f32_16x16x32_bf16 v[120:123], v[132:135], v[176:179], v[120:123]
	v_mfma_f32_16x16x32_bf16 v[124:127], v[150:153], v[176:179], v[124:127]
	v_mfma_f32_16x16x32_bf16 v[116:119], v[132:135], v[184:187], v[116:119]
	v_mfma_f32_16x16x32_bf16 v[112:115], v[150:153], v[184:187], v[112:115]
	v_mfma_f32_16x16x32_bf16 v[108:111], v[132:135], v[192:195], v[108:111]
	v_mfma_f32_16x16x32_bf16 v[104:107], v[150:153], v[192:195], v[104:107]
	v_mfma_f32_16x16x32_bf16 v[100:103], v[132:135], v[200:203], v[100:103]
	v_mfma_f32_16x16x32_bf16 v[96:99], v[150:153], v[200:203], v[96:99]
	s_setprio 1
	s_setprio 0
	v_mfma_f32_16x16x32_bf16 v[60:63], v[154:157], v[172:175], v[60:63]
	v_mfma_f32_16x16x32_bf16 v[56:59], v[162:165], v[172:175], v[56:59]
	v_mfma_f32_16x16x32_bf16 v[52:55], v[154:157], v[180:183], v[52:55]
	v_mfma_f32_16x16x32_bf16 v[48:51], v[162:165], v[180:183], v[48:51]
	v_mfma_f32_16x16x32_bf16 v[44:47], v[154:157], v[188:191], v[44:47]
	v_mfma_f32_16x16x32_bf16 v[40:43], v[162:165], v[188:191], v[40:43]
	v_mfma_f32_16x16x32_bf16 v[36:39], v[154:157], v[196:199], v[36:39]
	v_mfma_f32_16x16x32_bf16 v[32:35], v[162:165], v[196:199], v[32:35]
	v_mfma_f32_16x16x32_bf16 v[60:63], v[158:161], v[176:179], v[60:63]
	v_mfma_f32_16x16x32_bf16 v[56:59], v[166:169], v[176:179], v[56:59]
	v_mfma_f32_16x16x32_bf16 v[52:55], v[158:161], v[184:187], v[52:55]
	v_mfma_f32_16x16x32_bf16 v[48:51], v[166:169], v[184:187], v[48:51]
	v_mfma_f32_16x16x32_bf16 v[44:47], v[158:161], v[192:195], v[44:47]
	v_mfma_f32_16x16x32_bf16 v[40:43], v[166:169], v[192:195], v[40:43]
	v_mfma_f32_16x16x32_bf16 v[36:39], v[158:161], v[200:203], v[36:39]
	v_mfma_f32_16x16x32_bf16 v[32:35], v[166:169], v[200:203], v[32:35]
	s_setprio 1
	s_barrier
	s_add_i32 s20, s61, s35
	v_lshl_add_u64 v[204:205], v[204:205], 0, s[24:25]
	s_mov_b32 m0, s20
	ds_read_b128 v[172:175], v171 offset:49152
	ds_read_b128 v[176:179], v171 offset:50176
	ds_read_b128 v[180:183], v171 offset:51200
	ds_read_b128 v[184:187], v171 offset:52224
	ds_read_b128 v[188:191], v171 offset:53248
	ds_read_b128 v[192:195], v171 offset:54272
	ds_read_b128 v[196:199], v171 offset:55296
	ds_read_b128 v[200:203], v171 offset:56320
	global_load_lds_dwordx4 v[204:205], off
	s_add_i32 m0, s20, 0x2000
	s_add_u32 s8, s8, 0x10080
	v_lshl_add_u64 v[204:205], v[206:207], 0, s[24:25]
	s_addc_u32 s9, s9, 0
	s_add_i32 s20, s62, s35
	global_load_lds_dwordx4 v[204:205], off
	v_lshl_add_u64 v[204:205], s[8:9], 0, v[224:225]
	s_mov_b32 m0, s20
	s_nop 0
	global_load_lds_dwordx4 v[204:205], off
	v_lshl_add_u64 v[204:205], s[8:9], 0, v[136:137]
	s_add_i32 m0, s20, 0x2000
	s_nop 0
	global_load_lds_dwordx4 v[204:205], off
	v_lshl_add_u64 v[204:205], v[208:209], 0, s[24:25]
	s_mov_b32 m0, s57
	s_nop 0
	global_load_lds_dwordx4 v[204:205], off
	v_lshl_add_u64 v[204:205], v[210:211], 0, s[24:25]
	s_mov_b32 m0, s58
	s_nop 0
	global_load_lds_dwordx4 v[204:205], off
	s_waitcnt vmcnt(8)
	s_waitcnt lgkmcnt(0)
	s_barrier
	s_setprio 0
	s_waitcnt lgkmcnt(0)
	v_mfma_f32_16x16x32_bf16 v[92:95], v[128:131], v[172:175], v[92:95]
	v_mfma_f32_16x16x32_bf16 v[88:91], v[146:149], v[172:175], v[88:91]
	v_mfma_f32_16x16x32_bf16 v[84:87], v[128:131], v[180:183], v[84:87]
	v_mfma_f32_16x16x32_bf16 v[80:83], v[146:149], v[180:183], v[80:83]
	v_mfma_f32_16x16x32_bf16 v[76:79], v[128:131], v[188:191], v[76:79]
	v_mfma_f32_16x16x32_bf16 v[72:75], v[146:149], v[188:191], v[72:75]
	v_mfma_f32_16x16x32_bf16 v[68:71], v[128:131], v[196:199], v[68:71]
	v_mfma_f32_16x16x32_bf16 v[64:67], v[146:149], v[196:199], v[64:67]
	v_mfma_f32_16x16x32_bf16 v[92:95], v[132:135], v[176:179], v[92:95]
	v_mfma_f32_16x16x32_bf16 v[88:91], v[150:153], v[176:179], v[88:91]
	v_mfma_f32_16x16x32_bf16 v[84:87], v[132:135], v[184:187], v[84:87]
	v_mfma_f32_16x16x32_bf16 v[80:83], v[150:153], v[184:187], v[80:83]
	v_mfma_f32_16x16x32_bf16 v[76:79], v[132:135], v[192:195], v[76:79]
	v_mfma_f32_16x16x32_bf16 v[72:75], v[150:153], v[192:195], v[72:75]
	v_mfma_f32_16x16x32_bf16 v[68:71], v[132:135], v[200:203], v[68:71]
	v_mfma_f32_16x16x32_bf16 v[64:67], v[150:153], v[200:203], v[64:67]
	s_setprio 1
	s_setprio 0
	v_mfma_f32_16x16x32_bf16 v[28:31], v[154:157], v[172:175], v[28:31]
	v_mfma_f32_16x16x32_bf16 v[24:27], v[162:165], v[172:175], v[24:27]
	v_mfma_f32_16x16x32_bf16 v[20:23], v[154:157], v[180:183], v[20:23]
	v_mfma_f32_16x16x32_bf16 v[16:19], v[162:165], v[180:183], v[16:19]
	v_mfma_f32_16x16x32_bf16 v[12:15], v[154:157], v[188:191], v[12:15]
	v_mfma_f32_16x16x32_bf16 v[8:11], v[162:165], v[188:191], v[8:11]
	v_mfma_f32_16x16x32_bf16 v[4:7], v[154:157], v[196:199], v[4:7]
	v_mfma_f32_16x16x32_bf16 v[0:3], v[162:165], v[196:199], v[0:3]
	v_mfma_f32_16x16x32_bf16 v[28:31], v[158:161], v[176:179], v[28:31]
	v_mfma_f32_16x16x32_bf16 v[24:27], v[166:169], v[176:179], v[24:27]
	v_mfma_f32_16x16x32_bf16 v[20:23], v[158:161], v[184:187], v[20:23]
	v_mfma_f32_16x16x32_bf16 v[16:19], v[166:169], v[184:187], v[16:19]
	v_mfma_f32_16x16x32_bf16 v[12:15], v[158:161], v[192:195], v[12:15]
	v_mfma_f32_16x16x32_bf16 v[8:11], v[166:169], v[192:195], v[8:11]
	v_mfma_f32_16x16x32_bf16 v[4:7], v[158:161], v[200:203], v[4:7]
	v_mfma_f32_16x16x32_bf16 v[0:3], v[166:169], v[200:203], v[0:3]
	s_setprio 1
	s_barrier
	s_add_u32 s12, s12, 0x100
	s_addc_u32 s13, s13, 0
	s_add_u32 s30, s30, 0x100
	s_addc_u32 s31, s31, 0
	s_cmp_ge_i32 s33, s56
	s_mov_b32 s8, s33
	s_cbranch_scc0 .LBB0_920
	v_readlane_b32 s64, v253, 21
	v_readlane_b32 s63, v253, 24
	v_readlane_b32 s65, v253, 22

.LBB0_1313:
	s_add_i32 s56, s8, 2
	s_add_u32 s9, s12, 0xfff80080
	s_addc_u32 s28, s13, -1
	s_add_i32 s57, 0, 0x10000
	s_cmp_eq_u32 s48, s8
	s_cselect_b32 s29, s27, s28
	s_cselect_b32 s28, s35, s9
	v_add_u32_e32 v138, s57, v139
	s_cselect_b32 s9, s52, s55
	s_cselect_b32 s8, s53, s54
	s_add_i32 s60, 0, 0x14000
	ds_read_b128 v[140:143], v138
	ds_read_b128 v[146:149], v138 offset:1024
	ds_read_b128 v[150:153], v138 offset:2048
	ds_read_b128 v[154:157], v138 offset:3072
	v_add_u32_e32 v138, s60, v139
	ds_read_b128 v[158:161], v138
	ds_read_b128 v[162:165], v138 offset:1024
	ds_read_b128 v[166:169], v138 offset:2048
	ds_read_b128 v[170:173], v138 offset:3072
	v_lshl_add_u64 v[206:207], s[12:13], 0, v[134:135]
	s_add_i32 m0, s31, 0xc000
	ds_read_b128 v[174:177], v144
	ds_read_b128 v[178:181], v144 offset:1024
	ds_read_b128 v[182:185], v144 offset:2048
	ds_read_b128 v[186:189], v144 offset:3072
	ds_read_b128 v[190:193], v144 offset:4096
	ds_read_b128 v[194:197], v144 offset:5120
	ds_read_b128 v[198:201], v144 offset:6144
	ds_read_b128 v[202:205], v144 offset:7168
	global_load_lds_dwordx4 v[206:207], off
	v_lshl_add_u64 v[206:207], s[12:13], 0, v[136:137]
	s_add_i32 m0, s31, 0xe000
	s_nop 0
	global_load_lds_dwordx4 v[206:207], off
	s_waitcnt vmcnt(8)
	s_waitcnt lgkmcnt(0)
	s_barrier
	s_setprio 0
	s_waitcnt lgkmcnt(0)
	v_mfma_f32_16x16x32_bf16 v[116:119], v[140:143], v[174:177], v[116:119]
	v_mfma_f32_16x16x32_bf16 v[112:115], v[150:153], v[174:177], v[112:115]
	v_mfma_f32_16x16x32_bf16 v[100:103], v[140:143], v[182:185], v[100:103]
	v_mfma_f32_16x16x32_bf16 v[96:99], v[150:153], v[182:185], v[96:99]
	v_mfma_f32_16x16x32_bf16 v[84:87], v[140:143], v[190:193], v[84:87]
	v_mfma_f32_16x16x32_bf16 v[80:83], v[150:153], v[190:193], v[80:83]
	v_mfma_f32_16x16x32_bf16 v[68:71], v[140:143], v[198:201], v[68:71]
	v_mfma_f32_16x16x32_bf16 v[60:63], v[150:153], v[198:201], v[60:63]
	v_mfma_f32_16x16x32_bf16 v[116:119], v[146:149], v[178:181], v[116:119]
	v_mfma_f32_16x16x32_bf16 v[112:115], v[154:157], v[178:181], v[112:115]
	v_mfma_f32_16x16x32_bf16 v[100:103], v[146:149], v[186:189], v[100:103]
	v_mfma_f32_16x16x32_bf16 v[96:99], v[154:157], v[186:189], v[96:99]
	v_mfma_f32_16x16x32_bf16 v[84:87], v[146:149], v[194:197], v[84:87]
	v_mfma_f32_16x16x32_bf16 v[80:83], v[154:157], v[194:197], v[80:83]
	v_mfma_f32_16x16x32_bf16 v[68:71], v[146:149], v[202:205], v[68:71]
	v_mfma_f32_16x16x32_bf16 v[60:63], v[154:157], v[202:205], v[60:63]
	s_setprio 1
	s_setprio 0
	v_mfma_f32_16x16x32_bf16 v[124:127], v[158:161], v[174:177], v[124:127]
	v_mfma_f32_16x16x32_bf16 v[120:123], v[166:169], v[174:177], v[120:123]
	v_mfma_f32_16x16x32_bf16 v[108:111], v[158:161], v[182:185], v[108:111]
	v_mfma_f32_16x16x32_bf16 v[104:107], v[166:169], v[182:185], v[104:107]
	v_mfma_f32_16x16x32_bf16 v[92:95], v[158:161], v[190:193], v[92:95]
	v_mfma_f32_16x16x32_bf16 v[88:91], v[166:169], v[190:193], v[88:91]
	v_mfma_f32_16x16x32_bf16 v[76:79], v[158:161], v[198:201], v[76:79]
	v_mfma_f32_16x16x32_bf16 v[72:75], v[166:169], v[198:201], v[72:75]
	v_mfma_f32_16x16x32_bf16 v[124:127], v[162:165], v[178:181], v[124:127]
	v_mfma_f32_16x16x32_bf16 v[120:123], v[170:173], v[178:181], v[120:123]
	v_mfma_f32_16x16x32_bf16 v[108:111], v[162:165], v[186:189], v[108:111]
	v_mfma_f32_16x16x32_bf16 v[104:107], v[170:173], v[186:189], v[104:107]
	v_mfma_f32_16x16x32_bf16 v[92:95], v[162:165], v[194:197], v[92:95]
	v_mfma_f32_16x16x32_bf16 v[88:91], v[170:173], v[194:197], v[88:91]
	v_mfma_f32_16x16x32_bf16 v[76:79], v[162:165], v[202:205], v[76:79]
	v_mfma_f32_16x16x32_bf16 v[72:75], v[170:173], v[202:205], v[72:75]
	s_setprio 1
	s_barrier
	s_add_i32 s57, s57, s10
	v_lshl_add_u64 v[206:207], s[8:9], 0, v[224:225]
	s_mov_b32 m0, s57
	ds_read_b128 v[174:177], v144 offset:16384
	ds_read_b128 v[178:181], v144 offset:17408
	ds_read_b128 v[182:185], v144 offset:18432
	ds_read_b128 v[186:189], v144 offset:19456
	ds_read_b128 v[190:193], v144 offset:20480
	ds_read_b128 v[194:197], v144 offset:21504
	ds_read_b128 v[198:201], v144 offset:22528
	ds_read_b128 v[202:205], v144 offset:23552
	global_load_lds_dwordx4 v[206:207], off
	s_add_i32 m0, s57, 0x2000
	s_add_u32 s58, s8, 0x80000
	v_lshl_add_u64 v[208:209], s[8:9], 0, v[128:129]
	s_addc_u32 s59, s9, 0
	s_add_i32 s57, s60, s10
	global_load_lds_dwordx4 v[208:209], off
	v_lshl_add_u64 v[210:211], s[58:59], 0, v[224:225]
	s_mov_b32 m0, s57
	v_lshl_add_u64 v[212:213], s[28:29], 0, v[130:131]
	global_load_lds_dwordx4 v[210:211], off
	v_lshl_add_u64 v[210:211], s[58:59], 0, v[128:129]
	s_add_i32 m0, s57, 0x2000
	s_nop 0
	global_load_lds_dwordx4 v[210:211], off
	v_lshl_add_u64 v[210:211], s[28:29], 0, v[132:133]
	s_mov_b32 m0, s31
	s_nop 0
	global_load_lds_dwordx4 v[210:211], off
	s_mov_b32 m0, s33
	s_nop 0
	global_load_lds_dwordx4 v[212:213], off
	s_waitcnt vmcnt(8)
	s_waitcnt lgkmcnt(0)
	s_barrier
	s_setprio 0
	s_waitcnt lgkmcnt(0)
	v_mfma_f32_16x16x32_bf16 v[52:55], v[140:143], v[174:177], v[52:55]
	v_mfma_f32_16x16x32_bf16 v[48:51], v[150:153], v[174:177], v[48:51]
	v_mfma_f32_16x16x32_bf16 v[36:39], v[140:143], v[182:185], v[36:39]
	v_mfma_f32_16x16x32_bf16 v[32:35], v[150:153], v[182:185], v[32:35]
	v_mfma_f32_16x16x32_bf16 v[20:23], v[140:143], v[190:193], v[20:23]
	v_mfma_f32_16x16x32_bf16 v[16:19], v[150:153], v[190:193], v[16:19]
	v_mfma_f32_16x16x32_bf16 v[4:7], v[140:143], v[198:201], v[4:7]
	v_mfma_f32_16x16x32_bf16 v[0:3], v[150:153], v[198:201], v[0:3]
	v_mfma_f32_16x16x32_bf16 v[52:55], v[146:149], v[178:181], v[52:55]
	v_mfma_f32_16x16x32_bf16 v[48:51], v[154:157], v[178:181], v[48:51]
	v_mfma_f32_16x16x32_bf16 v[36:39], v[146:149], v[186:189], v[36:39]
	v_mfma_f32_16x16x32_bf16 v[32:35], v[154:157], v[186:189], v[32:35]
	v_mfma_f32_16x16x32_bf16 v[20:23], v[146:149], v[194:197], v[20:23]
	v_mfma_f32_16x16x32_bf16 v[16:19], v[154:157], v[194:197], v[16:19]
	v_mfma_f32_16x16x32_bf16 v[4:7], v[146:149], v[202:205], v[4:7]
	v_mfma_f32_16x16x32_bf16 v[0:3], v[154:157], v[202:205], v[0:3]
	s_setprio 1
	s_setprio 0
	v_mfma_f32_16x16x32_bf16 v[64:67], v[158:161], v[174:177], v[64:67]
	v_mfma_f32_16x16x32_bf16 v[56:59], v[166:169], v[174:177], v[56:59]
	v_mfma_f32_16x16x32_bf16 v[44:47], v[158:161], v[182:185], v[44:47]
	v_mfma_f32_16x16x32_bf16 v[40:43], v[166:169], v[182:185], v[40:43]
	v_mfma_f32_16x16x32_bf16 v[28:31], v[158:161], v[190:193], v[28:31]
	v_mfma_f32_16x16x32_bf16 v[24:27], v[166:169], v[190:193], v[24:27]
	v_mfma_f32_16x16x32_bf16 v[8:11], v[158:161], v[198:201], v[8:11]
	v_mfma_f32_16x16x32_bf16 v[12:15], v[166:169], v[198:201], v[12:15]
	v_mfma_f32_16x16x32_bf16 v[64:67], v[162:165], v[178:181], v[64:67]
	v_mfma_f32_16x16x32_bf16 v[56:59], v[170:173], v[178:181], v[56:59]
	v_mfma_f32_16x16x32_bf16 v[44:47], v[162:165], v[186:189], v[44:47]
	v_mfma_f32_16x16x32_bf16 v[40:43], v[170:173], v[186:189], v[40:43]
	v_mfma_f32_16x16x32_bf16 v[28:31], v[162:165], v[194:197], v[28:31]
	v_mfma_f32_16x16x32_bf16 v[24:27], v[170:173], v[194:197], v[24:27]
	v_mfma_f32_16x16x32_bf16 v[8:11], v[162:165], v[202:205], v[8:11]
	v_mfma_f32_16x16x32_bf16 v[12:15], v[170:173], v[202:205], v[12:15]
	s_setprio 1
	s_barrier
	s_add_i32 s57, 0, 0x18000
	v_add_u32_e32 v138, s57, v139
	s_add_i32 s58, 0, 0x1c000
	ds_read_b128 v[140:143], v138
	ds_read_b128 v[146:149], v138 offset:1024
	ds_read_b128 v[150:153], v138 offset:2048
	ds_read_b128 v[154:157], v138 offset:3072
	v_add_u32_e32 v138, s58, v139
	ds_read_b128 v[158:161], v138
	ds_read_b128 v[162:165], v138 offset:1024
	ds_read_b128 v[166:169], v138 offset:2048
	ds_read_b128 v[170:173], v138 offset:3072
	s_add_u32 s28, s28, 0x80000
	s_addc_u32 s29, s29, 0
	s_mov_b32 m0, s42
	v_lshl_add_u64 v[214:215], s[28:29], 0, v[132:133]
	ds_read_b128 v[174:177], v144 offset:32768
	ds_read_b128 v[178:181], v144 offset:33792
	ds_read_b128 v[182:185], v144 offset:34816
	ds_read_b128 v[186:189], v144 offset:35840
	ds_read_b128 v[190:193], v144 offset:36864
	ds_read_b128 v[194:197], v144 offset:37888
	ds_read_b128 v[198:201], v144 offset:38912
	ds_read_b128 v[202:205], v144 offset:39936
	global_load_lds_dwordx4 v[214:215], off
	v_lshl_add_u64 v[214:215], s[28:29], 0, v[130:131]
	s_mov_b32 m0, s43
	s_nop 0
	global_load_lds_dwordx4 v[214:215], off
	s_waitcnt vmcnt(8)
	s_waitcnt lgkmcnt(0)
	s_barrier
	s_setprio 0
	s_waitcnt lgkmcnt(0)
	v_mfma_f32_16x16x32_bf16 v[116:119], v[140:143], v[174:177], v[116:119]
	v_mfma_f32_16x16x32_bf16 v[112:115], v[150:153], v[174:177], v[112:115]
	v_mfma_f32_16x16x32_bf16 v[100:103], v[140:143], v[182:185], v[100:103]
	v_mfma_f32_16x16x32_bf16 v[96:99], v[150:153], v[182:185], v[96:99]
	v_mfma_f32_16x16x32_bf16 v[84:87], v[140:143], v[190:193], v[84:87]
	v_mfma_f32_16x16x32_bf16 v[80:83], v[150:153], v[190:193], v[80:83]
	v_mfma_f32_16x16x32_bf16 v[68:71], v[140:143], v[198:201], v[68:71]
	v_mfma_f32_16x16x32_bf16 v[60:63], v[150:153], v[198:201], v[60:63]
	v_mfma_f32_16x16x32_bf16 v[116:119], v[146:149], v[178:181], v[116:119]
	v_mfma_f32_16x16x32_bf16 v[112:115], v[154:157], v[178:181], v[112:115]
	v_mfma_f32_16x16x32_bf16 v[100:103], v[146:149], v[186:189], v[100:103]
	v_mfma_f32_16x16x32_bf16 v[96:99], v[154:157], v[186:189], v[96:99]
	v_mfma_f32_16x16x32_bf16 v[84:87], v[146:149], v[194:197], v[84:87]
	v_mfma_f32_16x16x32_bf16 v[80:83], v[154:157], v[194:197], v[80:83]
	v_mfma_f32_16x16x32_bf16 v[68:71], v[146:149], v[202:205], v[68:71]
	v_mfma_f32_16x16x32_bf16 v[60:63], v[154:157], v[202:205], v[60:63]
	s_setprio 1
	s_setprio 0
	v_mfma_f32_16x16x32_bf16 v[124:127], v[158:161], v[174:177], v[124:127]
	v_mfma_f32_16x16x32_bf16 v[120:123], v[166:169], v[174:177], v[120:123]
	v_mfma_f32_16x16x32_bf16 v[108:111], v[158:161], v[182:185], v[108:111]
	v_mfma_f32_16x16x32_bf16 v[104:107], v[166:169], v[182:185], v[104:107]
	v_mfma_f32_16x16x32_bf16 v[92:95], v[158:161], v[190:193], v[92:95]
	v_mfma_f32_16x16x32_bf16 v[88:91], v[166:169], v[190:193], v[88:91]
	v_mfma_f32_16x16x32_bf16 v[76:79], v[158:161], v[198:201], v[76:79]
	v_mfma_f32_16x16x32_bf16 v[72:75], v[166:169], v[198:201], v[72:75]
	v_mfma_f32_16x16x32_bf16 v[124:127], v[162:165], v[178:181], v[124:127]
	v_mfma_f32_16x16x32_bf16 v[120:123], v[170:173], v[178:181], v[120:123]
	v_mfma_f32_16x16x32_bf16 v[108:111], v[162:165], v[186:189], v[108:111]
	v_mfma_f32_16x16x32_bf16 v[104:107], v[170:173], v[186:189], v[104:107]
	v_mfma_f32_16x16x32_bf16 v[92:95], v[162:165], v[194:197], v[92:95]
	v_mfma_f32_16x16x32_bf16 v[88:91], v[170:173], v[194:197], v[88:91]
	v_mfma_f32_16x16x32_bf16 v[76:79], v[162:165], v[202:205], v[76:79]
	v_mfma_f32_16x16x32_bf16 v[72:75], v[170:173], v[202:205], v[72:75]
	s_setprio 1
	s_barrier
	s_add_i32 s28, s57, s10
	v_lshl_add_u64 v[206:207], v[206:207], 0, s[24:25]
	s_mov_b32 m0, s28
	ds_read_b128 v[174:177], v144 offset:49152
	ds_read_b128 v[178:181], v144 offset:50176
	ds_read_b128 v[182:185], v144 offset:51200
	ds_read_b128 v[186:189], v144 offset:52224
	ds_read_b128 v[190:193], v144 offset:53248
	ds_read_b128 v[194:197], v144 offset:54272
	ds_read_b128 v[198:201], v144 offset:55296
	ds_read_b128 v[202:205], v144 offset:56320
	global_load_lds_dwordx4 v[206:207], off
	s_add_i32 m0, s28, 0x2000
	s_add_u32 s8, s8, 0x80080
	v_lshl_add_u64 v[206:207], v[208:209], 0, s[24:25]
	s_addc_u32 s9, s9, 0
	s_add_i32 s28, s58, s10
	global_load_lds_dwordx4 v[206:207], off
	v_lshl_add_u64 v[206:207], s[8:9], 0, v[224:225]
	s_mov_b32 m0, s28
	s_nop 0
	global_load_lds_dwordx4 v[206:207], off
	v_lshl_add_u64 v[206:207], s[8:9], 0, v[128:129]
	s_add_i32 m0, s28, 0x2000
	s_nop 0
	global_load_lds_dwordx4 v[206:207], off
	v_lshl_add_u64 v[206:207], v[210:211], 0, s[24:25]
	s_mov_b32 m0, s46
	s_nop 0
	global_load_lds_dwordx4 v[206:207], off
	v_lshl_add_u64 v[206:207], v[212:213], 0, s[24:25]
	s_mov_b32 m0, s47
	s_nop 0
	global_load_lds_dwordx4 v[206:207], off
	s_waitcnt vmcnt(8)
	s_waitcnt lgkmcnt(0)
	s_barrier
	s_setprio 0
	s_waitcnt lgkmcnt(0)
	v_mfma_f32_16x16x32_bf16 v[52:55], v[140:143], v[174:177], v[52:55]
	v_mfma_f32_16x16x32_bf16 v[48:51], v[150:153], v[174:177], v[48:51]
	v_mfma_f32_16x16x32_bf16 v[36:39], v[140:143], v[182:185], v[36:39]
	v_mfma_f32_16x16x32_bf16 v[32:35], v[150:153], v[182:185], v[32:35]
	v_mfma_f32_16x16x32_bf16 v[20:23], v[140:143], v[190:193], v[20:23]
	v_mfma_f32_16x16x32_bf16 v[16:19], v[150:153], v[190:193], v[16:19]
	v_mfma_f32_16x16x32_bf16 v[4:7], v[140:143], v[198:201], v[4:7]
	v_mfma_f32_16x16x32_bf16 v[0:3], v[150:153], v[198:201], v[0:3]
	v_mfma_f32_16x16x32_bf16 v[52:55], v[146:149], v[178:181], v[52:55]
	v_mfma_f32_16x16x32_bf16 v[48:51], v[154:157], v[178:181], v[48:51]
	v_mfma_f32_16x16x32_bf16 v[36:39], v[146:149], v[186:189], v[36:39]
	v_mfma_f32_16x16x32_bf16 v[32:35], v[154:157], v[186:189], v[32:35]
	v_mfma_f32_16x16x32_bf16 v[20:23], v[146:149], v[194:197], v[20:23]
	v_mfma_f32_16x16x32_bf16 v[16:19], v[154:157], v[194:197], v[16:19]
	v_mfma_f32_16x16x32_bf16 v[4:7], v[146:149], v[202:205], v[4:7]
	v_mfma_f32_16x16x32_bf16 v[0:3], v[154:157], v[202:205], v[0:3]
	s_setprio 1
	s_setprio 0
	v_mfma_f32_16x16x32_bf16 v[64:67], v[158:161], v[174:177], v[64:67]
	v_mfma_f32_16x16x32_bf16 v[56:59], v[166:169], v[174:177], v[56:59]
	v_mfma_f32_16x16x32_bf16 v[44:47], v[158:161], v[182:185], v[44:47]
	v_mfma_f32_16x16x32_bf16 v[40:43], v[166:169], v[182:185], v[40:43]
	v_mfma_f32_16x16x32_bf16 v[28:31], v[158:161], v[190:193], v[28:31]
	v_mfma_f32_16x16x32_bf16 v[24:27], v[166:169], v[190:193], v[24:27]
	v_mfma_f32_16x16x32_bf16 v[8:11], v[158:161], v[198:201], v[8:11]
	v_mfma_f32_16x16x32_bf16 v[12:15], v[166:169], v[198:201], v[12:15]
	v_mfma_f32_16x16x32_bf16 v[64:67], v[162:165], v[178:181], v[64:67]
	v_mfma_f32_16x16x32_bf16 v[56:59], v[170:173], v[178:181], v[56:59]
	v_mfma_f32_16x16x32_bf16 v[44:47], v[162:165], v[186:189], v[44:47]
	v_mfma_f32_16x16x32_bf16 v[40:43], v[170:173], v[186:189], v[40:43]
	v_mfma_f32_16x16x32_bf16 v[28:31], v[162:165], v[194:197], v[28:31]
	v_mfma_f32_16x16x32_bf16 v[24:27], v[170:173], v[194:197], v[24:27]
	v_mfma_f32_16x16x32_bf16 v[8:11], v[162:165], v[202:205], v[8:11]
	v_mfma_f32_16x16x32_bf16 v[12:15], v[170:173], v[202:205], v[12:15]
	s_setprio 1
	s_barrier
	s_add_u32 s12, s12, 0x100
	s_addc_u32 s13, s13, 0
	s_add_u32 s54, s54, 0x100
	s_addc_u32 s55, s55, 0
	s_cmp_ge_i32 s56, s45
	s_mov_b32 s8, s56
	s_cbranch_scc0 .LBB0_1313
	s_mov_b32 s53, 0x5040100
	s_mov_b64 s[56:57], 0x400000
	s_mov_b64 s[58:59], 0x3fffff
	s_mov_b64 s[60:61], 0x20000

.LBB0_1626:
	s_add_i32 s33, s8, 2
	s_add_u32 s9, s12, 0xfff80080
	s_addc_u32 s28, s13, -1
	s_add_i32 s40, 0, 0x10000
	s_cmp_eq_u32 s68, s8
	s_cselect_b32 s29, s3, s28
	s_cselect_b32 s28, s7, s9
	s_cselect_b32 s9, s10, s31
	s_cselect_b32 s8, s21, s30
	s_add_i32 s43, 0, 0x14000
	v_add_u32_e32 v140, s40, v200
	v_add_u32_e32 v156, s43, v200
	ds_read_b128 v[128:131], v140
	ds_read_b128 v[132:135], v140 offset:1024
	ds_read_b128 v[136:139], v140 offset:2048
	ds_read_b128 v[140:143], v140 offset:3072
	ds_read_b128 v[144:147], v156
	ds_read_b128 v[148:151], v156 offset:1024
	ds_read_b128 v[152:155], v156 offset:2048
	ds_read_b128 v[156:159], v156 offset:3072
	v_lshl_add_u64 v[206:207], s[12:13], 0, v[184:185]
	s_add_i32 m0, s56, 0xc000
	ds_read_b128 v[160:163], v201
	ds_read_b128 v[164:167], v201 offset:1024
	ds_read_b128 v[168:171], v201 offset:2048
	ds_read_b128 v[172:175], v201 offset:3072
	ds_read_b128 v[188:191], v201 offset:4096
	ds_read_b128 v[192:195], v201 offset:5120
	ds_read_b128 v[196:199], v201 offset:6144
	ds_read_b128 v[202:205], v201 offset:7168
	global_load_lds_dwordx4 v[206:207], off
	v_lshl_add_u64 v[206:207], s[12:13], 0, v[186:187]
	s_add_i32 m0, s56, 0xe000
	s_nop 0
	global_load_lds_dwordx4 v[206:207], off
	s_waitcnt vmcnt(8)
	s_waitcnt lgkmcnt(0)
	s_barrier
	s_setprio 0
	s_waitcnt lgkmcnt(0)
	v_mfma_f32_16x16x32_bf16 v[112:115], v[128:131], v[160:163], v[112:115]
	v_mfma_f32_16x16x32_bf16 v[116:119], v[136:139], v[160:163], v[116:119]
	v_mfma_f32_16x16x32_bf16 v[100:103], v[128:131], v[168:171], v[100:103]
	v_mfma_f32_16x16x32_bf16 v[96:99], v[136:139], v[168:171], v[96:99]
	v_mfma_f32_16x16x32_bf16 v[84:87], v[128:131], v[188:191], v[84:87]
	v_mfma_f32_16x16x32_bf16 v[80:83], v[136:139], v[188:191], v[80:83]
	v_mfma_f32_16x16x32_bf16 v[68:71], v[128:131], v[196:199], v[68:71]
	v_mfma_f32_16x16x32_bf16 v[64:67], v[136:139], v[196:199], v[64:67]
	v_mfma_f32_16x16x32_bf16 v[112:115], v[132:135], v[164:167], v[112:115]
	v_mfma_f32_16x16x32_bf16 v[116:119], v[140:143], v[164:167], v[116:119]
	v_mfma_f32_16x16x32_bf16 v[100:103], v[132:135], v[172:175], v[100:103]
	v_mfma_f32_16x16x32_bf16 v[96:99], v[140:143], v[172:175], v[96:99]
	v_mfma_f32_16x16x32_bf16 v[84:87], v[132:135], v[192:195], v[84:87]
	v_mfma_f32_16x16x32_bf16 v[80:83], v[140:143], v[192:195], v[80:83]
	v_mfma_f32_16x16x32_bf16 v[68:71], v[132:135], v[202:205], v[68:71]
	v_mfma_f32_16x16x32_bf16 v[64:67], v[140:143], v[202:205], v[64:67]
	s_setprio 1
	s_setprio 0
	v_mfma_f32_16x16x32_bf16 v[120:123], v[144:147], v[160:163], v[120:123]
	v_mfma_f32_16x16x32_bf16 v[124:127], v[152:155], v[160:163], v[124:127]
	v_mfma_f32_16x16x32_bf16 v[108:111], v[144:147], v[168:171], v[108:111]
	v_mfma_f32_16x16x32_bf16 v[104:107], v[152:155], v[168:171], v[104:107]
	v_mfma_f32_16x16x32_bf16 v[92:95], v[144:147], v[188:191], v[92:95]
	v_mfma_f32_16x16x32_bf16 v[88:91], v[152:155], v[188:191], v[88:91]
	v_mfma_f32_16x16x32_bf16 v[76:79], v[144:147], v[196:199], v[76:79]
	v_mfma_f32_16x16x32_bf16 v[72:75], v[152:155], v[196:199], v[72:75]
	v_mfma_f32_16x16x32_bf16 v[120:123], v[148:151], v[164:167], v[120:123]
	v_mfma_f32_16x16x32_bf16 v[124:127], v[156:159], v[164:167], v[124:127]
	v_mfma_f32_16x16x32_bf16 v[108:111], v[148:151], v[172:175], v[108:111]
	v_mfma_f32_16x16x32_bf16 v[104:107], v[156:159], v[172:175], v[104:107]
	v_mfma_f32_16x16x32_bf16 v[92:95], v[148:151], v[192:195], v[92:95]
	v_mfma_f32_16x16x32_bf16 v[88:91], v[156:159], v[192:195], v[88:91]
	v_mfma_f32_16x16x32_bf16 v[76:79], v[148:151], v[202:205], v[76:79]
	v_mfma_f32_16x16x32_bf16 v[72:75], v[156:159], v[202:205], v[72:75]
	s_setprio 1
	s_barrier
	s_add_i32 s40, s40, s54
	v_lshl_add_u64 v[206:207], s[8:9], 0, v[180:181]
	s_mov_b32 m0, s40
	ds_read_b128 v[160:163], v201 offset:16384
	ds_read_b128 v[164:167], v201 offset:17408
	ds_read_b128 v[168:171], v201 offset:18432
	ds_read_b128 v[172:175], v201 offset:19456
	ds_read_b128 v[188:191], v201 offset:20480
	ds_read_b128 v[192:195], v201 offset:21504
	ds_read_b128 v[196:199], v201 offset:22528
	ds_read_b128 v[202:205], v201 offset:23552
	global_load_lds_dwordx4 v[206:207], off
	s_add_i32 m0, s40, 0x2000
	s_add_u32 s40, s8, 0x80000
	v_lshl_add_u64 v[208:209], s[8:9], 0, v[176:177]
	s_addc_u32 s41, s9, 0
	s_add_i32 s43, s43, s54
	global_load_lds_dwordx4 v[208:209], off
	v_lshl_add_u64 v[210:211], s[40:41], 0, v[180:181]
	s_mov_b32 m0, s43
	v_lshl_add_u64 v[212:213], s[28:29], 0, v[178:179]
	global_load_lds_dwordx4 v[210:211], off
	v_lshl_add_u64 v[210:211], s[40:41], 0, v[176:177]
	s_add_i32 m0, s43, 0x2000
	s_nop 0
	global_load_lds_dwordx4 v[210:211], off
	v_lshl_add_u64 v[210:211], s[28:29], 0, v[182:183]
	s_mov_b32 m0, s56
	s_nop 0
	global_load_lds_dwordx4 v[210:211], off
	s_mov_b32 m0, s57
	s_nop 0
	global_load_lds_dwordx4 v[212:213], off
	s_waitcnt vmcnt(8)
	s_waitcnt lgkmcnt(0)
	s_barrier
	s_setprio 0
	s_waitcnt lgkmcnt(0)
	v_mfma_f32_16x16x32_bf16 v[52:55], v[128:131], v[160:163], v[52:55]
	v_mfma_f32_16x16x32_bf16 v[48:51], v[136:139], v[160:163], v[48:51]
	v_mfma_f32_16x16x32_bf16 v[36:39], v[128:131], v[168:171], v[36:39]
	v_mfma_f32_16x16x32_bf16 v[32:35], v[136:139], v[168:171], v[32:35]
	v_mfma_f32_16x16x32_bf16 v[20:23], v[128:131], v[188:191], v[20:23]
	v_mfma_f32_16x16x32_bf16 v[16:19], v[136:139], v[188:191], v[16:19]
	v_mfma_f32_16x16x32_bf16 v[4:7], v[128:131], v[196:199], v[4:7]
	v_mfma_f32_16x16x32_bf16 v[0:3], v[136:139], v[196:199], v[0:3]
	v_mfma_f32_16x16x32_bf16 v[52:55], v[132:135], v[164:167], v[52:55]
	v_mfma_f32_16x16x32_bf16 v[48:51], v[140:143], v[164:167], v[48:51]
	v_mfma_f32_16x16x32_bf16 v[36:39], v[132:135], v[172:175], v[36:39]
	v_mfma_f32_16x16x32_bf16 v[32:35], v[140:143], v[172:175], v[32:35]
	v_mfma_f32_16x16x32_bf16 v[20:23], v[132:135], v[192:195], v[20:23]
	v_mfma_f32_16x16x32_bf16 v[16:19], v[140:143], v[192:195], v[16:19]
	v_mfma_f32_16x16x32_bf16 v[4:7], v[132:135], v[202:205], v[4:7]
	v_mfma_f32_16x16x32_bf16 v[0:3], v[140:143], v[202:205], v[0:3]
	s_setprio 1
	s_setprio 0
	v_mfma_f32_16x16x32_bf16 v[60:63], v[144:147], v[160:163], v[60:63]
	v_mfma_f32_16x16x32_bf16 v[56:59], v[152:155], v[160:163], v[56:59]
	v_mfma_f32_16x16x32_bf16 v[44:47], v[144:147], v[168:171], v[44:47]
	v_mfma_f32_16x16x32_bf16 v[40:43], v[152:155], v[168:171], v[40:43]
	v_mfma_f32_16x16x32_bf16 v[28:31], v[144:147], v[188:191], v[28:31]
	v_mfma_f32_16x16x32_bf16 v[24:27], v[152:155], v[188:191], v[24:27]
	v_mfma_f32_16x16x32_bf16 v[8:11], v[144:147], v[196:199], v[8:11]
	v_mfma_f32_16x16x32_bf16 v[12:15], v[152:155], v[196:199], v[12:15]
	v_mfma_f32_16x16x32_bf16 v[60:63], v[148:151], v[164:167], v[60:63]
	v_mfma_f32_16x16x32_bf16 v[56:59], v[156:159], v[164:167], v[56:59]
	v_mfma_f32_16x16x32_bf16 v[44:47], v[148:151], v[172:175], v[44:47]
	v_mfma_f32_16x16x32_bf16 v[40:43], v[156:159], v[172:175], v[40:43]
	v_mfma_f32_16x16x32_bf16 v[28:31], v[148:151], v[192:195], v[28:31]
	v_mfma_f32_16x16x32_bf16 v[24:27], v[156:159], v[192:195], v[24:27]
	v_mfma_f32_16x16x32_bf16 v[8:11], v[148:151], v[202:205], v[8:11]
	v_mfma_f32_16x16x32_bf16 v[12:15], v[156:159], v[202:205], v[12:15]
	s_setprio 1
	s_barrier
	s_add_i32 s40, 0, 0x18000
	s_add_i32 s41, 0, 0x1c000
	v_add_u32_e32 v140, s40, v200
	v_add_u32_e32 v156, s41, v200
	ds_read_b128 v[128:131], v140
	ds_read_b128 v[132:135], v140 offset:1024
	ds_read_b128 v[136:139], v140 offset:2048
	ds_read_b128 v[140:143], v140 offset:3072
	ds_read_b128 v[144:147], v156
	ds_read_b128 v[148:151], v156 offset:1024
	ds_read_b128 v[152:155], v156 offset:2048
	ds_read_b128 v[156:159], v156 offset:3072
	s_add_u32 s28, s28, 0x80000
	s_addc_u32 s29, s29, 0
	s_mov_b32 m0, s58
	v_lshl_add_u64 v[214:215], s[28:29], 0, v[182:183]
	ds_read_b128 v[160:163], v201 offset:32768
	ds_read_b128 v[164:167], v201 offset:33792
	ds_read_b128 v[168:171], v201 offset:34816
	ds_read_b128 v[172:175], v201 offset:35840
	ds_read_b128 v[188:191], v201 offset:36864
	ds_read_b128 v[192:195], v201 offset:37888
	ds_read_b128 v[196:199], v201 offset:38912
	ds_read_b128 v[202:205], v201 offset:39936
	global_load_lds_dwordx4 v[214:215], off
	v_lshl_add_u64 v[214:215], s[28:29], 0, v[178:179]
	s_mov_b32 m0, s59
	s_nop 0
	global_load_lds_dwordx4 v[214:215], off
	s_waitcnt vmcnt(8)
	s_waitcnt lgkmcnt(0)
	s_barrier
	s_setprio 0
	s_waitcnt lgkmcnt(0)
	v_mfma_f32_16x16x32_bf16 v[112:115], v[128:131], v[160:163], v[112:115]
	v_mfma_f32_16x16x32_bf16 v[116:119], v[136:139], v[160:163], v[116:119]
	v_mfma_f32_16x16x32_bf16 v[100:103], v[128:131], v[168:171], v[100:103]
	v_mfma_f32_16x16x32_bf16 v[96:99], v[136:139], v[168:171], v[96:99]
	v_mfma_f32_16x16x32_bf16 v[84:87], v[128:131], v[188:191], v[84:87]
	v_mfma_f32_16x16x32_bf16 v[80:83], v[136:139], v[188:191], v[80:83]
	v_mfma_f32_16x16x32_bf16 v[68:71], v[128:131], v[196:199], v[68:71]
	v_mfma_f32_16x16x32_bf16 v[64:67], v[136:139], v[196:199], v[64:67]
	v_mfma_f32_16x16x32_bf16 v[112:115], v[132:135], v[164:167], v[112:115]
	v_mfma_f32_16x16x32_bf16 v[116:119], v[140:143], v[164:167], v[116:119]
	v_mfma_f32_16x16x32_bf16 v[100:103], v[132:135], v[172:175], v[100:103]
	v_mfma_f32_16x16x32_bf16 v[96:99], v[140:143], v[172:175], v[96:99]
	v_mfma_f32_16x16x32_bf16 v[84:87], v[132:135], v[192:195], v[84:87]
	v_mfma_f32_16x16x32_bf16 v[80:83], v[140:143], v[192:195], v[80:83]
	v_mfma_f32_16x16x32_bf16 v[68:71], v[132:135], v[202:205], v[68:71]
	v_mfma_f32_16x16x32_bf16 v[64:67], v[140:143], v[202:205], v[64:67]
	s_setprio 1
	s_setprio 0
	v_mfma_f32_16x16x32_bf16 v[120:123], v[144:147], v[160:163], v[120:123]
	v_mfma_f32_16x16x32_bf16 v[124:127], v[152:155], v[160:163], v[124:127]
	v_mfma_f32_16x16x32_bf16 v[108:111], v[144:147], v[168:171], v[108:111]
	v_mfma_f32_16x16x32_bf16 v[104:107], v[152:155], v[168:171], v[104:107]
	v_mfma_f32_16x16x32_bf16 v[92:95], v[144:147], v[188:191], v[92:95]
	v_mfma_f32_16x16x32_bf16 v[88:91], v[152:155], v[188:191], v[88:91]
	v_mfma_f32_16x16x32_bf16 v[76:79], v[144:147], v[196:199], v[76:79]
	v_mfma_f32_16x16x32_bf16 v[72:75], v[152:155], v[196:199], v[72:75]
	v_mfma_f32_16x16x32_bf16 v[120:123], v[148:151], v[164:167], v[120:123]
	v_mfma_f32_16x16x32_bf16 v[124:127], v[156:159], v[164:167], v[124:127]
	v_mfma_f32_16x16x32_bf16 v[108:111], v[148:151], v[172:175], v[108:111]
	v_mfma_f32_16x16x32_bf16 v[104:107], v[156:159], v[172:175], v[104:107]
	v_mfma_f32_16x16x32_bf16 v[92:95], v[148:151], v[192:195], v[92:95]
	v_mfma_f32_16x16x32_bf16 v[88:91], v[156:159], v[192:195], v[88:91]
	v_mfma_f32_16x16x32_bf16 v[76:79], v[148:151], v[202:205], v[76:79]
	v_mfma_f32_16x16x32_bf16 v[72:75], v[156:159], v[202:205], v[72:75]
	s_setprio 1
	s_barrier
	s_add_i32 s28, s40, s54
	v_lshl_add_u64 v[206:207], v[206:207], 0, s[24:25]
	s_mov_b32 m0, s28
	ds_read_b128 v[160:163], v201 offset:49152
	ds_read_b128 v[164:167], v201 offset:50176
	ds_read_b128 v[168:171], v201 offset:51200
	ds_read_b128 v[172:175], v201 offset:52224
	ds_read_b128 v[188:191], v201 offset:53248
	ds_read_b128 v[192:195], v201 offset:54272
	ds_read_b128 v[196:199], v201 offset:55296
	ds_read_b128 v[202:205], v201 offset:56320
	global_load_lds_dwordx4 v[206:207], off
	s_add_i32 m0, s28, 0x2000
	s_add_u32 s8, s8, 0x80080
	v_lshl_add_u64 v[206:207], v[208:209], 0, s[24:25]
	s_addc_u32 s9, s9, 0
	s_add_i32 s28, s41, s54
	global_load_lds_dwordx4 v[206:207], off
	v_lshl_add_u64 v[206:207], s[8:9], 0, v[180:181]
	s_mov_b32 m0, s28
	s_nop 0
	global_load_lds_dwordx4 v[206:207], off
	v_lshl_add_u64 v[206:207], s[8:9], 0, v[176:177]
	s_add_i32 m0, s28, 0x2000
	s_nop 0
	global_load_lds_dwordx4 v[206:207], off
	v_lshl_add_u64 v[206:207], v[210:211], 0, s[24:25]
	s_mov_b32 m0, s66
	s_nop 0
	global_load_lds_dwordx4 v[206:207], off
	v_lshl_add_u64 v[206:207], v[212:213], 0, s[24:25]
	s_mov_b32 m0, s67
	s_nop 0
	global_load_lds_dwordx4 v[206:207], off
	s_waitcnt vmcnt(8)
	s_waitcnt lgkmcnt(0)
	s_barrier
	s_setprio 0
	s_waitcnt lgkmcnt(0)
	v_mfma_f32_16x16x32_bf16 v[52:55], v[128:131], v[160:163], v[52:55]
	v_mfma_f32_16x16x32_bf16 v[48:51], v[136:139], v[160:163], v[48:51]
	v_mfma_f32_16x16x32_bf16 v[36:39], v[128:131], v[168:171], v[36:39]
	v_mfma_f32_16x16x32_bf16 v[32:35], v[136:139], v[168:171], v[32:35]
	v_mfma_f32_16x16x32_bf16 v[20:23], v[128:131], v[188:191], v[20:23]
	v_mfma_f32_16x16x32_bf16 v[16:19], v[136:139], v[188:191], v[16:19]
	v_mfma_f32_16x16x32_bf16 v[4:7], v[128:131], v[196:199], v[4:7]
	v_mfma_f32_16x16x32_bf16 v[0:3], v[136:139], v[196:199], v[0:3]
	v_mfma_f32_16x16x32_bf16 v[52:55], v[132:135], v[164:167], v[52:55]
	v_mfma_f32_16x16x32_bf16 v[48:51], v[140:143], v[164:167], v[48:51]
	v_mfma_f32_16x16x32_bf16 v[36:39], v[132:135], v[172:175], v[36:39]
	v_mfma_f32_16x16x32_bf16 v[32:35], v[140:143], v[172:175], v[32:35]
	v_mfma_f32_16x16x32_bf16 v[20:23], v[132:135], v[192:195], v[20:23]
	v_mfma_f32_16x16x32_bf16 v[16:19], v[140:143], v[192:195], v[16:19]
	v_mfma_f32_16x16x32_bf16 v[4:7], v[132:135], v[202:205], v[4:7]
	v_mfma_f32_16x16x32_bf16 v[0:3], v[140:143], v[202:205], v[0:3]
	s_setprio 1
	s_setprio 0
	v_mfma_f32_16x16x32_bf16 v[60:63], v[144:147], v[160:163], v[60:63]
	v_mfma_f32_16x16x32_bf16 v[56:59], v[152:155], v[160:163], v[56:59]
	v_mfma_f32_16x16x32_bf16 v[44:47], v[144:147], v[168:171], v[44:47]
	v_mfma_f32_16x16x32_bf16 v[40:43], v[152:155], v[168:171], v[40:43]
	v_mfma_f32_16x16x32_bf16 v[28:31], v[144:147], v[188:191], v[28:31]
	v_mfma_f32_16x16x32_bf16 v[24:27], v[152:155], v[188:191], v[24:27]
	v_mfma_f32_16x16x32_bf16 v[8:11], v[144:147], v[196:199], v[8:11]
	v_mfma_f32_16x16x32_bf16 v[12:15], v[152:155], v[196:199], v[12:15]
	v_mfma_f32_16x16x32_bf16 v[60:63], v[148:151], v[164:167], v[60:63]
	v_mfma_f32_16x16x32_bf16 v[56:59], v[156:159], v[164:167], v[56:59]
	v_mfma_f32_16x16x32_bf16 v[44:47], v[148:151], v[172:175], v[44:47]
	v_mfma_f32_16x16x32_bf16 v[40:43], v[156:159], v[172:175], v[40:43]
	v_mfma_f32_16x16x32_bf16 v[28:31], v[148:151], v[192:195], v[28:31]
	v_mfma_f32_16x16x32_bf16 v[24:27], v[156:159], v[192:195], v[24:27]
	v_mfma_f32_16x16x32_bf16 v[8:11], v[148:151], v[202:205], v[8:11]
	v_mfma_f32_16x16x32_bf16 v[12:15], v[156:159], v[202:205], v[12:15]
	s_setprio 1
	s_barrier
	s_add_u32 s12, s12, 0x100
	s_addc_u32 s13, s13, 0
	s_add_u32 s30, s30, 0x100
	s_addc_u32 s31, s31, 0
	s_cmp_ge_i32 s33, s65
	s_mov_b32 s8, s33
	s_cbranch_scc0 .LBB0_1626

.LBB0_1667:
	s_add_i32 s56, s8, 2
	s_add_u32 s9, s12, 0xfff80080
	s_addc_u32 s28, s13, -1
	s_add_i32 s57, 0, 0x10000
	s_cmp_eq_u32 s48, s8
	s_cselect_b32 s29, s27, s28
	s_cselect_b32 s28, s35, s9
	s_cselect_b32 s9, s52, s55
	s_cselect_b32 s8, s53, s54
	s_add_i32 s60, 0, 0x14000
	v_add_u32_e32 v152, s57, v138
	v_add_u32_e32 v168, s60, v138
	ds_read_b128 v[140:143], v152
	ds_read_b128 v[144:147], v152 offset:1024
	ds_read_b128 v[148:151], v152 offset:2048
	ds_read_b128 v[152:155], v152 offset:3072
	ds_read_b128 v[156:159], v168
	ds_read_b128 v[160:163], v168 offset:1024
	ds_read_b128 v[164:167], v168 offset:2048
	ds_read_b128 v[168:171], v168 offset:3072
	v_lshl_add_u64 v[204:205], s[12:13], 0, v[134:135]
	s_add_i32 m0, s31, 0xc000
	ds_read_b128 v[172:175], v139
	ds_read_b128 v[176:179], v139 offset:1024
	ds_read_b128 v[180:183], v139 offset:2048
	ds_read_b128 v[184:187], v139 offset:3072
	ds_read_b128 v[188:191], v139 offset:4096
	ds_read_b128 v[192:195], v139 offset:5120
	ds_read_b128 v[196:199], v139 offset:6144
	ds_read_b128 v[200:203], v139 offset:7168
	global_load_lds_dwordx4 v[204:205], off
	v_lshl_add_u64 v[204:205], s[12:13], 0, v[136:137]
	s_add_i32 m0, s31, 0xe000
	s_nop 0
	global_load_lds_dwordx4 v[204:205], off
	s_waitcnt vmcnt(8)
	s_waitcnt lgkmcnt(0)
	s_barrier
	s_setprio 0
	s_waitcnt lgkmcnt(0)
	v_mfma_f32_16x16x32_bf16 v[112:115], v[140:143], v[172:175], v[112:115]
	v_mfma_f32_16x16x32_bf16 v[116:119], v[148:151], v[172:175], v[116:119]
	v_mfma_f32_16x16x32_bf16 v[96:99], v[140:143], v[180:183], v[96:99]
	v_mfma_f32_16x16x32_bf16 v[100:103], v[148:151], v[180:183], v[100:103]
	v_mfma_f32_16x16x32_bf16 v[80:83], v[140:143], v[188:191], v[80:83]
	v_mfma_f32_16x16x32_bf16 v[84:87], v[148:151], v[188:191], v[84:87]
	v_mfma_f32_16x16x32_bf16 v[48:51], v[140:143], v[196:199], v[48:51]
	v_mfma_f32_16x16x32_bf16 v[52:55], v[148:151], v[196:199], v[52:55]
	v_mfma_f32_16x16x32_bf16 v[112:115], v[144:147], v[176:179], v[112:115]
	v_mfma_f32_16x16x32_bf16 v[116:119], v[152:155], v[176:179], v[116:119]
	v_mfma_f32_16x16x32_bf16 v[96:99], v[144:147], v[184:187], v[96:99]
	v_mfma_f32_16x16x32_bf16 v[100:103], v[152:155], v[184:187], v[100:103]
	v_mfma_f32_16x16x32_bf16 v[80:83], v[144:147], v[192:195], v[80:83]
	v_mfma_f32_16x16x32_bf16 v[84:87], v[152:155], v[192:195], v[84:87]
	v_mfma_f32_16x16x32_bf16 v[48:51], v[144:147], v[200:203], v[48:51]
	v_mfma_f32_16x16x32_bf16 v[52:55], v[152:155], v[200:203], v[52:55]
	s_setprio 1
	s_setprio 0
	v_mfma_f32_16x16x32_bf16 v[120:123], v[156:159], v[172:175], v[120:123]
	v_mfma_f32_16x16x32_bf16 v[124:127], v[164:167], v[172:175], v[124:127]
	v_mfma_f32_16x16x32_bf16 v[104:107], v[156:159], v[180:183], v[104:107]
	v_mfma_f32_16x16x32_bf16 v[108:111], v[164:167], v[180:183], v[108:111]
	v_mfma_f32_16x16x32_bf16 v[88:91], v[156:159], v[188:191], v[88:91]
	v_mfma_f32_16x16x32_bf16 v[92:95], v[164:167], v[188:191], v[92:95]
	v_mfma_f32_16x16x32_bf16 v[64:67], v[156:159], v[196:199], v[64:67]
	v_mfma_f32_16x16x32_bf16 v[68:71], v[164:167], v[196:199], v[68:71]
	v_mfma_f32_16x16x32_bf16 v[120:123], v[160:163], v[176:179], v[120:123]
	v_mfma_f32_16x16x32_bf16 v[124:127], v[168:171], v[176:179], v[124:127]
	v_mfma_f32_16x16x32_bf16 v[104:107], v[160:163], v[184:187], v[104:107]
	v_mfma_f32_16x16x32_bf16 v[108:111], v[168:171], v[184:187], v[108:111]
	v_mfma_f32_16x16x32_bf16 v[88:91], v[160:163], v[192:195], v[88:91]
	v_mfma_f32_16x16x32_bf16 v[92:95], v[168:171], v[192:195], v[92:95]
	v_mfma_f32_16x16x32_bf16 v[64:67], v[160:163], v[200:203], v[64:67]
	v_mfma_f32_16x16x32_bf16 v[68:71], v[168:171], v[200:203], v[68:71]
	s_setprio 1
	s_barrier
	s_add_i32 s57, s57, s10
	v_lshl_add_u64 v[204:205], s[8:9], 0, v[224:225]
	s_mov_b32 m0, s57
	ds_read_b128 v[172:175], v139 offset:16384
	ds_read_b128 v[176:179], v139 offset:17408
	ds_read_b128 v[180:183], v139 offset:18432
	ds_read_b128 v[184:187], v139 offset:19456
	ds_read_b128 v[188:191], v139 offset:20480
	ds_read_b128 v[192:195], v139 offset:21504
	ds_read_b128 v[196:199], v139 offset:22528
	ds_read_b128 v[200:203], v139 offset:23552
	global_load_lds_dwordx4 v[204:205], off
	s_add_i32 m0, s57, 0x2000
	s_add_u32 s58, s8, 0x80000
	v_lshl_add_u64 v[206:207], s[8:9], 0, v[128:129]
	s_addc_u32 s59, s9, 0
	s_add_i32 s57, s60, s10
	global_load_lds_dwordx4 v[206:207], off
	v_lshl_add_u64 v[208:209], s[58:59], 0, v[224:225]
	s_mov_b32 m0, s57
	v_lshl_add_u64 v[210:211], s[28:29], 0, v[130:131]
	global_load_lds_dwordx4 v[208:209], off
	v_lshl_add_u64 v[208:209], s[58:59], 0, v[128:129]
	s_add_i32 m0, s57, 0x2000
	s_nop 0
	global_load_lds_dwordx4 v[208:209], off
	v_lshl_add_u64 v[208:209], s[28:29], 0, v[132:133]
	s_mov_b32 m0, s31
	s_nop 0
	global_load_lds_dwordx4 v[208:209], off
	s_mov_b32 m0, s33
	s_nop 0
	global_load_lds_dwordx4 v[210:211], off
	s_waitcnt vmcnt(8)
	s_waitcnt lgkmcnt(0)
	s_barrier
	s_setprio 0
	s_waitcnt lgkmcnt(0)
	v_mfma_f32_16x16x32_bf16 v[56:59], v[140:143], v[172:175], v[56:59]
	v_mfma_f32_16x16x32_bf16 v[60:63], v[148:151], v[172:175], v[60:63]
	v_mfma_f32_16x16x32_bf16 v[32:35], v[140:143], v[180:183], v[32:35]
	v_mfma_f32_16x16x32_bf16 v[36:39], v[148:151], v[180:183], v[36:39]
	v_mfma_f32_16x16x32_bf16 v[16:19], v[140:143], v[188:191], v[16:19]
	v_mfma_f32_16x16x32_bf16 v[20:23], v[148:151], v[188:191], v[20:23]
	v_mfma_f32_16x16x32_bf16 v[0:3], v[140:143], v[196:199], v[0:3]
	v_mfma_f32_16x16x32_bf16 v[4:7], v[148:151], v[196:199], v[4:7]
	v_mfma_f32_16x16x32_bf16 v[56:59], v[144:147], v[176:179], v[56:59]
	v_mfma_f32_16x16x32_bf16 v[60:63], v[152:155], v[176:179], v[60:63]
	v_mfma_f32_16x16x32_bf16 v[32:35], v[144:147], v[184:187], v[32:35]
	v_mfma_f32_16x16x32_bf16 v[36:39], v[152:155], v[184:187], v[36:39]
	v_mfma_f32_16x16x32_bf16 v[16:19], v[144:147], v[192:195], v[16:19]
	v_mfma_f32_16x16x32_bf16 v[20:23], v[152:155], v[192:195], v[20:23]
	v_mfma_f32_16x16x32_bf16 v[0:3], v[144:147], v[200:203], v[0:3]
	v_mfma_f32_16x16x32_bf16 v[4:7], v[152:155], v[200:203], v[4:7]
	s_setprio 1
	s_setprio 0
	v_mfma_f32_16x16x32_bf16 v[72:75], v[156:159], v[172:175], v[72:75]
	v_mfma_f32_16x16x32_bf16 v[76:79], v[164:167], v[172:175], v[76:79]
	v_mfma_f32_16x16x32_bf16 v[40:43], v[156:159], v[180:183], v[40:43]
	v_mfma_f32_16x16x32_bf16 v[44:47], v[164:167], v[180:183], v[44:47]
	v_mfma_f32_16x16x32_bf16 v[24:27], v[156:159], v[188:191], v[24:27]
	v_mfma_f32_16x16x32_bf16 v[28:31], v[164:167], v[188:191], v[28:31]
	v_mfma_f32_16x16x32_bf16 v[8:11], v[156:159], v[196:199], v[8:11]
	v_mfma_f32_16x16x32_bf16 v[12:15], v[164:167], v[196:199], v[12:15]
	v_mfma_f32_16x16x32_bf16 v[72:75], v[160:163], v[176:179], v[72:75]
	v_mfma_f32_16x16x32_bf16 v[76:79], v[168:171], v[176:179], v[76:79]
	v_mfma_f32_16x16x32_bf16 v[40:43], v[160:163], v[184:187], v[40:43]
	v_mfma_f32_16x16x32_bf16 v[44:47], v[168:171], v[184:187], v[44:47]
	v_mfma_f32_16x16x32_bf16 v[24:27], v[160:163], v[192:195], v[24:27]
	v_mfma_f32_16x16x32_bf16 v[28:31], v[168:171], v[192:195], v[28:31]
	v_mfma_f32_16x16x32_bf16 v[8:11], v[160:163], v[200:203], v[8:11]
	v_mfma_f32_16x16x32_bf16 v[12:15], v[168:171], v[200:203], v[12:15]
	s_setprio 1
	s_barrier
	s_add_i32 s57, 0, 0x18000
	s_add_i32 s58, 0, 0x1c000
	v_add_u32_e32 v152, s57, v138
	v_add_u32_e32 v168, s58, v138
	ds_read_b128 v[140:143], v152
	ds_read_b128 v[144:147], v152 offset:1024
	ds_read_b128 v[148:151], v152 offset:2048
	ds_read_b128 v[152:155], v152 offset:3072
	ds_read_b128 v[156:159], v168
	ds_read_b128 v[160:163], v168 offset:1024
	ds_read_b128 v[164:167], v168 offset:2048
	ds_read_b128 v[168:171], v168 offset:3072
	s_add_u32 s28, s28, 0x80000
	s_addc_u32 s29, s29, 0
	s_mov_b32 m0, s42
	v_lshl_add_u64 v[212:213], s[28:29], 0, v[132:133]
	ds_read_b128 v[172:175], v139 offset:32768
	ds_read_b128 v[176:179], v139 offset:33792
	ds_read_b128 v[180:183], v139 offset:34816
	ds_read_b128 v[184:187], v139 offset:35840
	ds_read_b128 v[188:191], v139 offset:36864
	ds_read_b128 v[192:195], v139 offset:37888
	ds_read_b128 v[196:199], v139 offset:38912
	ds_read_b128 v[200:203], v139 offset:39936
	global_load_lds_dwordx4 v[212:213], off
	v_lshl_add_u64 v[212:213], s[28:29], 0, v[130:131]
	s_mov_b32 m0, s43
	s_nop 0
	global_load_lds_dwordx4 v[212:213], off
	s_waitcnt vmcnt(8)
	s_waitcnt lgkmcnt(0)
	s_barrier
	s_setprio 0
	s_waitcnt lgkmcnt(0)
	v_mfma_f32_16x16x32_bf16 v[112:115], v[140:143], v[172:175], v[112:115]
	v_mfma_f32_16x16x32_bf16 v[116:119], v[148:151], v[172:175], v[116:119]
	v_mfma_f32_16x16x32_bf16 v[96:99], v[140:143], v[180:183], v[96:99]
	v_mfma_f32_16x16x32_bf16 v[100:103], v[148:151], v[180:183], v[100:103]
	v_mfma_f32_16x16x32_bf16 v[80:83], v[140:143], v[188:191], v[80:83]
	v_mfma_f32_16x16x32_bf16 v[84:87], v[148:151], v[188:191], v[84:87]
	v_mfma_f32_16x16x32_bf16 v[48:51], v[140:143], v[196:199], v[48:51]
	v_mfma_f32_16x16x32_bf16 v[52:55], v[148:151], v[196:199], v[52:55]
	v_mfma_f32_16x16x32_bf16 v[112:115], v[144:147], v[176:179], v[112:115]
	v_mfma_f32_16x16x32_bf16 v[116:119], v[152:155], v[176:179], v[116:119]
	v_mfma_f32_16x16x32_bf16 v[96:99], v[144:147], v[184:187], v[96:99]
	v_mfma_f32_16x16x32_bf16 v[100:103], v[152:155], v[184:187], v[100:103]
	v_mfma_f32_16x16x32_bf16 v[80:83], v[144:147], v[192:195], v[80:83]
	v_mfma_f32_16x16x32_bf16 v[84:87], v[152:155], v[192:195], v[84:87]
	v_mfma_f32_16x16x32_bf16 v[48:51], v[144:147], v[200:203], v[48:51]
	v_mfma_f32_16x16x32_bf16 v[52:55], v[152:155], v[200:203], v[52:55]
	s_setprio 1
	s_setprio 0
	v_mfma_f32_16x16x32_bf16 v[120:123], v[156:159], v[172:175], v[120:123]
	v_mfma_f32_16x16x32_bf16 v[124:127], v[164:167], v[172:175], v[124:127]
	v_mfma_f32_16x16x32_bf16 v[104:107], v[156:159], v[180:183], v[104:107]
	v_mfma_f32_16x16x32_bf16 v[108:111], v[164:167], v[180:183], v[108:111]
	v_mfma_f32_16x16x32_bf16 v[88:91], v[156:159], v[188:191], v[88:91]
	v_mfma_f32_16x16x32_bf16 v[92:95], v[164:167], v[188:191], v[92:95]
	v_mfma_f32_16x16x32_bf16 v[64:67], v[156:159], v[196:199], v[64:67]
	v_mfma_f32_16x16x32_bf16 v[68:71], v[164:167], v[196:199], v[68:71]
	v_mfma_f32_16x16x32_bf16 v[120:123], v[160:163], v[176:179], v[120:123]
	v_mfma_f32_16x16x32_bf16 v[124:127], v[168:171], v[176:179], v[124:127]
	v_mfma_f32_16x16x32_bf16 v[104:107], v[160:163], v[184:187], v[104:107]
	v_mfma_f32_16x16x32_bf16 v[108:111], v[168:171], v[184:187], v[108:111]
	v_mfma_f32_16x16x32_bf16 v[88:91], v[160:163], v[192:195], v[88:91]
	v_mfma_f32_16x16x32_bf16 v[92:95], v[168:171], v[192:195], v[92:95]
	v_mfma_f32_16x16x32_bf16 v[64:67], v[160:163], v[200:203], v[64:67]
	v_mfma_f32_16x16x32_bf16 v[68:71], v[168:171], v[200:203], v[68:71]
	s_setprio 1
	s_barrier
	s_add_i32 s28, s57, s10
	v_lshl_add_u64 v[204:205], v[204:205], 0, s[24:25]
	s_mov_b32 m0, s28
	ds_read_b128 v[172:175], v139 offset:49152
	ds_read_b128 v[176:179], v139 offset:50176
	ds_read_b128 v[180:183], v139 offset:51200
	ds_read_b128 v[184:187], v139 offset:52224
	ds_read_b128 v[188:191], v139 offset:53248
	ds_read_b128 v[192:195], v139 offset:54272
	ds_read_b128 v[196:199], v139 offset:55296
	ds_read_b128 v[200:203], v139 offset:56320
	global_load_lds_dwordx4 v[204:205], off
	s_add_i32 m0, s28, 0x2000
	s_add_u32 s8, s8, 0x80080
	v_lshl_add_u64 v[204:205], v[206:207], 0, s[24:25]
	s_addc_u32 s9, s9, 0
	s_add_i32 s28, s58, s10
	global_load_lds_dwordx4 v[204:205], off
	v_lshl_add_u64 v[204:205], s[8:9], 0, v[224:225]
	s_mov_b32 m0, s28
	s_nop 0
	global_load_lds_dwordx4 v[204:205], off
	v_lshl_add_u64 v[204:205], s[8:9], 0, v[128:129]
	s_add_i32 m0, s28, 0x2000
	s_nop 0
	global_load_lds_dwordx4 v[204:205], off
	v_lshl_add_u64 v[204:205], v[208:209], 0, s[24:25]
	s_mov_b32 m0, s46
	s_nop 0
	global_load_lds_dwordx4 v[204:205], off
	v_lshl_add_u64 v[204:205], v[210:211], 0, s[24:25]
	s_mov_b32 m0, s47
	s_nop 0
	global_load_lds_dwordx4 v[204:205], off
	s_waitcnt vmcnt(8)
	s_waitcnt lgkmcnt(0)
	s_barrier
	s_setprio 0
	s_waitcnt lgkmcnt(0)
	v_mfma_f32_16x16x32_bf16 v[56:59], v[140:143], v[172:175], v[56:59]
	v_mfma_f32_16x16x32_bf16 v[60:63], v[148:151], v[172:175], v[60:63]
	v_mfma_f32_16x16x32_bf16 v[32:35], v[140:143], v[180:183], v[32:35]
	v_mfma_f32_16x16x32_bf16 v[36:39], v[148:151], v[180:183], v[36:39]
	v_mfma_f32_16x16x32_bf16 v[16:19], v[140:143], v[188:191], v[16:19]
	v_mfma_f32_16x16x32_bf16 v[20:23], v[148:151], v[188:191], v[20:23]
	v_mfma_f32_16x16x32_bf16 v[0:3], v[140:143], v[196:199], v[0:3]
	v_mfma_f32_16x16x32_bf16 v[4:7], v[148:151], v[196:199], v[4:7]
	v_mfma_f32_16x16x32_bf16 v[56:59], v[144:147], v[176:179], v[56:59]
	v_mfma_f32_16x16x32_bf16 v[60:63], v[152:155], v[176:179], v[60:63]
	v_mfma_f32_16x16x32_bf16 v[32:35], v[144:147], v[184:187], v[32:35]
	v_mfma_f32_16x16x32_bf16 v[36:39], v[152:155], v[184:187], v[36:39]
	v_mfma_f32_16x16x32_bf16 v[16:19], v[144:147], v[192:195], v[16:19]
	v_mfma_f32_16x16x32_bf16 v[20:23], v[152:155], v[192:195], v[20:23]
	v_mfma_f32_16x16x32_bf16 v[0:3], v[144:147], v[200:203], v[0:3]
	v_mfma_f32_16x16x32_bf16 v[4:7], v[152:155], v[200:203], v[4:7]
	s_setprio 1
	s_setprio 0
	v_mfma_f32_16x16x32_bf16 v[72:75], v[156:159], v[172:175], v[72:75]
	v_mfma_f32_16x16x32_bf16 v[76:79], v[164:167], v[172:175], v[76:79]
	v_mfma_f32_16x16x32_bf16 v[40:43], v[156:159], v[180:183], v[40:43]
	v_mfma_f32_16x16x32_bf16 v[44:47], v[164:167], v[180:183], v[44:47]
	v_mfma_f32_16x16x32_bf16 v[24:27], v[156:159], v[188:191], v[24:27]
	v_mfma_f32_16x16x32_bf16 v[28:31], v[164:167], v[188:191], v[28:31]
	v_mfma_f32_16x16x32_bf16 v[8:11], v[156:159], v[196:199], v[8:11]
	v_mfma_f32_16x16x32_bf16 v[12:15], v[164:167], v[196:199], v[12:15]
	v_mfma_f32_16x16x32_bf16 v[72:75], v[160:163], v[176:179], v[72:75]
	v_mfma_f32_16x16x32_bf16 v[76:79], v[168:171], v[176:179], v[76:79]
	v_mfma_f32_16x16x32_bf16 v[40:43], v[160:163], v[184:187], v[40:43]
	v_mfma_f32_16x16x32_bf16 v[44:47], v[168:171], v[184:187], v[44:47]
	v_mfma_f32_16x16x32_bf16 v[24:27], v[160:163], v[192:195], v[24:27]
	v_mfma_f32_16x16x32_bf16 v[28:31], v[168:171], v[192:195], v[28:31]
	v_mfma_f32_16x16x32_bf16 v[8:11], v[160:163], v[200:203], v[8:11]
	v_mfma_f32_16x16x32_bf16 v[12:15], v[168:171], v[200:203], v[12:15]
	s_setprio 1
	s_barrier
	s_add_u32 s12, s12, 0x100
	s_addc_u32 s13, s13, 0
	s_add_u32 s54, s54, 0x100
	s_addc_u32 s55, s55, 0
	s_cmp_ge_i32 s56, s45
	s_mov_b32 s8, s56
	s_cbranch_scc0 .LBB0_1667
	s_mov_b32 s53, 0x5040100
	s_mov_b64 s[56:57], 0x400000
	s_mov_b64 s[58:59], 0x3fffff
	s_mov_b64 s[60:61], 0x20000

.LBB0_1892:
	s_add_i32 s33, s8, 2
	s_add_u32 s35, s12, 0x80
	s_addc_u32 s9, s13, 0
	s_add_i32 s37, 0, 0x10000
	s_cmp_eq_u32 s61, s8
	s_cselect_b32 s9, s3, s9
	s_cselect_b32 s8, s7, s35
	s_cselect_b32 s65, s28, s31
	s_cselect_b32 s64, s29, s30
	s_add_i32 s35, 0, 0x14000
	v_add_u32_e32 v140, s37, v214
	v_add_u32_e32 v156, s35, v214
	ds_read_b128 v[128:131], v140
	ds_read_b128 v[132:135], v140 offset:1024
	ds_read_b128 v[136:139], v140 offset:2048
	ds_read_b128 v[140:143], v140 offset:3072
	ds_read_b128 v[144:147], v156
	ds_read_b128 v[148:151], v156 offset:1024
	ds_read_b128 v[152:155], v156 offset:2048
	ds_read_b128 v[156:159], v156 offset:3072
	v_lshl_add_u64 v[202:203], s[12:13], 0, v[194:195]
	s_add_i32 m0, s53, 0xc000
	ds_read_b128 v[160:163], v215
	ds_read_b128 v[164:167], v215 offset:1024
	ds_read_b128 v[168:171], v215 offset:2048
	ds_read_b128 v[172:175], v215 offset:3072
	ds_read_b128 v[176:179], v215 offset:4096
	ds_read_b128 v[180:183], v215 offset:5120
	ds_read_b128 v[184:187], v215 offset:6144
	ds_read_b128 v[198:201], v215 offset:7168
	global_load_lds_dwordx4 v[202:203], off
	v_lshl_add_u64 v[202:203], s[12:13], 0, v[196:197]
	s_add_i32 m0, s53, 0xe000
	s_nop 0
	global_load_lds_dwordx4 v[202:203], off
	s_waitcnt vmcnt(8)
	s_waitcnt lgkmcnt(0)
	s_barrier
	s_setprio 0
	s_waitcnt lgkmcnt(0)
	v_mfma_f32_16x16x32_bf16 v[124:127], v[128:131], v[160:163], v[124:127]
	v_mfma_f32_16x16x32_bf16 v[120:123], v[136:139], v[160:163], v[120:123]
	v_mfma_f32_16x16x32_bf16 v[108:111], v[128:131], v[168:171], v[108:111]
	v_mfma_f32_16x16x32_bf16 v[104:107], v[136:139], v[168:171], v[104:107]
	v_mfma_f32_16x16x32_bf16 v[92:95], v[128:131], v[176:179], v[92:95]
	v_mfma_f32_16x16x32_bf16 v[88:91], v[136:139], v[176:179], v[88:91]
	v_mfma_f32_16x16x32_bf16 v[76:79], v[128:131], v[184:187], v[76:79]
	v_mfma_f32_16x16x32_bf16 v[72:75], v[136:139], v[184:187], v[72:75]
	v_mfma_f32_16x16x32_bf16 v[124:127], v[132:135], v[164:167], v[124:127]
	v_mfma_f32_16x16x32_bf16 v[120:123], v[140:143], v[164:167], v[120:123]
	v_mfma_f32_16x16x32_bf16 v[108:111], v[132:135], v[172:175], v[108:111]
	v_mfma_f32_16x16x32_bf16 v[104:107], v[140:143], v[172:175], v[104:107]
	v_mfma_f32_16x16x32_bf16 v[92:95], v[132:135], v[180:183], v[92:95]
	v_mfma_f32_16x16x32_bf16 v[88:91], v[140:143], v[180:183], v[88:91]
	v_mfma_f32_16x16x32_bf16 v[76:79], v[132:135], v[198:201], v[76:79]
	v_mfma_f32_16x16x32_bf16 v[72:75], v[140:143], v[198:201], v[72:75]
	s_setprio 1
	s_setprio 0
	v_mfma_f32_16x16x32_bf16 v[116:119], v[144:147], v[160:163], v[116:119]
	v_mfma_f32_16x16x32_bf16 v[112:115], v[152:155], v[160:163], v[112:115]
	v_mfma_f32_16x16x32_bf16 v[100:103], v[144:147], v[168:171], v[100:103]
	v_mfma_f32_16x16x32_bf16 v[96:99], v[152:155], v[168:171], v[96:99]
	v_mfma_f32_16x16x32_bf16 v[84:87], v[144:147], v[176:179], v[84:87]
	v_mfma_f32_16x16x32_bf16 v[80:83], v[152:155], v[176:179], v[80:83]
	v_mfma_f32_16x16x32_bf16 v[68:71], v[144:147], v[184:187], v[68:71]
	v_mfma_f32_16x16x32_bf16 v[64:67], v[152:155], v[184:187], v[64:67]
	v_mfma_f32_16x16x32_bf16 v[116:119], v[148:151], v[164:167], v[116:119]
	v_mfma_f32_16x16x32_bf16 v[112:115], v[156:159], v[164:167], v[112:115]
	v_mfma_f32_16x16x32_bf16 v[100:103], v[148:151], v[172:175], v[100:103]
	v_mfma_f32_16x16x32_bf16 v[96:99], v[156:159], v[172:175], v[96:99]
	v_mfma_f32_16x16x32_bf16 v[84:87], v[148:151], v[180:183], v[84:87]
	v_mfma_f32_16x16x32_bf16 v[80:83], v[156:159], v[180:183], v[80:83]
	v_mfma_f32_16x16x32_bf16 v[68:71], v[148:151], v[198:201], v[68:71]
	v_mfma_f32_16x16x32_bf16 v[64:67], v[156:159], v[198:201], v[64:67]
	s_setprio 1
	s_barrier
	s_add_i32 s37, s37, s50
	v_lshl_add_u64 v[202:203], s[64:65], 0, v[224:225]
	s_mov_b32 m0, s37
	ds_read_b128 v[160:163], v215 offset:16384
	ds_read_b128 v[164:167], v215 offset:17408
	ds_read_b128 v[168:171], v215 offset:18432
	ds_read_b128 v[172:175], v215 offset:19456
	ds_read_b128 v[176:179], v215 offset:20480
	ds_read_b128 v[180:183], v215 offset:21504
	ds_read_b128 v[184:187], v215 offset:22528
	ds_read_b128 v[198:201], v215 offset:23552
	global_load_lds_dwordx4 v[202:203], off
	s_add_i32 m0, s37, 0x2000
	v_lshl_add_u64 v[204:205], s[64:65], 0, v[188:189]
	s_add_u32 s64, s64, s10
	s_addc_u32 s65, s65, 0
	s_add_i32 s35, s35, s50
	global_load_lds_dwordx4 v[204:205], off
	v_lshl_add_u64 v[206:207], s[64:65], 0, v[224:225]
	s_mov_b32 m0, s35
	v_lshl_add_u64 v[208:209], s[64:65], 0, v[188:189]
	global_load_lds_dwordx4 v[206:207], off
	s_add_i32 m0, s35, 0x2000
	v_lshl_add_u64 v[210:211], s[8:9], 0, v[192:193]
	global_load_lds_dwordx4 v[208:209], off
	s_mov_b32 m0, s53
	v_lshl_add_u64 v[212:213], s[8:9], 0, v[190:191]
	global_load_lds_dwordx4 v[210:211], off
	s_mov_b32 m0, s54
	s_nop 0
	global_load_lds_dwordx4 v[212:213], off
	s_waitcnt vmcnt(8)
	s_waitcnt lgkmcnt(0)
	s_barrier
	s_setprio 0
	s_waitcnt lgkmcnt(0)
	v_mfma_f32_16x16x32_bf16 v[60:63], v[128:131], v[160:163], v[60:63]
	v_mfma_f32_16x16x32_bf16 v[56:59], v[136:139], v[160:163], v[56:59]
	v_mfma_f32_16x16x32_bf16 v[44:47], v[128:131], v[168:171], v[44:47]
	v_mfma_f32_16x16x32_bf16 v[40:43], v[136:139], v[168:171], v[40:43]
	v_mfma_f32_16x16x32_bf16 v[28:31], v[128:131], v[176:179], v[28:31]
	v_mfma_f32_16x16x32_bf16 v[24:27], v[136:139], v[176:179], v[24:27]
	v_mfma_f32_16x16x32_bf16 v[12:15], v[128:131], v[184:187], v[12:15]
	v_mfma_f32_16x16x32_bf16 v[8:11], v[136:139], v[184:187], v[8:11]
	v_mfma_f32_16x16x32_bf16 v[60:63], v[132:135], v[164:167], v[60:63]
	v_mfma_f32_16x16x32_bf16 v[56:59], v[140:143], v[164:167], v[56:59]
	v_mfma_f32_16x16x32_bf16 v[44:47], v[132:135], v[172:175], v[44:47]
	v_mfma_f32_16x16x32_bf16 v[40:43], v[140:143], v[172:175], v[40:43]
	v_mfma_f32_16x16x32_bf16 v[28:31], v[132:135], v[180:183], v[28:31]
	v_mfma_f32_16x16x32_bf16 v[24:27], v[140:143], v[180:183], v[24:27]
	v_mfma_f32_16x16x32_bf16 v[12:15], v[132:135], v[198:201], v[12:15]
	v_mfma_f32_16x16x32_bf16 v[8:11], v[140:143], v[198:201], v[8:11]
	s_setprio 1
	s_setprio 0
	v_mfma_f32_16x16x32_bf16 v[52:55], v[144:147], v[160:163], v[52:55]
	v_mfma_f32_16x16x32_bf16 v[48:51], v[152:155], v[160:163], v[48:51]
	v_mfma_f32_16x16x32_bf16 v[36:39], v[144:147], v[168:171], v[36:39]
	v_mfma_f32_16x16x32_bf16 v[32:35], v[152:155], v[168:171], v[32:35]
	v_mfma_f32_16x16x32_bf16 v[20:23], v[144:147], v[176:179], v[20:23]
	v_mfma_f32_16x16x32_bf16 v[16:19], v[152:155], v[176:179], v[16:19]
	v_mfma_f32_16x16x32_bf16 v[4:7], v[144:147], v[184:187], v[4:7]
	v_mfma_f32_16x16x32_bf16 v[0:3], v[152:155], v[184:187], v[0:3]
	v_mfma_f32_16x16x32_bf16 v[52:55], v[148:151], v[164:167], v[52:55]
	v_mfma_f32_16x16x32_bf16 v[48:51], v[156:159], v[164:167], v[48:51]
	v_mfma_f32_16x16x32_bf16 v[36:39], v[148:151], v[172:175], v[36:39]
	v_mfma_f32_16x16x32_bf16 v[32:35], v[156:159], v[172:175], v[32:35]
	v_mfma_f32_16x16x32_bf16 v[20:23], v[148:151], v[180:183], v[20:23]
	v_mfma_f32_16x16x32_bf16 v[16:19], v[156:159], v[180:183], v[16:19]
	v_mfma_f32_16x16x32_bf16 v[4:7], v[148:151], v[198:201], v[4:7]
	v_mfma_f32_16x16x32_bf16 v[0:3], v[156:159], v[198:201], v[0:3]
	s_setprio 1
	s_barrier
	s_add_i32 s35, 0, 0x18000
	s_add_i32 s37, 0, 0x1c000
	v_add_u32_e32 v140, s35, v214
	v_add_u32_e32 v156, s37, v214
	ds_read_b128 v[128:131], v140
	ds_read_b128 v[132:135], v140 offset:1024
	ds_read_b128 v[136:139], v140 offset:2048
	ds_read_b128 v[140:143], v140 offset:3072
	ds_read_b128 v[144:147], v156
	ds_read_b128 v[148:151], v156 offset:1024
	ds_read_b128 v[152:155], v156 offset:2048
	ds_read_b128 v[156:159], v156 offset:3072
	s_add_u32 s8, s8, s10
	s_addc_u32 s9, s9, 0
	s_mov_b32 m0, s55
	v_lshl_add_u64 v[216:217], s[8:9], 0, v[192:193]
	ds_read_b128 v[160:163], v215 offset:32768
	ds_read_b128 v[164:167], v215 offset:33792
	ds_read_b128 v[168:171], v215 offset:34816
	ds_read_b128 v[172:175], v215 offset:35840
	ds_read_b128 v[176:179], v215 offset:36864
	ds_read_b128 v[180:183], v215 offset:37888
	ds_read_b128 v[184:187], v215 offset:38912
	ds_read_b128 v[198:201], v215 offset:39936
	global_load_lds_dwordx4 v[216:217], off
	v_lshl_add_u64 v[216:217], s[8:9], 0, v[190:191]
	s_mov_b32 m0, s56
	s_nop 0
	global_load_lds_dwordx4 v[216:217], off
	s_waitcnt vmcnt(8)
	s_waitcnt lgkmcnt(0)
	s_barrier
	s_setprio 0
	s_waitcnt lgkmcnt(0)
	v_mfma_f32_16x16x32_bf16 v[124:127], v[128:131], v[160:163], v[124:127]
	v_mfma_f32_16x16x32_bf16 v[120:123], v[136:139], v[160:163], v[120:123]
	v_mfma_f32_16x16x32_bf16 v[108:111], v[128:131], v[168:171], v[108:111]
	v_mfma_f32_16x16x32_bf16 v[104:107], v[136:139], v[168:171], v[104:107]
	v_mfma_f32_16x16x32_bf16 v[92:95], v[128:131], v[176:179], v[92:95]
	v_mfma_f32_16x16x32_bf16 v[88:91], v[136:139], v[176:179], v[88:91]
	v_mfma_f32_16x16x32_bf16 v[76:79], v[128:131], v[184:187], v[76:79]
	v_mfma_f32_16x16x32_bf16 v[72:75], v[136:139], v[184:187], v[72:75]
	v_mfma_f32_16x16x32_bf16 v[124:127], v[132:135], v[164:167], v[124:127]
	v_mfma_f32_16x16x32_bf16 v[120:123], v[140:143], v[164:167], v[120:123]
	v_mfma_f32_16x16x32_bf16 v[108:111], v[132:135], v[172:175], v[108:111]
	v_mfma_f32_16x16x32_bf16 v[104:107], v[140:143], v[172:175], v[104:107]
	v_mfma_f32_16x16x32_bf16 v[92:95], v[132:135], v[180:183], v[92:95]
	v_mfma_f32_16x16x32_bf16 v[88:91], v[140:143], v[180:183], v[88:91]
	v_mfma_f32_16x16x32_bf16 v[76:79], v[132:135], v[198:201], v[76:79]
	v_mfma_f32_16x16x32_bf16 v[72:75], v[140:143], v[198:201], v[72:75]
	s_setprio 1
	s_setprio 0
	v_mfma_f32_16x16x32_bf16 v[116:119], v[144:147], v[160:163], v[116:119]
	v_mfma_f32_16x16x32_bf16 v[112:115], v[152:155], v[160:163], v[112:115]
	v_mfma_f32_16x16x32_bf16 v[100:103], v[144:147], v[168:171], v[100:103]
	v_mfma_f32_16x16x32_bf16 v[96:99], v[152:155], v[168:171], v[96:99]
	v_mfma_f32_16x16x32_bf16 v[84:87], v[144:147], v[176:179], v[84:87]
	v_mfma_f32_16x16x32_bf16 v[80:83], v[152:155], v[176:179], v[80:83]
	v_mfma_f32_16x16x32_bf16 v[68:71], v[144:147], v[184:187], v[68:71]
	v_mfma_f32_16x16x32_bf16 v[64:67], v[152:155], v[184:187], v[64:67]
	v_mfma_f32_16x16x32_bf16 v[116:119], v[148:151], v[164:167], v[116:119]
	v_mfma_f32_16x16x32_bf16 v[112:115], v[156:159], v[164:167], v[112:115]
	v_mfma_f32_16x16x32_bf16 v[100:103], v[148:151], v[172:175], v[100:103]
	v_mfma_f32_16x16x32_bf16 v[96:99], v[156:159], v[172:175], v[96:99]
	v_mfma_f32_16x16x32_bf16 v[84:87], v[148:151], v[180:183], v[84:87]
	v_mfma_f32_16x16x32_bf16 v[80:83], v[156:159], v[180:183], v[80:83]
	v_mfma_f32_16x16x32_bf16 v[68:71], v[148:151], v[198:201], v[68:71]
	v_mfma_f32_16x16x32_bf16 v[64:67], v[156:159], v[198:201], v[64:67]
	s_setprio 1
	s_barrier
	s_add_i32 s8, s35, s50
	v_lshl_add_u64 v[202:203], v[202:203], 0, s[24:25]
	s_mov_b32 m0, s8
	ds_read_b128 v[160:163], v215 offset:49152
	ds_read_b128 v[164:167], v215 offset:50176
	ds_read_b128 v[168:171], v215 offset:51200
	ds_read_b128 v[172:175], v215 offset:52224
	ds_read_b128 v[176:179], v215 offset:53248
	ds_read_b128 v[180:183], v215 offset:54272
	ds_read_b128 v[184:187], v215 offset:55296
	ds_read_b128 v[198:201], v215 offset:56320
	global_load_lds_dwordx4 v[202:203], off
	v_lshl_add_u64 v[202:203], v[204:205], 0, s[24:25]
	s_add_i32 m0, s8, 0x2000
	s_add_i32 s8, s37, s50
	global_load_lds_dwordx4 v[202:203], off
	v_lshl_add_u64 v[202:203], v[206:207], 0, s[24:25]
	s_mov_b32 m0, s8
	s_nop 0
	global_load_lds_dwordx4 v[202:203], off
	v_lshl_add_u64 v[202:203], v[208:209], 0, s[24:25]
	s_add_i32 m0, s8, 0x2000
	s_nop 0
	global_load_lds_dwordx4 v[202:203], off
	v_lshl_add_u64 v[202:203], v[210:211], 0, s[24:25]
	s_mov_b32 m0, s57
	s_nop 0
	global_load_lds_dwordx4 v[202:203], off
	v_lshl_add_u64 v[202:203], v[212:213], 0, s[24:25]
	s_mov_b32 m0, s58
	s_nop 0
	global_load_lds_dwordx4 v[202:203], off
	s_waitcnt vmcnt(8)
	s_waitcnt lgkmcnt(0)
	s_barrier
	s_setprio 0
	s_waitcnt lgkmcnt(0)
	v_mfma_f32_16x16x32_bf16 v[60:63], v[128:131], v[160:163], v[60:63]
	v_mfma_f32_16x16x32_bf16 v[56:59], v[136:139], v[160:163], v[56:59]
	v_mfma_f32_16x16x32_bf16 v[44:47], v[128:131], v[168:171], v[44:47]
	v_mfma_f32_16x16x32_bf16 v[40:43], v[136:139], v[168:171], v[40:43]
	v_mfma_f32_16x16x32_bf16 v[28:31], v[128:131], v[176:179], v[28:31]
	v_mfma_f32_16x16x32_bf16 v[24:27], v[136:139], v[176:179], v[24:27]
	v_mfma_f32_16x16x32_bf16 v[12:15], v[128:131], v[184:187], v[12:15]
	v_mfma_f32_16x16x32_bf16 v[8:11], v[136:139], v[184:187], v[8:11]
	v_mfma_f32_16x16x32_bf16 v[60:63], v[132:135], v[164:167], v[60:63]
	v_mfma_f32_16x16x32_bf16 v[56:59], v[140:143], v[164:167], v[56:59]
	v_mfma_f32_16x16x32_bf16 v[44:47], v[132:135], v[172:175], v[44:47]
	v_mfma_f32_16x16x32_bf16 v[40:43], v[140:143], v[172:175], v[40:43]
	v_mfma_f32_16x16x32_bf16 v[28:31], v[132:135], v[180:183], v[28:31]
	v_mfma_f32_16x16x32_bf16 v[24:27], v[140:143], v[180:183], v[24:27]
	v_mfma_f32_16x16x32_bf16 v[12:15], v[132:135], v[198:201], v[12:15]
	v_mfma_f32_16x16x32_bf16 v[8:11], v[140:143], v[198:201], v[8:11]
	s_setprio 1
	s_setprio 0
	v_mfma_f32_16x16x32_bf16 v[52:55], v[144:147], v[160:163], v[52:55]
	v_mfma_f32_16x16x32_bf16 v[48:51], v[152:155], v[160:163], v[48:51]
	v_mfma_f32_16x16x32_bf16 v[36:39], v[144:147], v[168:171], v[36:39]
	v_mfma_f32_16x16x32_bf16 v[32:35], v[152:155], v[168:171], v[32:35]
	v_mfma_f32_16x16x32_bf16 v[20:23], v[144:147], v[176:179], v[20:23]
	v_mfma_f32_16x16x32_bf16 v[16:19], v[152:155], v[176:179], v[16:19]
	v_mfma_f32_16x16x32_bf16 v[4:7], v[144:147], v[184:187], v[4:7]
	v_mfma_f32_16x16x32_bf16 v[0:3], v[152:155], v[184:187], v[0:3]
	v_mfma_f32_16x16x32_bf16 v[52:55], v[148:151], v[164:167], v[52:55]
	v_mfma_f32_16x16x32_bf16 v[48:51], v[156:159], v[164:167], v[48:51]
	v_mfma_f32_16x16x32_bf16 v[36:39], v[148:151], v[172:175], v[36:39]
	v_mfma_f32_16x16x32_bf16 v[32:35], v[156:159], v[172:175], v[32:35]
	v_mfma_f32_16x16x32_bf16 v[20:23], v[148:151], v[180:183], v[20:23]
	v_mfma_f32_16x16x32_bf16 v[16:19], v[156:159], v[180:183], v[16:19]
	v_mfma_f32_16x16x32_bf16 v[4:7], v[148:151], v[198:201], v[4:7]
	v_mfma_f32_16x16x32_bf16 v[0:3], v[156:159], v[198:201], v[0:3]
	s_setprio 1
	s_barrier
	s_add_u32 s12, s12, 0x100
	s_addc_u32 s13, s13, 0
	s_add_u32 s30, s30, 0x100
	s_addc_u32 s31, s31, 0
	s_cmp_ge_i32 s33, s60
	s_mov_b32 s8, s33
	s_cbranch_scc0 .LBB0_1892
	v_readlane_b32 s64, v253, 21
	v_readlane_b32 s65, v253, 22

.LBB0_2049:
	s_add_i32 s48, s28, 2
	s_add_u32 s8, s12, 0x100
	s_addc_u32 s9, s13, 0
	s_add_i32 s49, 0, 0x10000
	s_cmp_eq_u32 s66, s28
	s_cselect_b32 s43, s7, s9
	s_cselect_b32 s42, s30, s8
	s_cselect_b32 s29, s31, s37
	s_cselect_b32 s28, s33, s35
	s_add_i32 s70, 0, 0x14000
	v_add_u32_e32 v140, s49, v248
	v_add_u32_e32 v156, s70, v248
	ds_read_b128 v[128:131], v140
	ds_read_b128 v[132:135], v140 offset:1024
	ds_read_b128 v[136:139], v140 offset:2048
	ds_read_b128 v[140:143], v140 offset:3072
	ds_read_b128 v[144:147], v156
	ds_read_b128 v[148:151], v156 offset:1024
	ds_read_b128 v[152:155], v156 offset:2048
	ds_read_b128 v[156:159], v156 offset:3072
	v_lshl_add_u64 v[192:193], s[12:13], 0, v[236:237]
	s_add_i32 m0, s55, 0xc000
	ds_read_b128 v[160:163], v249
	ds_read_b128 v[164:167], v249 offset:1024
	ds_read_b128 v[168:171], v249 offset:2048
	ds_read_b128 v[172:175], v249 offset:3072
	ds_read_b128 v[176:179], v249 offset:4096
	ds_read_b128 v[180:183], v249 offset:5120
	ds_read_b128 v[184:187], v249 offset:6144
	ds_read_b128 v[188:191], v249 offset:7168
	global_load_lds_dwordx4 v[192:193], off
	v_lshl_add_u64 v[192:193], s[12:13], 0, v[238:239]
	s_add_i32 m0, s55, 0xe000
	s_nop 0
	global_load_lds_dwordx4 v[192:193], off
	s_waitcnt vmcnt(8)
	s_waitcnt lgkmcnt(0)
	s_barrier
	s_setprio 0
	s_waitcnt lgkmcnt(0)
	v_mfma_f32_16x16x32_bf16 v[100:103], v[128:131], v[160:163], v[100:103]
	v_mfma_f32_16x16x32_bf16 v[116:119], v[136:139], v[160:163], v[116:119]
	v_mfma_f32_16x16x32_bf16 v[96:99], v[128:131], v[168:171], v[96:99]
	v_mfma_f32_16x16x32_bf16 v[112:115], v[136:139], v[168:171], v[112:115]
	v_mfma_f32_16x16x32_bf16 v[104:107], v[128:131], v[176:179], v[104:107]
	v_mfma_f32_16x16x32_bf16 v[120:123], v[136:139], v[176:179], v[120:123]
	v_mfma_f32_16x16x32_bf16 v[108:111], v[128:131], v[184:187], v[108:111]
	v_mfma_f32_16x16x32_bf16 v[124:127], v[136:139], v[184:187], v[124:127]
	v_mfma_f32_16x16x32_bf16 v[100:103], v[132:135], v[164:167], v[100:103]
	v_mfma_f32_16x16x32_bf16 v[116:119], v[140:143], v[164:167], v[116:119]
	v_mfma_f32_16x16x32_bf16 v[96:99], v[132:135], v[172:175], v[96:99]
	v_mfma_f32_16x16x32_bf16 v[112:115], v[140:143], v[172:175], v[112:115]
	v_mfma_f32_16x16x32_bf16 v[104:107], v[132:135], v[180:183], v[104:107]
	v_mfma_f32_16x16x32_bf16 v[120:123], v[140:143], v[180:183], v[120:123]
	v_mfma_f32_16x16x32_bf16 v[108:111], v[132:135], v[188:191], v[108:111]
	v_mfma_f32_16x16x32_bf16 v[124:127], v[140:143], v[188:191], v[124:127]
	s_setprio 1
	s_setprio 0
	v_mfma_f32_16x16x32_bf16 v[84:87], v[144:147], v[160:163], v[84:87]
	v_mfma_f32_16x16x32_bf16 v[68:71], v[152:155], v[160:163], v[68:71]
	v_mfma_f32_16x16x32_bf16 v[80:83], v[144:147], v[168:171], v[80:83]
	v_mfma_f32_16x16x32_bf16 v[64:67], v[152:155], v[168:171], v[64:67]
	v_mfma_f32_16x16x32_bf16 v[88:91], v[144:147], v[176:179], v[88:91]
	v_mfma_f32_16x16x32_bf16 v[72:75], v[152:155], v[176:179], v[72:75]
	v_mfma_f32_16x16x32_bf16 v[92:95], v[144:147], v[184:187], v[92:95]
	v_mfma_f32_16x16x32_bf16 v[76:79], v[152:155], v[184:187], v[76:79]
	v_mfma_f32_16x16x32_bf16 v[84:87], v[148:151], v[164:167], v[84:87]
	v_mfma_f32_16x16x32_bf16 v[68:71], v[156:159], v[164:167], v[68:71]
	v_mfma_f32_16x16x32_bf16 v[80:83], v[148:151], v[172:175], v[80:83]
	v_mfma_f32_16x16x32_bf16 v[64:67], v[156:159], v[172:175], v[64:67]
	v_mfma_f32_16x16x32_bf16 v[88:91], v[148:151], v[180:183], v[88:91]
	v_mfma_f32_16x16x32_bf16 v[72:75], v[156:159], v[180:183], v[72:75]
	v_mfma_f32_16x16x32_bf16 v[92:95], v[148:151], v[188:191], v[92:95]
	v_mfma_f32_16x16x32_bf16 v[76:79], v[156:159], v[188:191], v[76:79]
	s_setprio 1
	s_barrier
	s_add_i32 s12, s49, s53
	v_lshl_add_u64 v[192:193], s[28:29], 0, v[224:225]
	s_mov_b32 m0, s12
	ds_read_b128 v[160:163], v249 offset:16384
	ds_read_b128 v[164:167], v249 offset:17408
	ds_read_b128 v[168:171], v249 offset:18432
	ds_read_b128 v[172:175], v249 offset:19456
	ds_read_b128 v[176:179], v249 offset:20480
	ds_read_b128 v[180:183], v249 offset:21504
	ds_read_b128 v[184:187], v249 offset:22528
	ds_read_b128 v[188:191], v249 offset:23552
	global_load_lds_dwordx4 v[192:193], off
	s_add_i32 m0, s12, 0x2000
	s_add_u32 s12, s28, 0x80000
	v_lshl_add_u64 v[194:195], s[28:29], 0, v[230:231]
	s_addc_u32 s13, s29, 0
	s_add_i32 s49, s70, s53
	global_load_lds_dwordx4 v[194:195], off
	v_lshl_add_u64 v[196:197], s[12:13], 0, v[224:225]
	s_mov_b32 m0, s49
	v_lshl_add_u64 v[198:199], s[42:43], 0, v[232:233]
	global_load_lds_dwordx4 v[196:197], off
	v_lshl_add_u64 v[196:197], s[12:13], 0, v[230:231]
	s_add_i32 m0, s49, 0x2000
	s_nop 0
	global_load_lds_dwordx4 v[196:197], off
	v_lshl_add_u64 v[196:197], s[42:43], 0, v[234:235]
	s_mov_b32 m0, s55
	s_nop 0
	global_load_lds_dwordx4 v[196:197], off
	s_mov_b32 m0, s56
	s_nop 0
	global_load_lds_dwordx4 v[198:199], off
	s_waitcnt vmcnt(8)
	s_waitcnt lgkmcnt(0)
	s_barrier
	s_setprio 0
	s_waitcnt lgkmcnt(0)
	v_mfma_f32_16x16x32_bf16 v[16:19], v[128:131], v[160:163], v[16:19]
	v_mfma_f32_16x16x32_bf16 v[44:47], v[136:139], v[160:163], v[44:47]
	v_mfma_f32_16x16x32_bf16 v[24:27], v[128:131], v[168:171], v[24:27]
	v_mfma_f32_16x16x32_bf16 v[52:55], v[136:139], v[168:171], v[52:55]
	v_mfma_f32_16x16x32_bf16 v[32:35], v[128:131], v[176:179], v[32:35]
	v_mfma_f32_16x16x32_bf16 v[56:59], v[136:139], v[176:179], v[56:59]
	v_mfma_f32_16x16x32_bf16 v[40:43], v[128:131], v[184:187], v[40:43]
	v_mfma_f32_16x16x32_bf16 v[60:63], v[136:139], v[184:187], v[60:63]
	v_mfma_f32_16x16x32_bf16 v[16:19], v[132:135], v[164:167], v[16:19]
	v_mfma_f32_16x16x32_bf16 v[44:47], v[140:143], v[164:167], v[44:47]
	v_mfma_f32_16x16x32_bf16 v[24:27], v[132:135], v[172:175], v[24:27]
	v_mfma_f32_16x16x32_bf16 v[52:55], v[140:143], v[172:175], v[52:55]
	v_mfma_f32_16x16x32_bf16 v[32:35], v[132:135], v[180:183], v[32:35]
	v_mfma_f32_16x16x32_bf16 v[56:59], v[140:143], v[180:183], v[56:59]
	v_mfma_f32_16x16x32_bf16 v[40:43], v[132:135], v[188:191], v[40:43]
	v_mfma_f32_16x16x32_bf16 v[60:63], v[140:143], v[188:191], v[60:63]
	s_setprio 1
	s_setprio 0
	v_mfma_f32_16x16x32_bf16 v[20:23], v[144:147], v[160:163], v[20:23]
	v_mfma_f32_16x16x32_bf16 v[4:7], v[152:155], v[160:163], v[4:7]
	v_mfma_f32_16x16x32_bf16 v[28:31], v[144:147], v[168:171], v[28:31]
	v_mfma_f32_16x16x32_bf16 v[0:3], v[152:155], v[168:171], v[0:3]
	v_mfma_f32_16x16x32_bf16 v[36:39], v[144:147], v[176:179], v[36:39]
	v_mfma_f32_16x16x32_bf16 v[8:11], v[152:155], v[176:179], v[8:11]
	v_mfma_f32_16x16x32_bf16 v[48:51], v[144:147], v[184:187], v[48:51]
	v_mfma_f32_16x16x32_bf16 v[12:15], v[152:155], v[184:187], v[12:15]
	v_mfma_f32_16x16x32_bf16 v[20:23], v[148:151], v[164:167], v[20:23]
	v_mfma_f32_16x16x32_bf16 v[4:7], v[156:159], v[164:167], v[4:7]
	v_mfma_f32_16x16x32_bf16 v[28:31], v[148:151], v[172:175], v[28:31]
	v_mfma_f32_16x16x32_bf16 v[0:3], v[156:159], v[172:175], v[0:3]
	v_mfma_f32_16x16x32_bf16 v[36:39], v[148:151], v[180:183], v[36:39]
	v_mfma_f32_16x16x32_bf16 v[8:11], v[156:159], v[180:183], v[8:11]
	v_mfma_f32_16x16x32_bf16 v[48:51], v[148:151], v[188:191], v[48:51]
	v_mfma_f32_16x16x32_bf16 v[12:15], v[156:159], v[188:191], v[12:15]
	s_setprio 1
	s_barrier
	s_add_i32 s49, 0, 0x18000
	s_add_i32 s70, 0, 0x1c000
	v_add_u32_e32 v140, s49, v248
	v_add_u32_e32 v156, s70, v248
	ds_read_b128 v[128:131], v140
	ds_read_b128 v[132:135], v140 offset:1024
	ds_read_b128 v[136:139], v140 offset:2048
	ds_read_b128 v[140:143], v140 offset:3072
	ds_read_b128 v[144:147], v156
	ds_read_b128 v[148:151], v156 offset:1024
	ds_read_b128 v[152:155], v156 offset:2048
	ds_read_b128 v[156:159], v156 offset:3072
	s_add_u32 s12, s42, 0x80000
	s_addc_u32 s13, s43, 0
	s_mov_b32 m0, s57
	v_lshl_add_u64 v[200:201], s[12:13], 0, v[234:235]
	ds_read_b128 v[160:163], v249 offset:32768
	ds_read_b128 v[164:167], v249 offset:33792
	ds_read_b128 v[168:171], v249 offset:34816
	ds_read_b128 v[172:175], v249 offset:35840
	ds_read_b128 v[176:179], v249 offset:36864
	ds_read_b128 v[180:183], v249 offset:37888
	ds_read_b128 v[184:187], v249 offset:38912
	ds_read_b128 v[188:191], v249 offset:39936
	global_load_lds_dwordx4 v[200:201], off
	v_lshl_add_u64 v[200:201], s[12:13], 0, v[232:233]
	s_mov_b32 m0, s58
	s_nop 0
	global_load_lds_dwordx4 v[200:201], off
	s_waitcnt vmcnt(8)
	s_waitcnt lgkmcnt(0)
	s_barrier
	s_setprio 0
	s_waitcnt lgkmcnt(0)
	v_mfma_f32_16x16x32_bf16 v[100:103], v[128:131], v[160:163], v[100:103]
	v_mfma_f32_16x16x32_bf16 v[116:119], v[136:139], v[160:163], v[116:119]
	v_mfma_f32_16x16x32_bf16 v[96:99], v[128:131], v[168:171], v[96:99]
	v_mfma_f32_16x16x32_bf16 v[112:115], v[136:139], v[168:171], v[112:115]
	v_mfma_f32_16x16x32_bf16 v[104:107], v[128:131], v[176:179], v[104:107]
	v_mfma_f32_16x16x32_bf16 v[120:123], v[136:139], v[176:179], v[120:123]
	v_mfma_f32_16x16x32_bf16 v[108:111], v[128:131], v[184:187], v[108:111]
	v_mfma_f32_16x16x32_bf16 v[124:127], v[136:139], v[184:187], v[124:127]
	v_mfma_f32_16x16x32_bf16 v[100:103], v[132:135], v[164:167], v[100:103]
	v_mfma_f32_16x16x32_bf16 v[116:119], v[140:143], v[164:167], v[116:119]
	v_mfma_f32_16x16x32_bf16 v[96:99], v[132:135], v[172:175], v[96:99]
	v_mfma_f32_16x16x32_bf16 v[112:115], v[140:143], v[172:175], v[112:115]
	v_mfma_f32_16x16x32_bf16 v[104:107], v[132:135], v[180:183], v[104:107]
	v_mfma_f32_16x16x32_bf16 v[120:123], v[140:143], v[180:183], v[120:123]
	v_mfma_f32_16x16x32_bf16 v[108:111], v[132:135], v[188:191], v[108:111]
	v_mfma_f32_16x16x32_bf16 v[124:127], v[140:143], v[188:191], v[124:127]
	s_setprio 1
	s_setprio 0
	v_mfma_f32_16x16x32_bf16 v[84:87], v[144:147], v[160:163], v[84:87]
	v_mfma_f32_16x16x32_bf16 v[68:71], v[152:155], v[160:163], v[68:71]
	v_mfma_f32_16x16x32_bf16 v[80:83], v[144:147], v[168:171], v[80:83]
	v_mfma_f32_16x16x32_bf16 v[64:67], v[152:155], v[168:171], v[64:67]
	v_mfma_f32_16x16x32_bf16 v[88:91], v[144:147], v[176:179], v[88:91]
	v_mfma_f32_16x16x32_bf16 v[72:75], v[152:155], v[176:179], v[72:75]
	v_mfma_f32_16x16x32_bf16 v[92:95], v[144:147], v[184:187], v[92:95]
	v_mfma_f32_16x16x32_bf16 v[76:79], v[152:155], v[184:187], v[76:79]
	v_mfma_f32_16x16x32_bf16 v[84:87], v[148:151], v[164:167], v[84:87]
	v_mfma_f32_16x16x32_bf16 v[68:71], v[156:159], v[164:167], v[68:71]
	v_mfma_f32_16x16x32_bf16 v[80:83], v[148:151], v[172:175], v[80:83]
	v_mfma_f32_16x16x32_bf16 v[64:67], v[156:159], v[172:175], v[64:67]
	v_mfma_f32_16x16x32_bf16 v[88:91], v[148:151], v[180:183], v[88:91]
	v_mfma_f32_16x16x32_bf16 v[72:75], v[156:159], v[180:183], v[72:75]
	v_mfma_f32_16x16x32_bf16 v[92:95], v[148:151], v[188:191], v[92:95]
	v_mfma_f32_16x16x32_bf16 v[76:79], v[156:159], v[188:191], v[76:79]
	s_setprio 1
	s_barrier
	s_add_i32 s12, s49, s53
	v_lshl_add_u64 v[192:193], v[192:193], 0, s[24:25]
	s_mov_b32 m0, s12
	ds_read_b128 v[160:163], v249 offset:49152
	ds_read_b128 v[164:167], v249 offset:50176
	ds_read_b128 v[168:171], v249 offset:51200
	ds_read_b128 v[172:175], v249 offset:52224
	ds_read_b128 v[176:179], v249 offset:53248
	ds_read_b128 v[180:183], v249 offset:54272
	ds_read_b128 v[184:187], v249 offset:55296
	ds_read_b128 v[188:191], v249 offset:56320
	global_load_lds_dwordx4 v[192:193], off
	s_add_i32 m0, s12, 0x2000
	s_add_u32 s12, s28, 0x80080
	v_lshl_add_u64 v[192:193], v[194:195], 0, s[24:25]
	s_addc_u32 s13, s29, 0
	s_add_i32 s28, s70, s53
	global_load_lds_dwordx4 v[192:193], off
	v_lshl_add_u64 v[192:193], s[12:13], 0, v[224:225]
	s_mov_b32 m0, s28
	s_nop 0
	global_load_lds_dwordx4 v[192:193], off
	v_lshl_add_u64 v[192:193], s[12:13], 0, v[230:231]
	s_add_i32 m0, s28, 0x2000
	s_nop 0
	global_load_lds_dwordx4 v[192:193], off
	v_lshl_add_u64 v[192:193], v[196:197], 0, s[24:25]
	s_mov_b32 m0, s63
	s_nop 0
	global_load_lds_dwordx4 v[192:193], off
	v_lshl_add_u64 v[192:193], v[198:199], 0, s[24:25]
	s_mov_b32 m0, s64
	s_nop 0
	global_load_lds_dwordx4 v[192:193], off
	s_waitcnt vmcnt(8)
	s_waitcnt lgkmcnt(0)
	s_barrier
	s_setprio 0
	s_waitcnt lgkmcnt(0)
	v_mfma_f32_16x16x32_bf16 v[16:19], v[128:131], v[160:163], v[16:19]
	v_mfma_f32_16x16x32_bf16 v[44:47], v[136:139], v[160:163], v[44:47]
	v_mfma_f32_16x16x32_bf16 v[24:27], v[128:131], v[168:171], v[24:27]
	v_mfma_f32_16x16x32_bf16 v[52:55], v[136:139], v[168:171], v[52:55]
	v_mfma_f32_16x16x32_bf16 v[32:35], v[128:131], v[176:179], v[32:35]
	v_mfma_f32_16x16x32_bf16 v[56:59], v[136:139], v[176:179], v[56:59]
	v_mfma_f32_16x16x32_bf16 v[40:43], v[128:131], v[184:187], v[40:43]
	v_mfma_f32_16x16x32_bf16 v[60:63], v[136:139], v[184:187], v[60:63]
	v_mfma_f32_16x16x32_bf16 v[16:19], v[132:135], v[164:167], v[16:19]
	v_mfma_f32_16x16x32_bf16 v[44:47], v[140:143], v[164:167], v[44:47]
	v_mfma_f32_16x16x32_bf16 v[24:27], v[132:135], v[172:175], v[24:27]
	v_mfma_f32_16x16x32_bf16 v[52:55], v[140:143], v[172:175], v[52:55]
	v_mfma_f32_16x16x32_bf16 v[32:35], v[132:135], v[180:183], v[32:35]
	v_mfma_f32_16x16x32_bf16 v[56:59], v[140:143], v[180:183], v[56:59]
	v_mfma_f32_16x16x32_bf16 v[40:43], v[132:135], v[188:191], v[40:43]
	v_mfma_f32_16x16x32_bf16 v[60:63], v[140:143], v[188:191], v[60:63]
	s_setprio 1
	s_setprio 0
	v_mfma_f32_16x16x32_bf16 v[20:23], v[144:147], v[160:163], v[20:23]
	v_mfma_f32_16x16x32_bf16 v[4:7], v[152:155], v[160:163], v[4:7]
	v_mfma_f32_16x16x32_bf16 v[28:31], v[144:147], v[168:171], v[28:31]
	v_mfma_f32_16x16x32_bf16 v[0:3], v[152:155], v[168:171], v[0:3]
	v_mfma_f32_16x16x32_bf16 v[36:39], v[144:147], v[176:179], v[36:39]
	v_mfma_f32_16x16x32_bf16 v[8:11], v[152:155], v[176:179], v[8:11]
	v_mfma_f32_16x16x32_bf16 v[48:51], v[144:147], v[184:187], v[48:51]
	v_mfma_f32_16x16x32_bf16 v[12:15], v[152:155], v[184:187], v[12:15]
	v_mfma_f32_16x16x32_bf16 v[20:23], v[148:151], v[164:167], v[20:23]
	v_mfma_f32_16x16x32_bf16 v[4:7], v[156:159], v[164:167], v[4:7]
	v_mfma_f32_16x16x32_bf16 v[28:31], v[148:151], v[172:175], v[28:31]
	v_mfma_f32_16x16x32_bf16 v[0:3], v[156:159], v[172:175], v[0:3]
	v_mfma_f32_16x16x32_bf16 v[36:39], v[148:151], v[180:183], v[36:39]
	v_mfma_f32_16x16x32_bf16 v[8:11], v[156:159], v[180:183], v[8:11]
	v_mfma_f32_16x16x32_bf16 v[48:51], v[148:151], v[188:191], v[48:51]
	v_mfma_f32_16x16x32_bf16 v[12:15], v[156:159], v[188:191], v[12:15]
	s_setprio 1
	s_barrier
	s_add_u32 s35, s35, 0x100
	s_addc_u32 s37, s37, 0
	s_cmp_ge_i32 s48, s62
	s_mov_b64 s[12:13], s[8:9]
	s_mov_b32 s28, s48
	s_cbranch_scc0 .LBB0_2049

.LBB0_2092:
	s_add_i32 s58, s8, 2
	s_add_u32 s9, s12, 0xffff0080
	s_addc_u32 s28, s13, -1
	s_add_i32 s59, 0, 0x10000
	s_cmp_eq_u32 s50, s8
	s_cselect_b32 s29, s27, s28
	s_cselect_b32 s28, s35, s9
	s_cselect_b32 s9, s54, s57
	s_cselect_b32 s8, s55, s56
	s_add_i32 s62, 0, 0x14000
	v_add_u32_e32 v152, s59, v138
	v_add_u32_e32 v168, s62, v138
	ds_read_b128 v[140:143], v152
	ds_read_b128 v[144:147], v152 offset:1024
	ds_read_b128 v[148:151], v152 offset:2048
	ds_read_b128 v[152:155], v152 offset:3072
	ds_read_b128 v[156:159], v168
	ds_read_b128 v[160:163], v168 offset:1024
	ds_read_b128 v[164:167], v168 offset:2048
	ds_read_b128 v[168:171], v168 offset:3072
	v_lshl_add_u64 v[204:205], s[12:13], 0, v[134:135]
	s_add_i32 m0, s31, 0xc000
	ds_read_b128 v[172:175], v139
	ds_read_b128 v[176:179], v139 offset:1024
	ds_read_b128 v[180:183], v139 offset:2048
	ds_read_b128 v[184:187], v139 offset:3072
	ds_read_b128 v[188:191], v139 offset:4096
	ds_read_b128 v[192:195], v139 offset:5120
	ds_read_b128 v[196:199], v139 offset:6144
	ds_read_b128 v[200:203], v139 offset:7168
	global_load_lds_dwordx4 v[204:205], off
	v_lshl_add_u64 v[204:205], s[12:13], 0, v[136:137]
	s_add_i32 m0, s31, 0xe000
	s_nop 0
	global_load_lds_dwordx4 v[204:205], off
	s_waitcnt vmcnt(8)
	s_waitcnt lgkmcnt(0)
	s_barrier
	s_setprio 0
	s_waitcnt lgkmcnt(0)
	v_mfma_f32_16x16x32_bf16 v[112:115], v[140:143], v[172:175], v[112:115]
	v_mfma_f32_16x16x32_bf16 v[116:119], v[148:151], v[172:175], v[116:119]
	v_mfma_f32_16x16x32_bf16 v[96:99], v[140:143], v[180:183], v[96:99]
	v_mfma_f32_16x16x32_bf16 v[100:103], v[148:151], v[180:183], v[100:103]
	v_mfma_f32_16x16x32_bf16 v[80:83], v[140:143], v[188:191], v[80:83]
	v_mfma_f32_16x16x32_bf16 v[84:87], v[148:151], v[188:191], v[84:87]
	v_mfma_f32_16x16x32_bf16 v[48:51], v[140:143], v[196:199], v[48:51]
	v_mfma_f32_16x16x32_bf16 v[52:55], v[148:151], v[196:199], v[52:55]
	v_mfma_f32_16x16x32_bf16 v[112:115], v[144:147], v[176:179], v[112:115]
	v_mfma_f32_16x16x32_bf16 v[116:119], v[152:155], v[176:179], v[116:119]
	v_mfma_f32_16x16x32_bf16 v[96:99], v[144:147], v[184:187], v[96:99]
	v_mfma_f32_16x16x32_bf16 v[100:103], v[152:155], v[184:187], v[100:103]
	v_mfma_f32_16x16x32_bf16 v[80:83], v[144:147], v[192:195], v[80:83]
	v_mfma_f32_16x16x32_bf16 v[84:87], v[152:155], v[192:195], v[84:87]
	v_mfma_f32_16x16x32_bf16 v[48:51], v[144:147], v[200:203], v[48:51]
	v_mfma_f32_16x16x32_bf16 v[52:55], v[152:155], v[200:203], v[52:55]
	s_setprio 1
	s_setprio 0
	v_mfma_f32_16x16x32_bf16 v[120:123], v[156:159], v[172:175], v[120:123]
	v_mfma_f32_16x16x32_bf16 v[124:127], v[164:167], v[172:175], v[124:127]
	v_mfma_f32_16x16x32_bf16 v[104:107], v[156:159], v[180:183], v[104:107]
	v_mfma_f32_16x16x32_bf16 v[108:111], v[164:167], v[180:183], v[108:111]
	v_mfma_f32_16x16x32_bf16 v[88:91], v[156:159], v[188:191], v[88:91]
	v_mfma_f32_16x16x32_bf16 v[92:95], v[164:167], v[188:191], v[92:95]
	v_mfma_f32_16x16x32_bf16 v[64:67], v[156:159], v[196:199], v[64:67]
	v_mfma_f32_16x16x32_bf16 v[68:71], v[164:167], v[196:199], v[68:71]
	v_mfma_f32_16x16x32_bf16 v[120:123], v[160:163], v[176:179], v[120:123]
	v_mfma_f32_16x16x32_bf16 v[124:127], v[168:171], v[176:179], v[124:127]
	v_mfma_f32_16x16x32_bf16 v[104:107], v[160:163], v[184:187], v[104:107]
	v_mfma_f32_16x16x32_bf16 v[108:111], v[168:171], v[184:187], v[108:111]
	v_mfma_f32_16x16x32_bf16 v[88:91], v[160:163], v[192:195], v[88:91]
	v_mfma_f32_16x16x32_bf16 v[92:95], v[168:171], v[192:195], v[92:95]
	v_mfma_f32_16x16x32_bf16 v[64:67], v[160:163], v[200:203], v[64:67]
	v_mfma_f32_16x16x32_bf16 v[68:71], v[168:171], v[200:203], v[68:71]
	s_setprio 1
	s_barrier
	s_add_i32 s59, s59, s10
	v_lshl_add_u64 v[204:205], s[8:9], 0, v[224:225]
	s_mov_b32 m0, s59
	ds_read_b128 v[172:175], v139 offset:16384
	ds_read_b128 v[176:179], v139 offset:17408
	ds_read_b128 v[180:183], v139 offset:18432
	ds_read_b128 v[184:187], v139 offset:19456
	ds_read_b128 v[188:191], v139 offset:20480
	ds_read_b128 v[192:195], v139 offset:21504
	ds_read_b128 v[196:199], v139 offset:22528
	ds_read_b128 v[200:203], v139 offset:23552
	global_load_lds_dwordx4 v[204:205], off
	s_add_i32 m0, s59, 0x2000
	s_add_u32 s60, s8, 0x10000
	v_lshl_add_u64 v[206:207], s[8:9], 0, v[128:129]
	s_addc_u32 s61, s9, 0
	s_add_i32 s59, s62, s10
	global_load_lds_dwordx4 v[206:207], off
	v_lshl_add_u64 v[208:209], s[60:61], 0, v[224:225]
	s_mov_b32 m0, s59
	v_lshl_add_u64 v[210:211], s[28:29], 0, v[130:131]
	global_load_lds_dwordx4 v[208:209], off
	v_lshl_add_u64 v[208:209], s[60:61], 0, v[128:129]
	s_add_i32 m0, s59, 0x2000
	s_nop 0
	global_load_lds_dwordx4 v[208:209], off
	v_lshl_add_u64 v[208:209], s[28:29], 0, v[132:133]
	s_mov_b32 m0, s31
	s_nop 0
	global_load_lds_dwordx4 v[208:209], off
	s_mov_b32 m0, s33
	s_nop 0
	global_load_lds_dwordx4 v[210:211], off
	s_waitcnt vmcnt(8)
	s_waitcnt lgkmcnt(0)
	s_barrier
	s_setprio 0
	s_waitcnt lgkmcnt(0)
	v_mfma_f32_16x16x32_bf16 v[56:59], v[140:143], v[172:175], v[56:59]
	v_mfma_f32_16x16x32_bf16 v[60:63], v[148:151], v[172:175], v[60:63]
	v_mfma_f32_16x16x32_bf16 v[32:35], v[140:143], v[180:183], v[32:35]
	v_mfma_f32_16x16x32_bf16 v[36:39], v[148:151], v[180:183], v[36:39]
	v_mfma_f32_16x16x32_bf16 v[16:19], v[140:143], v[188:191], v[16:19]
	v_mfma_f32_16x16x32_bf16 v[20:23], v[148:151], v[188:191], v[20:23]
	v_mfma_f32_16x16x32_bf16 v[0:3], v[140:143], v[196:199], v[0:3]
	v_mfma_f32_16x16x32_bf16 v[4:7], v[148:151], v[196:199], v[4:7]
	v_mfma_f32_16x16x32_bf16 v[56:59], v[144:147], v[176:179], v[56:59]
	v_mfma_f32_16x16x32_bf16 v[60:63], v[152:155], v[176:179], v[60:63]
	v_mfma_f32_16x16x32_bf16 v[32:35], v[144:147], v[184:187], v[32:35]
	v_mfma_f32_16x16x32_bf16 v[36:39], v[152:155], v[184:187], v[36:39]
	v_mfma_f32_16x16x32_bf16 v[16:19], v[144:147], v[192:195], v[16:19]
	v_mfma_f32_16x16x32_bf16 v[20:23], v[152:155], v[192:195], v[20:23]
	v_mfma_f32_16x16x32_bf16 v[0:3], v[144:147], v[200:203], v[0:3]
	v_mfma_f32_16x16x32_bf16 v[4:7], v[152:155], v[200:203], v[4:7]
	s_setprio 1
	s_setprio 0
	v_mfma_f32_16x16x32_bf16 v[72:75], v[156:159], v[172:175], v[72:75]
	v_mfma_f32_16x16x32_bf16 v[76:79], v[164:167], v[172:175], v[76:79]
	v_mfma_f32_16x16x32_bf16 v[40:43], v[156:159], v[180:183], v[40:43]
	v_mfma_f32_16x16x32_bf16 v[44:47], v[164:167], v[180:183], v[44:47]
	v_mfma_f32_16x16x32_bf16 v[24:27], v[156:159], v[188:191], v[24:27]
	v_mfma_f32_16x16x32_bf16 v[28:31], v[164:167], v[188:191], v[28:31]
	v_mfma_f32_16x16x32_bf16 v[8:11], v[156:159], v[196:199], v[8:11]
	v_mfma_f32_16x16x32_bf16 v[12:15], v[164:167], v[196:199], v[12:15]
	v_mfma_f32_16x16x32_bf16 v[72:75], v[160:163], v[176:179], v[72:75]
	v_mfma_f32_16x16x32_bf16 v[76:79], v[168:171], v[176:179], v[76:79]
	v_mfma_f32_16x16x32_bf16 v[40:43], v[160:163], v[184:187], v[40:43]
	v_mfma_f32_16x16x32_bf16 v[44:47], v[168:171], v[184:187], v[44:47]
	v_mfma_f32_16x16x32_bf16 v[24:27], v[160:163], v[192:195], v[24:27]
	v_mfma_f32_16x16x32_bf16 v[28:31], v[168:171], v[192:195], v[28:31]
	v_mfma_f32_16x16x32_bf16 v[8:11], v[160:163], v[200:203], v[8:11]
	v_mfma_f32_16x16x32_bf16 v[12:15], v[168:171], v[200:203], v[12:15]
	s_setprio 1
	s_barrier
	s_add_i32 s59, 0, 0x18000
	s_add_i32 s60, 0, 0x1c000
	v_add_u32_e32 v152, s59, v138
	v_add_u32_e32 v168, s60, v138
	ds_read_b128 v[140:143], v152
	ds_read_b128 v[144:147], v152 offset:1024
	ds_read_b128 v[148:151], v152 offset:2048
	ds_read_b128 v[152:155], v152 offset:3072
	ds_read_b128 v[156:159], v168
	ds_read_b128 v[160:163], v168 offset:1024
	ds_read_b128 v[164:167], v168 offset:2048
	ds_read_b128 v[168:171], v168 offset:3072
	s_add_u32 s28, s28, 0x10000
	s_addc_u32 s29, s29, 0
	s_mov_b32 m0, s44
	v_lshl_add_u64 v[212:213], s[28:29], 0, v[132:133]
	ds_read_b128 v[172:175], v139 offset:32768
	ds_read_b128 v[176:179], v139 offset:33792
	ds_read_b128 v[180:183], v139 offset:34816
	ds_read_b128 v[184:187], v139 offset:35840
	ds_read_b128 v[188:191], v139 offset:36864
	ds_read_b128 v[192:195], v139 offset:37888
	ds_read_b128 v[196:199], v139 offset:38912
	ds_read_b128 v[200:203], v139 offset:39936
	global_load_lds_dwordx4 v[212:213], off
	v_lshl_add_u64 v[212:213], s[28:29], 0, v[130:131]
	s_mov_b32 m0, s45
	s_nop 0
	global_load_lds_dwordx4 v[212:213], off
	s_waitcnt vmcnt(8)
	s_waitcnt lgkmcnt(0)
	s_barrier
	s_setprio 0
	s_waitcnt lgkmcnt(0)
	v_mfma_f32_16x16x32_bf16 v[112:115], v[140:143], v[172:175], v[112:115]
	v_mfma_f32_16x16x32_bf16 v[116:119], v[148:151], v[172:175], v[116:119]
	v_mfma_f32_16x16x32_bf16 v[96:99], v[140:143], v[180:183], v[96:99]
	v_mfma_f32_16x16x32_bf16 v[100:103], v[148:151], v[180:183], v[100:103]
	v_mfma_f32_16x16x32_bf16 v[80:83], v[140:143], v[188:191], v[80:83]
	v_mfma_f32_16x16x32_bf16 v[84:87], v[148:151], v[188:191], v[84:87]
	v_mfma_f32_16x16x32_bf16 v[48:51], v[140:143], v[196:199], v[48:51]
	v_mfma_f32_16x16x32_bf16 v[52:55], v[148:151], v[196:199], v[52:55]
	v_mfma_f32_16x16x32_bf16 v[112:115], v[144:147], v[176:179], v[112:115]
	v_mfma_f32_16x16x32_bf16 v[116:119], v[152:155], v[176:179], v[116:119]
	v_mfma_f32_16x16x32_bf16 v[96:99], v[144:147], v[184:187], v[96:99]
	v_mfma_f32_16x16x32_bf16 v[100:103], v[152:155], v[184:187], v[100:103]
	v_mfma_f32_16x16x32_bf16 v[80:83], v[144:147], v[192:195], v[80:83]
	v_mfma_f32_16x16x32_bf16 v[84:87], v[152:155], v[192:195], v[84:87]
	v_mfma_f32_16x16x32_bf16 v[48:51], v[144:147], v[200:203], v[48:51]
	v_mfma_f32_16x16x32_bf16 v[52:55], v[152:155], v[200:203], v[52:55]
	s_setprio 1
	s_setprio 0
	v_mfma_f32_16x16x32_bf16 v[120:123], v[156:159], v[172:175], v[120:123]
	v_mfma_f32_16x16x32_bf16 v[124:127], v[164:167], v[172:175], v[124:127]
	v_mfma_f32_16x16x32_bf16 v[104:107], v[156:159], v[180:183], v[104:107]
	v_mfma_f32_16x16x32_bf16 v[108:111], v[164:167], v[180:183], v[108:111]
	v_mfma_f32_16x16x32_bf16 v[88:91], v[156:159], v[188:191], v[88:91]
	v_mfma_f32_16x16x32_bf16 v[92:95], v[164:167], v[188:191], v[92:95]
	v_mfma_f32_16x16x32_bf16 v[64:67], v[156:159], v[196:199], v[64:67]
	v_mfma_f32_16x16x32_bf16 v[68:71], v[164:167], v[196:199], v[68:71]
	v_mfma_f32_16x16x32_bf16 v[120:123], v[160:163], v[176:179], v[120:123]
	v_mfma_f32_16x16x32_bf16 v[124:127], v[168:171], v[176:179], v[124:127]
	v_mfma_f32_16x16x32_bf16 v[104:107], v[160:163], v[184:187], v[104:107]
	v_mfma_f32_16x16x32_bf16 v[108:111], v[168:171], v[184:187], v[108:111]
	v_mfma_f32_16x16x32_bf16 v[88:91], v[160:163], v[192:195], v[88:91]
	v_mfma_f32_16x16x32_bf16 v[92:95], v[168:171], v[192:195], v[92:95]
	v_mfma_f32_16x16x32_bf16 v[64:67], v[160:163], v[200:203], v[64:67]
	v_mfma_f32_16x16x32_bf16 v[68:71], v[168:171], v[200:203], v[68:71]
	s_setprio 1
	s_barrier
	s_add_i32 s28, s59, s10
	v_lshl_add_u64 v[204:205], v[204:205], 0, s[24:25]
	s_mov_b32 m0, s28
	ds_read_b128 v[172:175], v139 offset:49152
	ds_read_b128 v[176:179], v139 offset:50176
	ds_read_b128 v[180:183], v139 offset:51200
	ds_read_b128 v[184:187], v139 offset:52224
	ds_read_b128 v[188:191], v139 offset:53248
	ds_read_b128 v[192:195], v139 offset:54272
	ds_read_b128 v[196:199], v139 offset:55296
	ds_read_b128 v[200:203], v139 offset:56320
	global_load_lds_dwordx4 v[204:205], off
	s_add_i32 m0, s28, 0x2000
	s_add_u32 s8, s8, 0x10080
	v_lshl_add_u64 v[204:205], v[206:207], 0, s[24:25]
	s_addc_u32 s9, s9, 0
	s_add_i32 s28, s60, s10
	global_load_lds_dwordx4 v[204:205], off
	v_lshl_add_u64 v[204:205], s[8:9], 0, v[224:225]
	s_mov_b32 m0, s28
	s_nop 0
	global_load_lds_dwordx4 v[204:205], off
	v_lshl_add_u64 v[204:205], s[8:9], 0, v[128:129]
	s_add_i32 m0, s28, 0x2000
	s_nop 0
	global_load_lds_dwordx4 v[204:205], off
	v_lshl_add_u64 v[204:205], v[208:209], 0, s[24:25]
	s_mov_b32 m0, s48
	s_nop 0
	global_load_lds_dwordx4 v[204:205], off
	v_lshl_add_u64 v[204:205], v[210:211], 0, s[24:25]
	s_mov_b32 m0, s49
	s_nop 0
	global_load_lds_dwordx4 v[204:205], off
	s_waitcnt vmcnt(8)
	s_waitcnt lgkmcnt(0)
	s_barrier
	s_setprio 0
	s_waitcnt lgkmcnt(0)
	v_mfma_f32_16x16x32_bf16 v[56:59], v[140:143], v[172:175], v[56:59]
	v_mfma_f32_16x16x32_bf16 v[60:63], v[148:151], v[172:175], v[60:63]
	v_mfma_f32_16x16x32_bf16 v[32:35], v[140:143], v[180:183], v[32:35]
	v_mfma_f32_16x16x32_bf16 v[36:39], v[148:151], v[180:183], v[36:39]
	v_mfma_f32_16x16x32_bf16 v[16:19], v[140:143], v[188:191], v[16:19]
	v_mfma_f32_16x16x32_bf16 v[20:23], v[148:151], v[188:191], v[20:23]
	v_mfma_f32_16x16x32_bf16 v[0:3], v[140:143], v[196:199], v[0:3]
	v_mfma_f32_16x16x32_bf16 v[4:7], v[148:151], v[196:199], v[4:7]
	v_mfma_f32_16x16x32_bf16 v[56:59], v[144:147], v[176:179], v[56:59]
	v_mfma_f32_16x16x32_bf16 v[60:63], v[152:155], v[176:179], v[60:63]
	v_mfma_f32_16x16x32_bf16 v[32:35], v[144:147], v[184:187], v[32:35]
	v_mfma_f32_16x16x32_bf16 v[36:39], v[152:155], v[184:187], v[36:39]
	v_mfma_f32_16x16x32_bf16 v[16:19], v[144:147], v[192:195], v[16:19]
	v_mfma_f32_16x16x32_bf16 v[20:23], v[152:155], v[192:195], v[20:23]
	v_mfma_f32_16x16x32_bf16 v[0:3], v[144:147], v[200:203], v[0:3]
	v_mfma_f32_16x16x32_bf16 v[4:7], v[152:155], v[200:203], v[4:7]
	s_setprio 1
	s_setprio 0
	v_mfma_f32_16x16x32_bf16 v[72:75], v[156:159], v[172:175], v[72:75]
	v_mfma_f32_16x16x32_bf16 v[76:79], v[164:167], v[172:175], v[76:79]
	v_mfma_f32_16x16x32_bf16 v[40:43], v[156:159], v[180:183], v[40:43]
	v_mfma_f32_16x16x32_bf16 v[44:47], v[164:167], v[180:183], v[44:47]
	v_mfma_f32_16x16x32_bf16 v[24:27], v[156:159], v[188:191], v[24:27]
	v_mfma_f32_16x16x32_bf16 v[28:31], v[164:167], v[188:191], v[28:31]
	v_mfma_f32_16x16x32_bf16 v[8:11], v[156:159], v[196:199], v[8:11]
	v_mfma_f32_16x16x32_bf16 v[12:15], v[164:167], v[196:199], v[12:15]
	v_mfma_f32_16x16x32_bf16 v[72:75], v[160:163], v[176:179], v[72:75]
	v_mfma_f32_16x16x32_bf16 v[76:79], v[168:171], v[176:179], v[76:79]
	v_mfma_f32_16x16x32_bf16 v[40:43], v[160:163], v[184:187], v[40:43]
	v_mfma_f32_16x16x32_bf16 v[44:47], v[168:171], v[184:187], v[44:47]
	v_mfma_f32_16x16x32_bf16 v[24:27], v[160:163], v[192:195], v[24:27]
	v_mfma_f32_16x16x32_bf16 v[28:31], v[168:171], v[192:195], v[28:31]
	v_mfma_f32_16x16x32_bf16 v[8:11], v[160:163], v[200:203], v[8:11]
	v_mfma_f32_16x16x32_bf16 v[12:15], v[168:171], v[200:203], v[12:15]
	s_setprio 1
	s_barrier
	s_add_u32 s12, s12, 0x100
	s_addc_u32 s13, s13, 0
	s_add_u32 s56, s56, 0x100
	s_addc_u32 s57, s57, 0
	s_cmp_ge_i32 s58, s47
	s_mov_b32 s8, s58
	s_cbranch_scc0 .LBB0_2092
	s_mov_b64 s[56:57], 0x400000
	s_mov_b64 s[58:59], 0x3fffff
	s_mov_b64 s[60:61], 0x20000

.LBB0_2239:
	s_add_i32 s30, s28, 2
	s_add_u32 s8, s12, 0x100
	s_addc_u32 s9, s13, 0
	s_add_i32 s31, 0, 0x10000
	s_cmp_eq_u32 s63, s28
	s_cselect_b32 s49, s43, s9
	s_cselect_b32 s48, s42, s8
	s_cselect_b32 s29, s47, s7
	s_cselect_b32 s28, s46, s3
	s_add_i32 s33, 0, 0x14000
	v_add_u32_e32 v100, s31, v230
	v_add_u32_e32 v124, s33, v230
	ds_read_b128 v[84:87], v100
	ds_read_b128 v[88:91], v100 offset:1024
	ds_read_b128 v[96:99], v100 offset:2048
	ds_read_b128 v[100:103], v100 offset:3072
	ds_read_b128 v[112:115], v124
	ds_read_b128 v[116:119], v124 offset:1024
	ds_read_b128 v[120:123], v124 offset:2048
	ds_read_b128 v[124:127], v124 offset:3072
	v_lshl_add_u64 v[202:203], s[12:13], 0, v[198:199]
	s_add_i32 m0, s56, 0xc000
	ds_read_b128 v[160:163], v231
	ds_read_b128 v[164:167], v231 offset:1024
	ds_read_b128 v[168:171], v231 offset:2048
	ds_read_b128 v[172:175], v231 offset:3072
	ds_read_b128 v[176:179], v231 offset:4096
	ds_read_b128 v[180:183], v231 offset:5120
	ds_read_b128 v[184:187], v231 offset:6144
	ds_read_b128 v[188:191], v231 offset:7168
	global_load_lds_dwordx4 v[202:203], off
	v_lshl_add_u64 v[202:203], s[12:13], 0, v[200:201]
	s_add_i32 m0, s56, 0xe000
	s_nop 0
	global_load_lds_dwordx4 v[202:203], off
	s_waitcnt vmcnt(8)
	s_waitcnt lgkmcnt(0)
	s_barrier
	s_setprio 0
	s_waitcnt lgkmcnt(0)
	v_mfma_f32_16x16x32_bf16 v[152:155], v[84:87], v[160:163], v[152:155]
	v_mfma_f32_16x16x32_bf16 v[156:159], v[96:99], v[160:163], v[156:159]
	v_mfma_f32_16x16x32_bf16 v[140:143], v[84:87], v[168:171], v[140:143]
	v_mfma_f32_16x16x32_bf16 v[136:139], v[96:99], v[168:171], v[136:139]
	v_mfma_f32_16x16x32_bf16 v[108:111], v[84:87], v[176:179], v[108:111]
	v_mfma_f32_16x16x32_bf16 v[104:107], v[96:99], v[176:179], v[104:107]
	v_mfma_f32_16x16x32_bf16 v[76:79], v[84:87], v[184:187], v[76:79]
	v_mfma_f32_16x16x32_bf16 v[72:75], v[96:99], v[184:187], v[72:75]
	v_mfma_f32_16x16x32_bf16 v[152:155], v[88:91], v[164:167], v[152:155]
	v_mfma_f32_16x16x32_bf16 v[156:159], v[100:103], v[164:167], v[156:159]
	v_mfma_f32_16x16x32_bf16 v[140:143], v[88:91], v[172:175], v[140:143]
	v_mfma_f32_16x16x32_bf16 v[136:139], v[100:103], v[172:175], v[136:139]
	v_mfma_f32_16x16x32_bf16 v[108:111], v[88:91], v[180:183], v[108:111]
	v_mfma_f32_16x16x32_bf16 v[104:107], v[100:103], v[180:183], v[104:107]
	v_mfma_f32_16x16x32_bf16 v[76:79], v[88:91], v[188:191], v[76:79]
	v_mfma_f32_16x16x32_bf16 v[72:75], v[100:103], v[188:191], v[72:75]
	s_setprio 1
	s_setprio 0
	v_mfma_f32_16x16x32_bf16 v[148:151], v[112:115], v[160:163], v[148:151]
	v_mfma_f32_16x16x32_bf16 v[144:147], v[120:123], v[160:163], v[144:147]
	v_mfma_f32_16x16x32_bf16 v[132:135], v[112:115], v[168:171], v[132:135]
	v_mfma_f32_16x16x32_bf16 v[128:131], v[120:123], v[168:171], v[128:131]
	v_mfma_f32_16x16x32_bf16 v[92:95], v[112:115], v[176:179], v[92:95]
	v_mfma_f32_16x16x32_bf16 v[80:83], v[120:123], v[176:179], v[80:83]
	v_mfma_f32_16x16x32_bf16 v[68:71], v[112:115], v[184:187], v[68:71]
	v_mfma_f32_16x16x32_bf16 v[64:67], v[120:123], v[184:187], v[64:67]
	v_mfma_f32_16x16x32_bf16 v[148:151], v[116:119], v[164:167], v[148:151]
	v_mfma_f32_16x16x32_bf16 v[144:147], v[124:127], v[164:167], v[144:147]
	v_mfma_f32_16x16x32_bf16 v[132:135], v[116:119], v[172:175], v[132:135]
	v_mfma_f32_16x16x32_bf16 v[128:131], v[124:127], v[172:175], v[128:131]
	v_mfma_f32_16x16x32_bf16 v[92:95], v[116:119], v[180:183], v[92:95]
	v_mfma_f32_16x16x32_bf16 v[80:83], v[124:127], v[180:183], v[80:83]
	v_mfma_f32_16x16x32_bf16 v[68:71], v[116:119], v[188:191], v[68:71]
	v_mfma_f32_16x16x32_bf16 v[64:67], v[124:127], v[188:191], v[64:67]
	s_setprio 1
	s_barrier
	s_add_i32 s12, s31, s54
	v_lshl_add_u64 v[202:203], s[28:29], 0, v[224:225]
	s_mov_b32 m0, s12
	ds_read_b128 v[160:163], v231 offset:16384
	ds_read_b128 v[164:167], v231 offset:17408
	ds_read_b128 v[168:171], v231 offset:18432
	ds_read_b128 v[172:175], v231 offset:19456
	ds_read_b128 v[176:179], v231 offset:20480
	ds_read_b128 v[180:183], v231 offset:21504
	ds_read_b128 v[184:187], v231 offset:22528
	ds_read_b128 v[188:191], v231 offset:23552
	global_load_lds_dwordx4 v[202:203], off
	s_add_i32 m0, s12, 0x2000
	s_add_u32 s12, s28, 0x158000
	v_lshl_add_u64 v[204:205], s[28:29], 0, v[192:193]
	s_addc_u32 s13, s29, 0
	s_add_i32 s31, s33, s54
	global_load_lds_dwordx4 v[204:205], off
	v_lshl_add_u64 v[206:207], s[12:13], 0, v[224:225]
	s_mov_b32 m0, s31
	v_lshl_add_u64 v[208:209], s[48:49], 0, v[194:195]
	global_load_lds_dwordx4 v[206:207], off
	v_lshl_add_u64 v[206:207], s[12:13], 0, v[192:193]
	s_add_i32 m0, s31, 0x2000
	s_nop 0
	global_load_lds_dwordx4 v[206:207], off
	v_lshl_add_u64 v[206:207], s[48:49], 0, v[196:197]
	s_mov_b32 m0, s56
	s_nop 0
	global_load_lds_dwordx4 v[206:207], off
	s_mov_b32 m0, s57
	s_nop 0
	global_load_lds_dwordx4 v[208:209], off
	s_waitcnt vmcnt(8)
	s_waitcnt lgkmcnt(0)
	s_barrier
	s_setprio 0
	s_waitcnt lgkmcnt(0)
	v_mfma_f32_16x16x32_bf16 v[60:63], v[84:87], v[160:163], v[60:63]
	v_mfma_f32_16x16x32_bf16 v[56:59], v[96:99], v[160:163], v[56:59]
	v_mfma_f32_16x16x32_bf16 v[44:47], v[84:87], v[168:171], v[44:47]
	v_mfma_f32_16x16x32_bf16 v[40:43], v[96:99], v[168:171], v[40:43]
	v_mfma_f32_16x16x32_bf16 v[28:31], v[84:87], v[176:179], v[28:31]
	v_mfma_f32_16x16x32_bf16 v[24:27], v[96:99], v[176:179], v[24:27]
	v_mfma_f32_16x16x32_bf16 v[12:15], v[84:87], v[184:187], v[12:15]
	v_mfma_f32_16x16x32_bf16 v[8:11], v[96:99], v[184:187], v[8:11]
	v_mfma_f32_16x16x32_bf16 v[60:63], v[88:91], v[164:167], v[60:63]
	v_mfma_f32_16x16x32_bf16 v[56:59], v[100:103], v[164:167], v[56:59]
	v_mfma_f32_16x16x32_bf16 v[44:47], v[88:91], v[172:175], v[44:47]
	v_mfma_f32_16x16x32_bf16 v[40:43], v[100:103], v[172:175], v[40:43]
	v_mfma_f32_16x16x32_bf16 v[28:31], v[88:91], v[180:183], v[28:31]
	v_mfma_f32_16x16x32_bf16 v[24:27], v[100:103], v[180:183], v[24:27]
	v_mfma_f32_16x16x32_bf16 v[12:15], v[88:91], v[188:191], v[12:15]
	v_mfma_f32_16x16x32_bf16 v[8:11], v[100:103], v[188:191], v[8:11]
	s_setprio 1
	s_setprio 0
	v_mfma_f32_16x16x32_bf16 v[52:55], v[112:115], v[160:163], v[52:55]
	v_mfma_f32_16x16x32_bf16 v[48:51], v[120:123], v[160:163], v[48:51]
	v_mfma_f32_16x16x32_bf16 v[36:39], v[112:115], v[168:171], v[36:39]
	v_mfma_f32_16x16x32_bf16 v[32:35], v[120:123], v[168:171], v[32:35]
	v_mfma_f32_16x16x32_bf16 v[20:23], v[112:115], v[176:179], v[20:23]
	v_mfma_f32_16x16x32_bf16 v[16:19], v[120:123], v[176:179], v[16:19]
	v_mfma_f32_16x16x32_bf16 v[4:7], v[112:115], v[184:187], v[4:7]
	v_mfma_f32_16x16x32_bf16 v[0:3], v[120:123], v[184:187], v[0:3]
	v_mfma_f32_16x16x32_bf16 v[52:55], v[116:119], v[164:167], v[52:55]
	v_mfma_f32_16x16x32_bf16 v[48:51], v[124:127], v[164:167], v[48:51]
	v_mfma_f32_16x16x32_bf16 v[36:39], v[116:119], v[172:175], v[36:39]
	v_mfma_f32_16x16x32_bf16 v[32:35], v[124:127], v[172:175], v[32:35]
	v_mfma_f32_16x16x32_bf16 v[20:23], v[116:119], v[180:183], v[20:23]
	v_mfma_f32_16x16x32_bf16 v[16:19], v[124:127], v[180:183], v[16:19]
	v_mfma_f32_16x16x32_bf16 v[4:7], v[116:119], v[188:191], v[4:7]
	v_mfma_f32_16x16x32_bf16 v[0:3], v[124:127], v[188:191], v[0:3]
	s_setprio 1
	s_barrier
	s_add_i32 s31, 0, 0x18000
	s_add_i32 s33, 0, 0x1c000
	v_add_u32_e32 v100, s31, v230
	v_add_u32_e32 v124, s33, v230
	ds_read_b128 v[84:87], v100
	ds_read_b128 v[88:91], v100 offset:1024
	ds_read_b128 v[96:99], v100 offset:2048
	ds_read_b128 v[100:103], v100 offset:3072
	ds_read_b128 v[112:115], v124
	ds_read_b128 v[116:119], v124 offset:1024
	ds_read_b128 v[120:123], v124 offset:2048
	ds_read_b128 v[124:127], v124 offset:3072
	s_add_u32 s12, s48, 0x158000
	s_addc_u32 s13, s49, 0
	s_mov_b32 m0, s58
	v_lshl_add_u64 v[210:211], s[12:13], 0, v[196:197]
	ds_read_b128 v[160:163], v231 offset:32768
	ds_read_b128 v[164:167], v231 offset:33792
	ds_read_b128 v[168:171], v231 offset:34816
	ds_read_b128 v[172:175], v231 offset:35840
	ds_read_b128 v[176:179], v231 offset:36864
	ds_read_b128 v[180:183], v231 offset:37888
	ds_read_b128 v[184:187], v231 offset:38912
	ds_read_b128 v[188:191], v231 offset:39936
	global_load_lds_dwordx4 v[210:211], off
	v_lshl_add_u64 v[210:211], s[12:13], 0, v[194:195]
	s_mov_b32 m0, s59
	s_nop 0
	global_load_lds_dwordx4 v[210:211], off
	s_waitcnt vmcnt(8)
	s_waitcnt lgkmcnt(0)
	s_barrier
	s_setprio 0
	s_waitcnt lgkmcnt(0)
	v_mfma_f32_16x16x32_bf16 v[152:155], v[84:87], v[160:163], v[152:155]
	v_mfma_f32_16x16x32_bf16 v[156:159], v[96:99], v[160:163], v[156:159]
	v_mfma_f32_16x16x32_bf16 v[140:143], v[84:87], v[168:171], v[140:143]
	v_mfma_f32_16x16x32_bf16 v[136:139], v[96:99], v[168:171], v[136:139]
	v_mfma_f32_16x16x32_bf16 v[108:111], v[84:87], v[176:179], v[108:111]
	v_mfma_f32_16x16x32_bf16 v[104:107], v[96:99], v[176:179], v[104:107]
	v_mfma_f32_16x16x32_bf16 v[76:79], v[84:87], v[184:187], v[76:79]
	v_mfma_f32_16x16x32_bf16 v[72:75], v[96:99], v[184:187], v[72:75]
	v_mfma_f32_16x16x32_bf16 v[152:155], v[88:91], v[164:167], v[152:155]
	v_mfma_f32_16x16x32_bf16 v[156:159], v[100:103], v[164:167], v[156:159]
	v_mfma_f32_16x16x32_bf16 v[140:143], v[88:91], v[172:175], v[140:143]
	v_mfma_f32_16x16x32_bf16 v[136:139], v[100:103], v[172:175], v[136:139]
	v_mfma_f32_16x16x32_bf16 v[108:111], v[88:91], v[180:183], v[108:111]
	v_mfma_f32_16x16x32_bf16 v[104:107], v[100:103], v[180:183], v[104:107]
	v_mfma_f32_16x16x32_bf16 v[76:79], v[88:91], v[188:191], v[76:79]
	v_mfma_f32_16x16x32_bf16 v[72:75], v[100:103], v[188:191], v[72:75]
	s_setprio 1
	s_setprio 0
	v_mfma_f32_16x16x32_bf16 v[148:151], v[112:115], v[160:163], v[148:151]
	v_mfma_f32_16x16x32_bf16 v[144:147], v[120:123], v[160:163], v[144:147]
	v_mfma_f32_16x16x32_bf16 v[132:135], v[112:115], v[168:171], v[132:135]
	v_mfma_f32_16x16x32_bf16 v[128:131], v[120:123], v[168:171], v[128:131]
	v_mfma_f32_16x16x32_bf16 v[92:95], v[112:115], v[176:179], v[92:95]
	v_mfma_f32_16x16x32_bf16 v[80:83], v[120:123], v[176:179], v[80:83]
	v_mfma_f32_16x16x32_bf16 v[68:71], v[112:115], v[184:187], v[68:71]
	v_mfma_f32_16x16x32_bf16 v[64:67], v[120:123], v[184:187], v[64:67]
	v_mfma_f32_16x16x32_bf16 v[148:151], v[116:119], v[164:167], v[148:151]
	v_mfma_f32_16x16x32_bf16 v[144:147], v[124:127], v[164:167], v[144:147]
	v_mfma_f32_16x16x32_bf16 v[132:135], v[116:119], v[172:175], v[132:135]
	v_mfma_f32_16x16x32_bf16 v[128:131], v[124:127], v[172:175], v[128:131]
	v_mfma_f32_16x16x32_bf16 v[92:95], v[116:119], v[180:183], v[92:95]
	v_mfma_f32_16x16x32_bf16 v[80:83], v[124:127], v[180:183], v[80:83]
	v_mfma_f32_16x16x32_bf16 v[68:71], v[116:119], v[188:191], v[68:71]
	v_mfma_f32_16x16x32_bf16 v[64:67], v[124:127], v[188:191], v[64:67]
	s_setprio 1
	s_barrier
	s_add_i32 s12, s31, s54
	v_lshl_add_u64 v[202:203], v[202:203], 0, s[24:25]
	s_mov_b32 m0, s12
	ds_read_b128 v[160:163], v231 offset:49152
	ds_read_b128 v[164:167], v231 offset:50176
	ds_read_b128 v[168:171], v231 offset:51200
	ds_read_b128 v[172:175], v231 offset:52224
	ds_read_b128 v[176:179], v231 offset:53248
	ds_read_b128 v[180:183], v231 offset:54272
	ds_read_b128 v[184:187], v231 offset:55296
	ds_read_b128 v[188:191], v231 offset:56320
	global_load_lds_dwordx4 v[202:203], off
	s_add_i32 m0, s12, 0x2000
	s_add_u32 s12, s28, 0x158080
	v_lshl_add_u64 v[202:203], v[204:205], 0, s[24:25]
	s_addc_u32 s13, s29, 0
	s_add_i32 s28, s33, s54
	global_load_lds_dwordx4 v[202:203], off
	v_lshl_add_u64 v[202:203], s[12:13], 0, v[224:225]
	s_mov_b32 m0, s28
	s_nop 0
	global_load_lds_dwordx4 v[202:203], off
	v_lshl_add_u64 v[202:203], s[12:13], 0, v[192:193]
	s_add_i32 m0, s28, 0x2000
	s_nop 0
	global_load_lds_dwordx4 v[202:203], off
	v_lshl_add_u64 v[202:203], v[206:207], 0, s[24:25]
	s_mov_b32 m0, s61
	s_nop 0
	global_load_lds_dwordx4 v[202:203], off
	v_lshl_add_u64 v[202:203], v[208:209], 0, s[24:25]
	s_mov_b32 m0, s62
	s_nop 0
	global_load_lds_dwordx4 v[202:203], off
	s_waitcnt vmcnt(8)
	s_waitcnt lgkmcnt(0)
	s_barrier
	s_setprio 0
	s_waitcnt lgkmcnt(0)
	v_mfma_f32_16x16x32_bf16 v[60:63], v[84:87], v[160:163], v[60:63]
	v_mfma_f32_16x16x32_bf16 v[56:59], v[96:99], v[160:163], v[56:59]
	v_mfma_f32_16x16x32_bf16 v[44:47], v[84:87], v[168:171], v[44:47]
	v_mfma_f32_16x16x32_bf16 v[40:43], v[96:99], v[168:171], v[40:43]
	v_mfma_f32_16x16x32_bf16 v[28:31], v[84:87], v[176:179], v[28:31]
	v_mfma_f32_16x16x32_bf16 v[24:27], v[96:99], v[176:179], v[24:27]
	v_mfma_f32_16x16x32_bf16 v[12:15], v[84:87], v[184:187], v[12:15]
	v_mfma_f32_16x16x32_bf16 v[8:11], v[96:99], v[184:187], v[8:11]
	v_mfma_f32_16x16x32_bf16 v[60:63], v[88:91], v[164:167], v[60:63]
	v_mfma_f32_16x16x32_bf16 v[56:59], v[100:103], v[164:167], v[56:59]
	v_mfma_f32_16x16x32_bf16 v[44:47], v[88:91], v[172:175], v[44:47]
	v_mfma_f32_16x16x32_bf16 v[40:43], v[100:103], v[172:175], v[40:43]
	v_mfma_f32_16x16x32_bf16 v[28:31], v[88:91], v[180:183], v[28:31]
	v_mfma_f32_16x16x32_bf16 v[24:27], v[100:103], v[180:183], v[24:27]
	v_mfma_f32_16x16x32_bf16 v[12:15], v[88:91], v[188:191], v[12:15]
	v_mfma_f32_16x16x32_bf16 v[8:11], v[100:103], v[188:191], v[8:11]
	s_setprio 1
	s_setprio 0
	v_mfma_f32_16x16x32_bf16 v[52:55], v[112:115], v[160:163], v[52:55]
	v_mfma_f32_16x16x32_bf16 v[48:51], v[120:123], v[160:163], v[48:51]
	v_mfma_f32_16x16x32_bf16 v[36:39], v[112:115], v[168:171], v[36:39]
	v_mfma_f32_16x16x32_bf16 v[32:35], v[120:123], v[168:171], v[32:35]
	v_mfma_f32_16x16x32_bf16 v[20:23], v[112:115], v[176:179], v[20:23]
	v_mfma_f32_16x16x32_bf16 v[16:19], v[120:123], v[176:179], v[16:19]
	v_mfma_f32_16x16x32_bf16 v[4:7], v[112:115], v[184:187], v[4:7]
	v_mfma_f32_16x16x32_bf16 v[0:3], v[120:123], v[184:187], v[0:3]
	v_mfma_f32_16x16x32_bf16 v[52:55], v[116:119], v[164:167], v[52:55]
	v_mfma_f32_16x16x32_bf16 v[48:51], v[124:127], v[164:167], v[48:51]
	v_mfma_f32_16x16x32_bf16 v[36:39], v[116:119], v[172:175], v[36:39]
	v_mfma_f32_16x16x32_bf16 v[32:35], v[124:127], v[172:175], v[32:35]
	v_mfma_f32_16x16x32_bf16 v[20:23], v[116:119], v[180:183], v[20:23]
	v_mfma_f32_16x16x32_bf16 v[16:19], v[124:127], v[180:183], v[16:19]
	v_mfma_f32_16x16x32_bf16 v[4:7], v[116:119], v[188:191], v[4:7]
	v_mfma_f32_16x16x32_bf16 v[0:3], v[124:127], v[188:191], v[0:3]
	s_setprio 1
	s_barrier
	s_add_u32 s3, s3, 0x100
	s_addc_u32 s7, s7, 0
	s_cmp_ge_i32 s30, s60
	s_mov_b64 s[12:13], s[8:9]
	s_mov_b32 s28, s30
	s_cbranch_scc0 .LBB0_2239
	v_readlane_b32 s48, v253, 35
	v_readlane_b32 s49, v253, 36
	s_and_b64 vcc, exec, s[44:45]
	s_cbranch_vccnz .LBB0_2244
	s_branch .LBB0_2245

.LBB0_2404:
	s_add_i32 s40, s8, 2
	s_add_u32 s9, s12, 0xfff80080
	s_addc_u32 s16, s13, -1
	s_add_i32 s41, 0, 0x10000
	s_cmp_eq_u32 s93, s8
	s_cselect_b32 s17, s7, s16
	s_cselect_b32 s16, s22, s9
	s_cselect_b32 s9, s23, s33
	s_cselect_b32 s8, s30, s31
	s_add_i32 s71, 0, 0x14000
	v_add_u32_e32 v52, s41, v202
	v_add_u32_e32 v156, s71, v202
	ds_read_b128 v[40:43], v52
	ds_read_b128 v[44:47], v52 offset:1024
	ds_read_b128 v[48:51], v52 offset:2048
	ds_read_b128 v[52:55], v52 offset:3072
	ds_read_b128 v[80:83], v156
	ds_read_b128 v[84:87], v156 offset:1024
	ds_read_b128 v[152:155], v156 offset:2048
	ds_read_b128 v[156:159], v156 offset:3072
	v_lshl_add_u64 v[204:205], s[12:13], 0, v[182:183]
	s_add_i32 m0, s84, 0xc000
	ds_read_b128 v[160:163], v203
	ds_read_b128 v[164:167], v203 offset:1024
	ds_read_b128 v[168:171], v203 offset:2048
	ds_read_b128 v[172:175], v203 offset:3072
	ds_read_b128 v[186:189], v203 offset:4096
	ds_read_b128 v[190:193], v203 offset:5120
	ds_read_b128 v[194:197], v203 offset:6144
	ds_read_b128 v[198:201], v203 offset:7168
	global_load_lds_dwordx4 v[204:205], off
	v_lshl_add_u64 v[204:205], s[12:13], 0, v[184:185]
	s_add_i32 m0, s84, 0xe000
	s_nop 0
	global_load_lds_dwordx4 v[204:205], off
	s_waitcnt vmcnt(8)
	s_waitcnt lgkmcnt(0)
	s_barrier
	s_setprio 0
	s_waitcnt lgkmcnt(0)
	v_mfma_f32_16x16x32_bf16 v[76:79], v[40:43], v[160:163], v[76:79]
	v_mfma_f32_16x16x32_bf16 v[72:75], v[48:51], v[160:163], v[72:75]
	v_mfma_f32_16x16x32_bf16 v[140:143], v[40:43], v[168:171], v[140:143]
	v_mfma_f32_16x16x32_bf16 v[136:139], v[48:51], v[168:171], v[136:139]
	v_mfma_f32_16x16x32_bf16 v[124:127], v[40:43], v[186:189], v[124:127]
	v_mfma_f32_16x16x32_bf16 v[120:123], v[48:51], v[186:189], v[120:123]
	v_mfma_f32_16x16x32_bf16 v[108:111], v[40:43], v[194:197], v[108:111]
	v_mfma_f32_16x16x32_bf16 v[104:107], v[48:51], v[194:197], v[104:107]
	v_mfma_f32_16x16x32_bf16 v[76:79], v[44:47], v[164:167], v[76:79]
	v_mfma_f32_16x16x32_bf16 v[72:75], v[52:55], v[164:167], v[72:75]
	v_mfma_f32_16x16x32_bf16 v[140:143], v[44:47], v[172:175], v[140:143]
	v_mfma_f32_16x16x32_bf16 v[136:139], v[52:55], v[172:175], v[136:139]
	v_mfma_f32_16x16x32_bf16 v[124:127], v[44:47], v[190:193], v[124:127]
	v_mfma_f32_16x16x32_bf16 v[120:123], v[52:55], v[190:193], v[120:123]
	v_mfma_f32_16x16x32_bf16 v[108:111], v[44:47], v[198:201], v[108:111]
	v_mfma_f32_16x16x32_bf16 v[104:107], v[52:55], v[198:201], v[104:107]
	s_setprio 1
	s_setprio 0
	v_mfma_f32_16x16x32_bf16 v[148:151], v[80:83], v[160:163], v[148:151]
	v_mfma_f32_16x16x32_bf16 v[144:147], v[152:155], v[160:163], v[144:147]
	v_mfma_f32_16x16x32_bf16 v[132:135], v[80:83], v[168:171], v[132:135]
	v_mfma_f32_16x16x32_bf16 v[128:131], v[152:155], v[168:171], v[128:131]
	v_mfma_f32_16x16x32_bf16 v[116:119], v[80:83], v[186:189], v[116:119]
	v_mfma_f32_16x16x32_bf16 v[112:115], v[152:155], v[186:189], v[112:115]
	v_mfma_f32_16x16x32_bf16 v[100:103], v[80:83], v[194:197], v[100:103]
	v_mfma_f32_16x16x32_bf16 v[96:99], v[152:155], v[194:197], v[96:99]
	v_mfma_f32_16x16x32_bf16 v[148:151], v[84:87], v[164:167], v[148:151]
	v_mfma_f32_16x16x32_bf16 v[144:147], v[156:159], v[164:167], v[144:147]
	v_mfma_f32_16x16x32_bf16 v[132:135], v[84:87], v[172:175], v[132:135]
	v_mfma_f32_16x16x32_bf16 v[128:131], v[156:159], v[172:175], v[128:131]
	v_mfma_f32_16x16x32_bf16 v[116:119], v[84:87], v[190:193], v[116:119]
	v_mfma_f32_16x16x32_bf16 v[112:115], v[156:159], v[190:193], v[112:115]
	v_mfma_f32_16x16x32_bf16 v[100:103], v[84:87], v[198:201], v[100:103]
	v_mfma_f32_16x16x32_bf16 v[96:99], v[156:159], v[198:201], v[96:99]
	s_setprio 1
	s_barrier
	s_add_i32 s41, s41, s28
	v_lshl_add_u64 v[204:205], s[8:9], 0, v[224:225]
	s_mov_b32 m0, s41
	ds_read_b128 v[160:163], v203 offset:16384
	ds_read_b128 v[164:167], v203 offset:17408
	ds_read_b128 v[168:171], v203 offset:18432
	ds_read_b128 v[172:175], v203 offset:19456
	ds_read_b128 v[186:189], v203 offset:20480
	ds_read_b128 v[190:193], v203 offset:21504
	ds_read_b128 v[194:197], v203 offset:22528
	ds_read_b128 v[198:201], v203 offset:23552
	global_load_lds_dwordx4 v[204:205], off
	s_add_i32 m0, s41, 0x2000
	s_add_u32 s42, s8, 0x80000
	v_lshl_add_u64 v[206:207], s[8:9], 0, v[176:177]
	s_addc_u32 s43, s9, 0
	s_add_i32 s41, s71, s28
	global_load_lds_dwordx4 v[206:207], off
	v_lshl_add_u64 v[208:209], s[42:43], 0, v[224:225]
	s_mov_b32 m0, s41
	v_lshl_add_u64 v[210:211], s[16:17], 0, v[178:179]
	global_load_lds_dwordx4 v[208:209], off
	v_lshl_add_u64 v[208:209], s[42:43], 0, v[176:177]
	s_add_i32 m0, s41, 0x2000
	s_nop 0
	global_load_lds_dwordx4 v[208:209], off
	v_lshl_add_u64 v[208:209], s[16:17], 0, v[180:181]
	s_mov_b32 m0, s84
	s_nop 0
	global_load_lds_dwordx4 v[208:209], off
	s_mov_b32 m0, s85
	s_nop 0
	global_load_lds_dwordx4 v[210:211], off
	s_waitcnt vmcnt(8)
	s_waitcnt lgkmcnt(0)
	s_barrier
	s_setprio 0
	s_waitcnt lgkmcnt(0)
	v_mfma_f32_16x16x32_bf16 v[92:95], v[40:43], v[160:163], v[92:95]
	v_mfma_f32_16x16x32_bf16 v[88:91], v[48:51], v[160:163], v[88:91]
	v_mfma_f32_16x16x32_bf16 v[60:63], v[40:43], v[168:171], v[60:63]
	v_mfma_f32_16x16x32_bf16 v[56:59], v[48:51], v[168:171], v[56:59]
	v_mfma_f32_16x16x32_bf16 v[28:31], v[40:43], v[186:189], v[28:31]
	v_mfma_f32_16x16x32_bf16 v[24:27], v[48:51], v[186:189], v[24:27]
	v_mfma_f32_16x16x32_bf16 v[12:15], v[40:43], v[194:197], v[12:15]
	v_mfma_f32_16x16x32_bf16 v[8:11], v[48:51], v[194:197], v[8:11]
	v_mfma_f32_16x16x32_bf16 v[92:95], v[44:47], v[164:167], v[92:95]
	v_mfma_f32_16x16x32_bf16 v[88:91], v[52:55], v[164:167], v[88:91]
	v_mfma_f32_16x16x32_bf16 v[60:63], v[44:47], v[172:175], v[60:63]
	v_mfma_f32_16x16x32_bf16 v[56:59], v[52:55], v[172:175], v[56:59]
	v_mfma_f32_16x16x32_bf16 v[28:31], v[44:47], v[190:193], v[28:31]
	v_mfma_f32_16x16x32_bf16 v[24:27], v[52:55], v[190:193], v[24:27]
	v_mfma_f32_16x16x32_bf16 v[12:15], v[44:47], v[198:201], v[12:15]
	v_mfma_f32_16x16x32_bf16 v[8:11], v[52:55], v[198:201], v[8:11]
	s_setprio 1
	s_setprio 0
	v_mfma_f32_16x16x32_bf16 v[36:39], v[80:83], v[168:171], v[36:39]
	v_mfma_f32_16x16x32_bf16 v[32:35], v[152:155], v[168:171], v[32:35]
	v_mfma_f32_16x16x32_bf16 v[20:23], v[80:83], v[186:189], v[20:23]
	v_mfma_f32_16x16x32_bf16 v[16:19], v[152:155], v[186:189], v[16:19]
	v_mfma_f32_16x16x32_bf16 v[4:7], v[80:83], v[194:197], v[4:7]
	v_mfma_f32_16x16x32_bf16 v[0:3], v[152:155], v[194:197], v[0:3]
	v_mfma_f32_16x16x32_bf16 v[40:43], v[80:83], v[160:163], v[68:71]
	v_mfma_f32_16x16x32_bf16 v[44:47], v[152:155], v[160:163], v[64:67]
	v_mfma_f32_16x16x32_bf16 v[36:39], v[84:87], v[172:175], v[36:39]
	v_mfma_f32_16x16x32_bf16 v[32:35], v[156:159], v[172:175], v[32:35]
	v_mfma_f32_16x16x32_bf16 v[20:23], v[84:87], v[190:193], v[20:23]
	v_mfma_f32_16x16x32_bf16 v[16:19], v[156:159], v[190:193], v[16:19]
	v_mfma_f32_16x16x32_bf16 v[4:7], v[84:87], v[198:201], v[4:7]
	v_mfma_f32_16x16x32_bf16 v[0:3], v[156:159], v[198:201], v[0:3]
	v_mfma_f32_16x16x32_bf16 v[40:43], v[84:87], v[164:167], v[40:43]
	v_mfma_f32_16x16x32_bf16 v[44:47], v[156:159], v[164:167], v[44:47]
	s_setprio 1
	s_barrier
	s_add_i32 s41, 0, 0x18000
	s_add_i32 s42, 0, 0x1c000
	v_add_u32_e32 v68, s41, v202
	v_add_u32_e32 v156, s42, v202
	ds_read_b128 v[48:51], v68
	ds_read_b128 v[52:55], v68 offset:1024
	ds_read_b128 v[64:67], v68 offset:2048
	ds_read_b128 v[68:71], v68 offset:3072
	ds_read_b128 v[80:83], v156
	ds_read_b128 v[84:87], v156 offset:1024
	ds_read_b128 v[152:155], v156 offset:2048
	ds_read_b128 v[156:159], v156 offset:3072
	s_add_u32 s16, s16, 0x80000
	s_addc_u32 s17, s17, 0
	s_mov_b32 m0, s86
	v_lshl_add_u64 v[212:213], s[16:17], 0, v[180:181]
	ds_read_b128 v[160:163], v203 offset:32768
	ds_read_b128 v[164:167], v203 offset:33792
	ds_read_b128 v[168:171], v203 offset:34816
	ds_read_b128 v[172:175], v203 offset:35840
	ds_read_b128 v[186:189], v203 offset:36864
	ds_read_b128 v[190:193], v203 offset:37888
	ds_read_b128 v[194:197], v203 offset:38912
	ds_read_b128 v[198:201], v203 offset:39936
	global_load_lds_dwordx4 v[212:213], off
	v_lshl_add_u64 v[212:213], s[16:17], 0, v[178:179]
	s_mov_b32 m0, s87
	s_nop 0
	global_load_lds_dwordx4 v[212:213], off
	s_waitcnt vmcnt(8)
	s_waitcnt lgkmcnt(0)
	s_barrier
	s_setprio 0
	s_waitcnt lgkmcnt(0)
	v_mfma_f32_16x16x32_bf16 v[76:79], v[48:51], v[160:163], v[76:79]
	v_mfma_f32_16x16x32_bf16 v[72:75], v[64:67], v[160:163], v[72:75]
	v_mfma_f32_16x16x32_bf16 v[140:143], v[48:51], v[168:171], v[140:143]
	v_mfma_f32_16x16x32_bf16 v[136:139], v[64:67], v[168:171], v[136:139]
	v_mfma_f32_16x16x32_bf16 v[124:127], v[48:51], v[186:189], v[124:127]
	v_mfma_f32_16x16x32_bf16 v[120:123], v[64:67], v[186:189], v[120:123]
	v_mfma_f32_16x16x32_bf16 v[108:111], v[48:51], v[194:197], v[108:111]
	v_mfma_f32_16x16x32_bf16 v[104:107], v[64:67], v[194:197], v[104:107]
	v_mfma_f32_16x16x32_bf16 v[76:79], v[52:55], v[164:167], v[76:79]
	v_mfma_f32_16x16x32_bf16 v[72:75], v[68:71], v[164:167], v[72:75]
	v_mfma_f32_16x16x32_bf16 v[140:143], v[52:55], v[172:175], v[140:143]
	v_mfma_f32_16x16x32_bf16 v[136:139], v[68:71], v[172:175], v[136:139]
	v_mfma_f32_16x16x32_bf16 v[124:127], v[52:55], v[190:193], v[124:127]
	v_mfma_f32_16x16x32_bf16 v[120:123], v[68:71], v[190:193], v[120:123]
	v_mfma_f32_16x16x32_bf16 v[108:111], v[52:55], v[198:201], v[108:111]
	v_mfma_f32_16x16x32_bf16 v[104:107], v[68:71], v[198:201], v[104:107]
	s_setprio 1
	s_setprio 0
	v_mfma_f32_16x16x32_bf16 v[148:151], v[80:83], v[160:163], v[148:151]
	v_mfma_f32_16x16x32_bf16 v[144:147], v[152:155], v[160:163], v[144:147]
	v_mfma_f32_16x16x32_bf16 v[132:135], v[80:83], v[168:171], v[132:135]
	v_mfma_f32_16x16x32_bf16 v[128:131], v[152:155], v[168:171], v[128:131]
	v_mfma_f32_16x16x32_bf16 v[116:119], v[80:83], v[186:189], v[116:119]
	v_mfma_f32_16x16x32_bf16 v[112:115], v[152:155], v[186:189], v[112:115]
	v_mfma_f32_16x16x32_bf16 v[100:103], v[80:83], v[194:197], v[100:103]
	v_mfma_f32_16x16x32_bf16 v[96:99], v[152:155], v[194:197], v[96:99]
	v_mfma_f32_16x16x32_bf16 v[148:151], v[84:87], v[164:167], v[148:151]
	v_mfma_f32_16x16x32_bf16 v[144:147], v[156:159], v[164:167], v[144:147]
	v_mfma_f32_16x16x32_bf16 v[132:135], v[84:87], v[172:175], v[132:135]
	v_mfma_f32_16x16x32_bf16 v[128:131], v[156:159], v[172:175], v[128:131]
	v_mfma_f32_16x16x32_bf16 v[116:119], v[84:87], v[190:193], v[116:119]
	v_mfma_f32_16x16x32_bf16 v[112:115], v[156:159], v[190:193], v[112:115]
	v_mfma_f32_16x16x32_bf16 v[100:103], v[84:87], v[198:201], v[100:103]
	v_mfma_f32_16x16x32_bf16 v[96:99], v[156:159], v[198:201], v[96:99]
	s_setprio 1
	s_barrier
	s_add_i32 s16, s41, s28
	v_lshl_add_u64 v[204:205], v[204:205], 0, s[24:25]
	s_mov_b32 m0, s16
	ds_read_b128 v[160:163], v203 offset:49152
	ds_read_b128 v[164:167], v203 offset:50176
	ds_read_b128 v[168:171], v203 offset:51200
	ds_read_b128 v[172:175], v203 offset:52224
	ds_read_b128 v[186:189], v203 offset:53248
	ds_read_b128 v[190:193], v203 offset:54272
	ds_read_b128 v[194:197], v203 offset:55296
	ds_read_b128 v[198:201], v203 offset:56320
	global_load_lds_dwordx4 v[204:205], off
	s_add_i32 m0, s16, 0x2000
	s_add_u32 s8, s8, 0x80080
	v_lshl_add_u64 v[204:205], v[206:207], 0, s[24:25]
	s_addc_u32 s9, s9, 0
	s_add_i32 s16, s42, s28
	global_load_lds_dwordx4 v[204:205], off
	v_lshl_add_u64 v[204:205], s[8:9], 0, v[224:225]
	s_mov_b32 m0, s16
	s_nop 0
	global_load_lds_dwordx4 v[204:205], off
	v_lshl_add_u64 v[204:205], s[8:9], 0, v[176:177]
	s_add_i32 m0, s16, 0x2000
	s_nop 0
	global_load_lds_dwordx4 v[204:205], off
	v_lshl_add_u64 v[204:205], v[208:209], 0, s[24:25]
	s_mov_b32 m0, s18
	s_nop 0
	global_load_lds_dwordx4 v[204:205], off
	v_lshl_add_u64 v[204:205], v[210:211], 0, s[24:25]
	s_mov_b32 m0, s19
	s_nop 0
	global_load_lds_dwordx4 v[204:205], off
	s_waitcnt vmcnt(8)
	s_waitcnt lgkmcnt(0)
	s_barrier
	s_setprio 0
	s_waitcnt lgkmcnt(0)
	v_mfma_f32_16x16x32_bf16 v[92:95], v[48:51], v[160:163], v[92:95]
	v_mfma_f32_16x16x32_bf16 v[88:91], v[64:67], v[160:163], v[88:91]
	v_mfma_f32_16x16x32_bf16 v[60:63], v[48:51], v[168:171], v[60:63]
	v_mfma_f32_16x16x32_bf16 v[56:59], v[64:67], v[168:171], v[56:59]
	v_mfma_f32_16x16x32_bf16 v[28:31], v[48:51], v[186:189], v[28:31]
	v_mfma_f32_16x16x32_bf16 v[24:27], v[64:67], v[186:189], v[24:27]
	v_mfma_f32_16x16x32_bf16 v[12:15], v[48:51], v[194:197], v[12:15]
	v_mfma_f32_16x16x32_bf16 v[8:11], v[64:67], v[194:197], v[8:11]
	v_mfma_f32_16x16x32_bf16 v[92:95], v[52:55], v[164:167], v[92:95]
	v_mfma_f32_16x16x32_bf16 v[88:91], v[68:71], v[164:167], v[88:91]
	v_mfma_f32_16x16x32_bf16 v[60:63], v[52:55], v[172:175], v[60:63]
	v_mfma_f32_16x16x32_bf16 v[56:59], v[68:71], v[172:175], v[56:59]
	v_mfma_f32_16x16x32_bf16 v[28:31], v[52:55], v[190:193], v[28:31]
	v_mfma_f32_16x16x32_bf16 v[24:27], v[68:71], v[190:193], v[24:27]
	v_mfma_f32_16x16x32_bf16 v[12:15], v[52:55], v[198:201], v[12:15]
	v_mfma_f32_16x16x32_bf16 v[8:11], v[68:71], v[198:201], v[8:11]
	s_setprio 1
	s_setprio 0
	v_mfma_f32_16x16x32_bf16 v[40:43], v[80:83], v[160:163], v[40:43]
	v_mfma_f32_16x16x32_bf16 v[68:71], v[84:87], v[164:167], v[40:43]
	v_mfma_f32_16x16x32_bf16 v[40:43], v[152:155], v[160:163], v[44:47]
	v_mfma_f32_16x16x32_bf16 v[36:39], v[80:83], v[168:171], v[36:39]
	v_mfma_f32_16x16x32_bf16 v[32:35], v[152:155], v[168:171], v[32:35]
	v_mfma_f32_16x16x32_bf16 v[20:23], v[80:83], v[186:189], v[20:23]
	v_mfma_f32_16x16x32_bf16 v[16:19], v[152:155], v[186:189], v[16:19]
	v_mfma_f32_16x16x32_bf16 v[4:7], v[80:83], v[194:197], v[4:7]
	v_mfma_f32_16x16x32_bf16 v[0:3], v[152:155], v[194:197], v[0:3]
	v_mfma_f32_16x16x32_bf16 v[64:67], v[156:159], v[164:167], v[40:43]
	v_mfma_f32_16x16x32_bf16 v[36:39], v[84:87], v[172:175], v[36:39]
	v_mfma_f32_16x16x32_bf16 v[32:35], v[156:159], v[172:175], v[32:35]
	v_mfma_f32_16x16x32_bf16 v[20:23], v[84:87], v[190:193], v[20:23]
	v_mfma_f32_16x16x32_bf16 v[16:19], v[156:159], v[190:193], v[16:19]
	v_mfma_f32_16x16x32_bf16 v[4:7], v[84:87], v[198:201], v[4:7]
	v_mfma_f32_16x16x32_bf16 v[0:3], v[156:159], v[198:201], v[0:3]
	s_setprio 1
	s_barrier
	s_add_u32 s12, s12, 0x100
	s_addc_u32 s13, s13, 0
	s_add_u32 s31, s31, 0x100
	s_addc_u32 s33, s33, 0
	s_cmp_ge_i32 s40, s27
	s_mov_b32 s8, s40
	s_cbranch_scc0 .LBB0_2404
